# v12 + MFMA accumulator-pair order, full snake (every consecutive pair shares one operand fragment)
# baseline (speedup 1.0000x reference)
; #define PG8_STAGE(bufoff, gbase, voff) do { _Pragma("unroll") for (int _i = 0; _i < 2; ++_i) \
;         __builtin_amdgcn_global_load_lds((const unsigned*)((const char*)(gbase) + (voff)[_i]), (PG8_LAS unsigned*)(lds + (bufoff) + ldsw + _i * 8192), 16, 0, 0); } while (0)
; #define PG8_LDA(dst, b, h) do { _Pragma("unroll") for (int m = 0; m < 4; ++m) _Pragma("unroll") for (int k = 0; k < 2; ++k) dst[m][k] = *(const PG8_LAS bf16x8*)(lds + PG8_SA(b, h) + aoff + m * 2048 + k * 1024); } while (0)
; #define PG8_LDB(dst, b, h) do { _Pragma("unroll") for (int n = 0; n < 2; ++n) _Pragma("unroll") for (int k = 0; k < 2; ++k) dst[n][k] = *(const PG8_LAS bf16x8*)(lds + PG8_SB(b, h) + boff + n * 2048 + k * 1024); } while (0)
; #define PG8_MMA(ai, bj, At, Bt) do { __builtin_amdgcn_s_setprio(1); _Pragma("unroll") for (int m = 0; m < 4; ++m) _Pragma("unroll") for (int n = 0; n < 2; ++n) _Pragma("unroll") for (int k = 0; k < 2; ++k) \
;         acc[ai][bj][m][n] = __builtin_amdgcn_mfma_f32_16x16x32_bf16(Bt[n][k], At[m][k], acc[ai][bj][m][n], 0, 0, 0); __builtin_amdgcn_s_setprio(0); } while (0)
; #define PG8_WAIT_V(n) asm volatile("s_waitcnt vmcnt(" #n ")" ::: "memory")
; #define PG8_WAIT_L(n) asm volatile("s_waitcnt lgkmcnt(" #n ")" ::: "memory")
; #define PG8_BAR __builtin_amdgcn_s_barrier()
; #define PG8_SCHED __builtin_amdgcn_sched_barrier(0)
; template <class Epi, class Sched, bool ALIGN_EPI = false, bool SP2 = false>
; __device__ __forceinline__ void gemm_phase(PG8_LAS unsigned char* lds, const Gemm g, const Sched& S, const Epi& E) {
;     ...
;             const bool last = (t == nt - 2);
;             const char* a1 = cA + (size_t)(t + 1) * kstep;
;             const char* a2 = last ? nA : cA + (size_t)(t + 2) * kstep; const char* b2 = last ? nB : cB + (size_t)(t + 2) * kstep;
;             const char* a3 = a2 + kstep; const char* b3 = b2 + kstep;
;             if (last && has_next) S.a_ready(nxt);
;             if constexpr (SP2) {
;             PG8_LDB(B0, 0, 0); PG8_LDB(B1, 0, 1); PG8_SCHED; PG8_LDA(At, 0, 0); PG8_STAGE(PG8_SA(1, 1), a1 + hstep, voffA);
;             PG8_WAIT_V(8); PG8_WAIT_L(0); PG8_BAR; PG8_MMA(0, 0, At, B0); PG8_MMA(0, 1, At, B1); PG8_BAR; PG8_SCHED;
;             PG8_LDA(At, 0, 1); PG8_STAGE(PG8_SB(0, 0), b2, voffB); PG8_STAGE(PG8_SB(0, 1), b2 + hstep, voffB); PG8_STAGE(PG8_SA(0, 0), a2, voffA);
.LBB0_202:
	s_add_i32 s78, s38, 2
	s_add_u32 s79, s22, 0x80
	s_addc_u32 s39, s23, 0
	s_cmp_eq_u32 s33, s38
	s_cselect_b32 s39, s7, s39
	s_cselect_b32 s38, s6, s79
	v_add_u32_e32 v0, s19, v150
	s_cselect_b32 s81, s17, s77
	s_cselect_b32 s80, s16, s76
	s_add_i32 s79, 0, 0x14000
	ds_read_b128 v[152:155], v0
	ds_read_b128 v[156:159], v0 offset:1024
	ds_read_b128 v[160:163], v0 offset:2048
	ds_read_b128 v[164:167], v0 offset:3072
	v_add_u32_e32 v0, s79, v150
	ds_read_b128 v[168:171], v0
	ds_read_b128 v[172:175], v0 offset:1024
	ds_read_b128 v[176:179], v0 offset:2048
	ds_read_b128 v[184:187], v0 offset:3072
	v_lshl_add_u64 v[2:3], s[22:23], 0, v[144:145]
	s_add_i32 m0, s42, 0xc000
	ds_read_b128 v[188:191], v151
	ds_read_b128 v[192:195], v151 offset:1024
	ds_read_b128 v[196:199], v151 offset:2048
	ds_read_b128 v[200:203], v151 offset:3072
	ds_read_b128 v[204:207], v151 offset:4096
	ds_read_b128 v[230:233], v151 offset:5120
	ds_read_b128 v[234:237], v151 offset:6144
	ds_read_b128 v[238:241], v151 offset:7168
	global_load_lds_dwordx4 v[2:3], off
	v_lshl_add_u64 v[2:3], s[22:23], 0, v[146:147]
	s_add_i32 m0, s42, 0xe000
	s_nop 0
	global_load_lds_dwordx4 v[2:3], off
	s_waitcnt vmcnt(8)
	s_waitcnt lgkmcnt(0)
	s_barrier
	s_setprio 1
	s_waitcnt lgkmcnt(0)
	v_mfma_f32_16x16x32_bf16 v[132:135], v[152:155], v[188:191], v[132:135]
	v_mfma_f32_16x16x32_bf16 v[132:135], v[156:159], v[192:195], v[132:135]
	v_mfma_f32_16x16x32_bf16 v[128:131], v[160:163], v[188:191], v[128:131]
	v_mfma_f32_16x16x32_bf16 v[128:131], v[164:167], v[192:195], v[128:131]
	v_mfma_f32_16x16x32_bf16 v[112:115], v[160:163], v[196:199], v[112:115]
	v_mfma_f32_16x16x32_bf16 v[112:115], v[164:167], v[200:203], v[112:115]
	v_mfma_f32_16x16x32_bf16 v[116:119], v[152:155], v[196:199], v[116:119]
	v_mfma_f32_16x16x32_bf16 v[116:119], v[156:159], v[200:203], v[116:119]
	v_mfma_f32_16x16x32_bf16 v[100:103], v[152:155], v[204:207], v[100:103]
	v_mfma_f32_16x16x32_bf16 v[100:103], v[156:159], v[230:233], v[100:103]
	v_mfma_f32_16x16x32_bf16 v[96:99], v[160:163], v[204:207], v[96:99]
	v_mfma_f32_16x16x32_bf16 v[96:99], v[164:167], v[230:233], v[96:99]
	v_mfma_f32_16x16x32_bf16 v[80:83], v[160:163], v[234:237], v[80:83]
	v_mfma_f32_16x16x32_bf16 v[80:83], v[164:167], v[238:241], v[80:83]
	v_mfma_f32_16x16x32_bf16 v[84:87], v[152:155], v[234:237], v[84:87]
	v_mfma_f32_16x16x32_bf16 v[84:87], v[156:159], v[238:241], v[84:87]
	s_setprio 0
	s_setprio 1
	v_mfma_f32_16x16x32_bf16 v[124:127], v[168:171], v[188:191], v[124:127]
	v_mfma_f32_16x16x32_bf16 v[124:127], v[172:175], v[192:195], v[124:127]
	v_mfma_f32_16x16x32_bf16 v[120:123], v[176:179], v[188:191], v[120:123]
	v_mfma_f32_16x16x32_bf16 v[120:123], v[184:187], v[192:195], v[120:123]
	v_mfma_f32_16x16x32_bf16 v[104:107], v[176:179], v[196:199], v[104:107]
	v_mfma_f32_16x16x32_bf16 v[104:107], v[184:187], v[200:203], v[104:107]
	v_mfma_f32_16x16x32_bf16 v[108:111], v[168:171], v[196:199], v[108:111]
	v_mfma_f32_16x16x32_bf16 v[108:111], v[172:175], v[200:203], v[108:111]
	v_mfma_f32_16x16x32_bf16 v[92:95], v[168:171], v[204:207], v[92:95]
	v_mfma_f32_16x16x32_bf16 v[92:95], v[172:175], v[230:233], v[92:95]
	v_mfma_f32_16x16x32_bf16 v[88:91], v[176:179], v[204:207], v[88:91]
	v_mfma_f32_16x16x32_bf16 v[88:91], v[184:187], v[230:233], v[88:91]
	v_mfma_f32_16x16x32_bf16 v[72:75], v[176:179], v[234:237], v[72:75]
	v_mfma_f32_16x16x32_bf16 v[72:75], v[184:187], v[238:241], v[72:75]
	v_mfma_f32_16x16x32_bf16 v[76:79], v[168:171], v[234:237], v[76:79]
	v_mfma_f32_16x16x32_bf16 v[76:79], v[172:175], v[238:241], v[76:79]
	s_setprio 0
	s_barrier
	s_add_i32 s82, s19, s20
	v_lshl_add_u64 v[2:3], s[80:81], 0, v[140:141]
	s_mov_b32 m0, s82
	ds_read_b128 v[188:191], v151 offset:16384
	ds_read_b128 v[192:195], v151 offset:17408
	ds_read_b128 v[196:199], v151 offset:18432
	ds_read_b128 v[200:203], v151 offset:19456
	ds_read_b128 v[204:207], v151 offset:20480
	ds_read_b128 v[230:233], v151 offset:21504
	ds_read_b128 v[234:237], v151 offset:22528
	ds_read_b128 v[238:241], v151 offset:23552
	global_load_lds_dwordx4 v[2:3], off
	s_add_i32 m0, s82, 0x2000
	v_lshl_add_u64 v[180:181], s[80:81], 0, v[136:137]
	s_add_u32 s80, s80, s48
	s_addc_u32 s81, s81, s49
	s_add_i32 s79, s79, s20
	global_load_lds_dwordx4 v[180:181], off
	v_lshl_add_u64 v[208:209], s[80:81], 0, v[140:141]
	s_mov_b32 m0, s79
	v_lshl_add_u64 v[216:217], s[80:81], 0, v[136:137]
	global_load_lds_dwordx4 v[208:209], off
	s_add_i32 m0, s79, 0x2000
	v_lshl_add_u64 v[224:225], s[38:39], 0, v[142:143]
	global_load_lds_dwordx4 v[216:217], off
	s_mov_b32 m0, s42
	v_lshl_add_u64 v[226:227], s[38:39], 0, v[138:139]
	global_load_lds_dwordx4 v[224:225], off
	s_mov_b32 m0, s45
	s_nop 0
	global_load_lds_dwordx4 v[226:227], off
	s_waitcnt vmcnt(8)
	s_waitcnt lgkmcnt(0)
	s_barrier
; #define PG8_STAGE(bufoff, gbase, voff) do { _Pragma("unroll") for (int _i = 0; _i < 2; ++_i) \
;         __builtin_amdgcn_global_load_lds((const unsigned*)((const char*)(gbase) + (voff)[_i]), (PG8_LAS unsigned*)(lds + (bufoff) + ldsw + _i * 8192), 16, 0, 0); } while (0)
; #define PG8_LDA(dst, b, h) do { _Pragma("unroll") for (int m = 0; m < 4; ++m) _Pragma("unroll") for (int k = 0; k < 2; ++k) dst[m][k] = *(const PG8_LAS bf16x8*)(lds + PG8_SA(b, h) + aoff + m * 2048 + k * 1024); } while (0)
; #define PG8_LDB(dst, b, h) do { _Pragma("unroll") for (int n = 0; n < 2; ++n) _Pragma("unroll") for (int k = 0; k < 2; ++k) dst[n][k] = *(const PG8_LAS bf16x8*)(lds + PG8_SB(b, h) + boff + n * 2048 + k * 1024); } while (0)
; #define PG8_MMA(ai, bj, At, Bt) do { __builtin_amdgcn_s_setprio(1); _Pragma("unroll") for (int m = 0; m < 4; ++m) _Pragma("unroll") for (int n = 0; n < 2; ++n) _Pragma("unroll") for (int k = 0; k < 2; ++k) \
;         acc[ai][bj][m][n] = __builtin_amdgcn_mfma_f32_16x16x32_bf16(Bt[n][k], At[m][k], acc[ai][bj][m][n], 0, 0, 0); __builtin_amdgcn_s_setprio(0); } while (0)
; #define PG8_WAIT_V(n) asm volatile("s_waitcnt vmcnt(" #n ")" ::: "memory")
; #define PG8_WAIT_L(n) asm volatile("s_waitcnt lgkmcnt(" #n ")" ::: "memory")
; #define PG8_BAR __builtin_amdgcn_s_barrier()
; #define PG8_SCHED __builtin_amdgcn_sched_barrier(0)
; template <class Epi, class Sched, bool ALIGN_EPI = false, bool SP2 = false>
; __device__ __forceinline__ void gemm_phase(PG8_LAS unsigned char* lds, const Gemm g, const Sched& S, const Epi& E) {
;     ...
;             PG8_WAIT_V(8); PG8_WAIT_L(0); PG8_BAR; PG8_MMA(1, 0, At, B0); PG8_MMA(1, 1, At, B1); PG8_BAR; PG8_SCHED;
;             PG8_LDB(B0, 1, 0); PG8_LDB(B1, 1, 1); PG8_SCHED; PG8_LDA(At, 1, 0); PG8_STAGE(PG8_SA(0, 1), a2 + hstep, voffA);
;             PG8_WAIT_V(8); PG8_WAIT_L(0); PG8_BAR; PG8_MMA(0, 0, At, B0); PG8_MMA(0, 1, At, B1); PG8_BAR; PG8_SCHED;
	s_setprio 1
	s_waitcnt lgkmcnt(0)
	v_mfma_f32_16x16x32_bf16 v[68:71], v[152:155], v[188:191], v[68:71]
	v_mfma_f32_16x16x32_bf16 v[68:71], v[156:159], v[192:195], v[68:71]
	v_mfma_f32_16x16x32_bf16 v[64:67], v[160:163], v[188:191], v[64:67]
	v_mfma_f32_16x16x32_bf16 v[64:67], v[164:167], v[192:195], v[64:67]
	v_mfma_f32_16x16x32_bf16 v[48:51], v[160:163], v[196:199], v[48:51]
	v_mfma_f32_16x16x32_bf16 v[48:51], v[164:167], v[200:203], v[48:51]
	v_mfma_f32_16x16x32_bf16 v[52:55], v[152:155], v[196:199], v[52:55]
	v_mfma_f32_16x16x32_bf16 v[52:55], v[156:159], v[200:203], v[52:55]
	v_mfma_f32_16x16x32_bf16 v[36:39], v[152:155], v[204:207], v[36:39]
	v_mfma_f32_16x16x32_bf16 v[36:39], v[156:159], v[230:233], v[36:39]
	v_mfma_f32_16x16x32_bf16 v[32:35], v[160:163], v[204:207], v[32:35]
	v_mfma_f32_16x16x32_bf16 v[32:35], v[164:167], v[230:233], v[32:35]
	v_mfma_f32_16x16x32_bf16 v[16:19], v[160:163], v[234:237], v[16:19]
	v_mfma_f32_16x16x32_bf16 v[16:19], v[164:167], v[238:241], v[16:19]
	v_mfma_f32_16x16x32_bf16 v[20:23], v[152:155], v[234:237], v[20:23]
	v_mfma_f32_16x16x32_bf16 v[20:23], v[156:159], v[238:241], v[20:23]
	s_setprio 0
	s_setprio 1
	v_mfma_f32_16x16x32_bf16 v[60:63], v[168:171], v[188:191], v[60:63]
	v_mfma_f32_16x16x32_bf16 v[60:63], v[172:175], v[192:195], v[60:63]
	v_mfma_f32_16x16x32_bf16 v[56:59], v[176:179], v[188:191], v[56:59]
	v_mfma_f32_16x16x32_bf16 v[56:59], v[184:187], v[192:195], v[56:59]
	v_mfma_f32_16x16x32_bf16 v[40:43], v[176:179], v[196:199], v[40:43]
	v_mfma_f32_16x16x32_bf16 v[40:43], v[184:187], v[200:203], v[40:43]
	v_mfma_f32_16x16x32_bf16 v[44:47], v[168:171], v[196:199], v[44:47]
	v_mfma_f32_16x16x32_bf16 v[44:47], v[172:175], v[200:203], v[44:47]
	v_mfma_f32_16x16x32_bf16 v[28:31], v[168:171], v[204:207], v[28:31]
	v_mfma_f32_16x16x32_bf16 v[28:31], v[172:175], v[230:233], v[28:31]
	v_mfma_f32_16x16x32_bf16 v[24:27], v[176:179], v[204:207], v[24:27]
	v_mfma_f32_16x16x32_bf16 v[24:27], v[184:187], v[230:233], v[24:27]
	v_mfma_f32_16x16x32_bf16 v[8:11], v[176:179], v[234:237], v[8:11]
	v_mfma_f32_16x16x32_bf16 v[8:11], v[184:187], v[238:241], v[8:11]
	v_mfma_f32_16x16x32_bf16 v[12:15], v[168:171], v[234:237], v[12:15]
	v_mfma_f32_16x16x32_bf16 v[12:15], v[172:175], v[238:241], v[12:15]
	s_setprio 0
	s_barrier
	v_add_u32_e32 v0, s91, v150
	s_add_i32 s79, 0, 0x1c000
	ds_read_b128 v[152:155], v0
	ds_read_b128 v[156:159], v0 offset:1024
	ds_read_b128 v[160:163], v0 offset:2048
	ds_read_b128 v[164:167], v0 offset:3072
	v_add_u32_e32 v0, s79, v150
	ds_read_b128 v[168:171], v0
	ds_read_b128 v[172:175], v0 offset:1024
	ds_read_b128 v[176:179], v0 offset:2048
	ds_read_b128 v[184:187], v0 offset:3072
	s_add_u32 s38, s38, s48
	s_addc_u32 s39, s39, s49
	s_mov_b32 m0, s46
	v_lshl_add_u64 v[228:229], s[38:39], 0, v[142:143]
	ds_read_b128 v[188:191], v151 offset:32768
	ds_read_b128 v[192:195], v151 offset:33792
	ds_read_b128 v[196:199], v151 offset:34816
	ds_read_b128 v[200:203], v151 offset:35840
	ds_read_b128 v[204:207], v151 offset:36864
	ds_read_b128 v[230:233], v151 offset:37888
	ds_read_b128 v[234:237], v151 offset:38912
	ds_read_b128 v[238:241], v151 offset:39936
	global_load_lds_dwordx4 v[228:229], off
	v_lshl_add_u64 v[228:229], s[38:39], 0, v[138:139]
	s_mov_b32 m0, s47
	s_nop 0
	global_load_lds_dwordx4 v[228:229], off
	s_waitcnt vmcnt(8)
	s_waitcnt lgkmcnt(0)
	s_barrier
	s_setprio 1
	s_waitcnt lgkmcnt(0)
	v_mfma_f32_16x16x32_bf16 v[132:135], v[152:155], v[188:191], v[132:135]
	v_mfma_f32_16x16x32_bf16 v[132:135], v[156:159], v[192:195], v[132:135]
	v_mfma_f32_16x16x32_bf16 v[128:131], v[160:163], v[188:191], v[128:131]
	v_mfma_f32_16x16x32_bf16 v[128:131], v[164:167], v[192:195], v[128:131]
	v_mfma_f32_16x16x32_bf16 v[112:115], v[160:163], v[196:199], v[112:115]
	v_mfma_f32_16x16x32_bf16 v[112:115], v[164:167], v[200:203], v[112:115]
	v_mfma_f32_16x16x32_bf16 v[116:119], v[152:155], v[196:199], v[116:119]
	v_mfma_f32_16x16x32_bf16 v[116:119], v[156:159], v[200:203], v[116:119]
	v_mfma_f32_16x16x32_bf16 v[100:103], v[152:155], v[204:207], v[100:103]
	v_mfma_f32_16x16x32_bf16 v[100:103], v[156:159], v[230:233], v[100:103]
	v_mfma_f32_16x16x32_bf16 v[96:99], v[160:163], v[204:207], v[96:99]
	v_mfma_f32_16x16x32_bf16 v[96:99], v[164:167], v[230:233], v[96:99]
	v_mfma_f32_16x16x32_bf16 v[80:83], v[160:163], v[234:237], v[80:83]
	v_mfma_f32_16x16x32_bf16 v[80:83], v[164:167], v[238:241], v[80:83]
	v_mfma_f32_16x16x32_bf16 v[84:87], v[152:155], v[234:237], v[84:87]
	v_mfma_f32_16x16x32_bf16 v[84:87], v[156:159], v[238:241], v[84:87]
	s_setprio 0
	s_setprio 1
	v_mfma_f32_16x16x32_bf16 v[124:127], v[168:171], v[188:191], v[124:127]
	v_mfma_f32_16x16x32_bf16 v[124:127], v[172:175], v[192:195], v[124:127]
	v_mfma_f32_16x16x32_bf16 v[120:123], v[176:179], v[188:191], v[120:123]
	v_mfma_f32_16x16x32_bf16 v[120:123], v[184:187], v[192:195], v[120:123]
	v_mfma_f32_16x16x32_bf16 v[104:107], v[176:179], v[196:199], v[104:107]
	v_mfma_f32_16x16x32_bf16 v[104:107], v[184:187], v[200:203], v[104:107]
	v_mfma_f32_16x16x32_bf16 v[108:111], v[168:171], v[196:199], v[108:111]
	v_mfma_f32_16x16x32_bf16 v[108:111], v[172:175], v[200:203], v[108:111]
	v_mfma_f32_16x16x32_bf16 v[92:95], v[168:171], v[204:207], v[92:95]
	v_mfma_f32_16x16x32_bf16 v[92:95], v[172:175], v[230:233], v[92:95]
	v_mfma_f32_16x16x32_bf16 v[88:91], v[176:179], v[204:207], v[88:91]
	v_mfma_f32_16x16x32_bf16 v[88:91], v[184:187], v[230:233], v[88:91]
	v_mfma_f32_16x16x32_bf16 v[72:75], v[176:179], v[234:237], v[72:75]
	v_mfma_f32_16x16x32_bf16 v[72:75], v[184:187], v[238:241], v[72:75]
	v_mfma_f32_16x16x32_bf16 v[76:79], v[168:171], v[234:237], v[76:79]
	v_mfma_f32_16x16x32_bf16 v[76:79], v[172:175], v[238:241], v[76:79]
	s_setprio 0
	s_barrier
; #define PG8_STAGE(bufoff, gbase, voff) do { _Pragma("unroll") for (int _i = 0; _i < 2; ++_i) \
;         __builtin_amdgcn_global_load_lds((const unsigned*)((const char*)(gbase) + (voff)[_i]), (PG8_LAS unsigned*)(lds + (bufoff) + ldsw + _i * 8192), 16, 0, 0); } while (0)
; #define PG8_LDA(dst, b, h) do { _Pragma("unroll") for (int m = 0; m < 4; ++m) _Pragma("unroll") for (int k = 0; k < 2; ++k) dst[m][k] = *(const PG8_LAS bf16x8*)(lds + PG8_SA(b, h) + aoff + m * 2048 + k * 1024); } while (0)
; #define PG8_MMA(ai, bj, At, Bt) do { __builtin_amdgcn_s_setprio(1); _Pragma("unroll") for (int m = 0; m < 4; ++m) _Pragma("unroll") for (int n = 0; n < 2; ++n) _Pragma("unroll") for (int k = 0; k < 2; ++k) \
;         acc[ai][bj][m][n] = __builtin_amdgcn_mfma_f32_16x16x32_bf16(Bt[n][k], At[m][k], acc[ai][bj][m][n], 0, 0, 0); __builtin_amdgcn_s_setprio(0); } while (0)
; #define PG8_WAIT_V(n) asm volatile("s_waitcnt vmcnt(" #n ")" ::: "memory")
; #define PG8_WAIT_L(n) asm volatile("s_waitcnt lgkmcnt(" #n ")" ::: "memory")
; #define PG8_BAR __builtin_amdgcn_s_barrier()
; #define PG8_SCHED __builtin_amdgcn_sched_barrier(0)
; template <class Epi, class Sched, bool ALIGN_EPI = false, bool SP2 = false>
; __device__ __forceinline__ void gemm_phase(PG8_LAS unsigned char* lds, const Gemm g, const Sched& S, const Epi& E) {
;     ...
;             PG8_LDA(At, 1, 1); PG8_STAGE(PG8_SB(1, 0), b3, voffB); PG8_STAGE(PG8_SB(1, 1), b3 + hstep, voffB); PG8_STAGE(PG8_SA(1, 0), a3, voffA);
;             PG8_WAIT_V(8); PG8_WAIT_L(0); PG8_BAR; PG8_MMA(1, 0, At, B0); PG8_MMA(1, 1, At, B1); PG8_BAR; PG8_SCHED;
	s_add_i32 s38, s91, s20
	v_lshl_add_u64 v[2:3], v[2:3], 0, s[24:25]
	s_mov_b32 m0, s38
	ds_read_b128 v[188:191], v151 offset:49152
	ds_read_b128 v[192:195], v151 offset:50176
	ds_read_b128 v[196:199], v151 offset:51200
	ds_read_b128 v[200:203], v151 offset:52224
	ds_read_b128 v[204:207], v151 offset:53248
	ds_read_b128 v[230:233], v151 offset:54272
	ds_read_b128 v[234:237], v151 offset:55296
	ds_read_b128 v[238:241], v151 offset:56320
	global_load_lds_dwordx4 v[2:3], off
	v_lshl_add_u64 v[2:3], v[180:181], 0, s[24:25]
	s_add_i32 m0, s38, 0x2000
	s_add_i32 s38, s79, s20
	global_load_lds_dwordx4 v[2:3], off
	v_lshl_add_u64 v[2:3], v[208:209], 0, s[24:25]
	s_mov_b32 m0, s38
	s_nop 0
	global_load_lds_dwordx4 v[2:3], off
	v_lshl_add_u64 v[2:3], v[216:217], 0, s[24:25]
	s_add_i32 m0, s38, 0x2000
	s_nop 0
	global_load_lds_dwordx4 v[2:3], off
	v_lshl_add_u64 v[2:3], v[224:225], 0, s[24:25]
	s_mov_b32 m0, s52
	s_nop 0
	global_load_lds_dwordx4 v[2:3], off
	v_lshl_add_u64 v[2:3], v[226:227], 0, s[24:25]
	s_mov_b32 m0, s53
	s_nop 0
	global_load_lds_dwordx4 v[2:3], off
	s_waitcnt vmcnt(8)
	s_waitcnt lgkmcnt(0)
	s_barrier
	s_setprio 1
	s_waitcnt lgkmcnt(0)
	v_mfma_f32_16x16x32_bf16 v[68:71], v[152:155], v[188:191], v[68:71]
	v_mfma_f32_16x16x32_bf16 v[68:71], v[156:159], v[192:195], v[68:71]
	v_mfma_f32_16x16x32_bf16 v[64:67], v[160:163], v[188:191], v[64:67]
	v_mfma_f32_16x16x32_bf16 v[64:67], v[164:167], v[192:195], v[64:67]
	v_mfma_f32_16x16x32_bf16 v[48:51], v[160:163], v[196:199], v[48:51]
	v_mfma_f32_16x16x32_bf16 v[48:51], v[164:167], v[200:203], v[48:51]
	v_mfma_f32_16x16x32_bf16 v[52:55], v[152:155], v[196:199], v[52:55]
	v_mfma_f32_16x16x32_bf16 v[52:55], v[156:159], v[200:203], v[52:55]
	v_mfma_f32_16x16x32_bf16 v[36:39], v[152:155], v[204:207], v[36:39]
	v_mfma_f32_16x16x32_bf16 v[36:39], v[156:159], v[230:233], v[36:39]
	v_mfma_f32_16x16x32_bf16 v[32:35], v[160:163], v[204:207], v[32:35]
	v_mfma_f32_16x16x32_bf16 v[32:35], v[164:167], v[230:233], v[32:35]
	v_mfma_f32_16x16x32_bf16 v[16:19], v[160:163], v[234:237], v[16:19]
	v_mfma_f32_16x16x32_bf16 v[16:19], v[164:167], v[238:241], v[16:19]
	v_mfma_f32_16x16x32_bf16 v[20:23], v[152:155], v[234:237], v[20:23]
	v_mfma_f32_16x16x32_bf16 v[20:23], v[156:159], v[238:241], v[20:23]
	s_setprio 0
	s_setprio 1
	v_mfma_f32_16x16x32_bf16 v[60:63], v[168:171], v[188:191], v[60:63]
	v_mfma_f32_16x16x32_bf16 v[60:63], v[172:175], v[192:195], v[60:63]
	v_mfma_f32_16x16x32_bf16 v[56:59], v[176:179], v[188:191], v[56:59]
	v_mfma_f32_16x16x32_bf16 v[56:59], v[184:187], v[192:195], v[56:59]
	v_mfma_f32_16x16x32_bf16 v[40:43], v[176:179], v[196:199], v[40:43]
	v_mfma_f32_16x16x32_bf16 v[40:43], v[184:187], v[200:203], v[40:43]
	v_mfma_f32_16x16x32_bf16 v[44:47], v[168:171], v[196:199], v[44:47]
	v_mfma_f32_16x16x32_bf16 v[44:47], v[172:175], v[200:203], v[44:47]
	v_mfma_f32_16x16x32_bf16 v[28:31], v[168:171], v[204:207], v[28:31]
	v_mfma_f32_16x16x32_bf16 v[28:31], v[172:175], v[230:233], v[28:31]
	v_mfma_f32_16x16x32_bf16 v[24:27], v[176:179], v[204:207], v[24:27]
	v_mfma_f32_16x16x32_bf16 v[24:27], v[184:187], v[230:233], v[24:27]
	v_mfma_f32_16x16x32_bf16 v[8:11], v[176:179], v[234:237], v[8:11]
	v_mfma_f32_16x16x32_bf16 v[8:11], v[184:187], v[238:241], v[8:11]
	v_mfma_f32_16x16x32_bf16 v[12:15], v[168:171], v[234:237], v[12:15]
	v_mfma_f32_16x16x32_bf16 v[12:15], v[172:175], v[238:241], v[12:15]
	s_setprio 0
	s_barrier
	s_add_u32 s22, s22, 0x100
	s_addc_u32 s23, s23, 0
	s_add_u32 s76, s76, 0x100
	s_addc_u32 s77, s77, 0
	s_cmp_ge_u32 s78, s9
	s_mov_b32 s38, s78
	s_cbranch_scc0 .LBB0_202

; #define PG8_STAGE(bufoff, gbase, voff) do { _Pragma("unroll") for (int _i = 0; _i < 2; ++_i) \
;         __builtin_amdgcn_global_load_lds((const unsigned*)((const char*)(gbase) + (voff)[_i]), (PG8_LAS unsigned*)(lds + (bufoff) + ldsw + _i * 8192), 16, 0, 0); } while (0)
; #define PG8_LDA(dst, b, h) do { _Pragma("unroll") for (int m = 0; m < 4; ++m) _Pragma("unroll") for (int k = 0; k < 2; ++k) dst[m][k] = *(const PG8_LAS bf16x8*)(lds + PG8_SA(b, h) + aoff + m * 2048 + k * 1024); } while (0)
; #define PG8_LDB(dst, b, h) do { _Pragma("unroll") for (int n = 0; n < 2; ++n) _Pragma("unroll") for (int k = 0; k < 2; ++k) dst[n][k] = *(const PG8_LAS bf16x8*)(lds + PG8_SB(b, h) + boff + n * 2048 + k * 1024); } while (0)
; #define PG8_MMA(ai, bj, At, Bt) do { __builtin_amdgcn_s_setprio(1); _Pragma("unroll") for (int m = 0; m < 4; ++m) _Pragma("unroll") for (int n = 0; n < 2; ++n) _Pragma("unroll") for (int k = 0; k < 2; ++k) \
;         acc[ai][bj][m][n] = __builtin_amdgcn_mfma_f32_16x16x32_bf16(Bt[n][k], At[m][k], acc[ai][bj][m][n], 0, 0, 0); __builtin_amdgcn_s_setprio(0); } while (0)
; #define PG8_WAIT_V(n) asm volatile("s_waitcnt vmcnt(" #n ")" ::: "memory")
; #define PG8_WAIT_L(n) asm volatile("s_waitcnt lgkmcnt(" #n ")" ::: "memory")
; #define PG8_BAR __builtin_amdgcn_s_barrier()
; template <class Epi, class Sched, bool ALIGN_EPI = false, bool SP2 = false>
; __device__ __forceinline__ void gemm_phase(PG8_LAS unsigned char* lds, const Gemm g, const Sched& S, const Epi& E) {
;     ...
;             if constexpr (Epi::KHOOK) { if ((t & 7) == 0 && t != 0) E.khook(acc, t >> 3, wr, fr, lds); }
;             const bool last = (t == nt - 2);
;             const char* a1 = cA + (size_t)(t + 1) * kstep;
;             const char* a2 = last ? nA : cA + (size_t)(t + 2) * kstep; const char* b2 = last ? nB : cB + (size_t)(t + 2) * kstep;
;             const char* a3 = a2 + kstep; const char* b3 = b2 + kstep;
;             if (last && has_next) S.a_ready(nxt);
;             if constexpr (SP2) {
;             PG8_LDB(B0, 0, 0); PG8_LDB(B1, 0, 1); PG8_SCHED; PG8_LDA(At, 0, 0); PG8_STAGE(PG8_SA(1, 1), a1 + hstep, voffA);
;             PG8_WAIT_V(8); PG8_WAIT_L(0); PG8_BAR; PG8_MMA(0, 0, At, B0); PG8_MMA(0, 1, At, B1); PG8_BAR; PG8_SCHED;
;             PG8_LDA(At, 0, 1); PG8_STAGE(PG8_SB(0, 0), b2, voffB); PG8_STAGE(PG8_SB(0, 1), b2 + hstep, voffB); PG8_STAGE(PG8_SA(0, 0), a2, voffA);
.LBB0_245:
	v_readlane_b32 s22, v252, 59
	v_readlane_b32 s23, v252, 60
	s_andn2_b64 vcc, exec, s[22:23]
	s_cbranch_vccnz .LBB0_252
	s_add_u32 s40, s6, s48
	s_addc_u32 s41, s7, s49
	s_add_u32 s37, s6, 0x100
	s_addc_u32 s80, s7, 0
	s_and_b64 s[22:23], s[12:13], exec
	s_cselect_b32 s23, s5, s80
	s_cselect_b32 s22, s4, s37
	s_add_u32 s37, s10, 0x100
	s_addc_u32 s82, s11, 0
	s_and_b64 s[80:81], s[12:13], exec
	s_cselect_b32 s85, s17, s82
	s_cselect_b32 s84, s16, s37
	s_add_i32 s83, 0, 0x14000
	v_add_u32_e32 v150, s19, v147
	v_add_u32_e32 v151, s83, v147
	ds_read_b128 v[152:155], v150
	ds_read_b128 v[156:159], v150 offset:1024
	ds_read_b128 v[160:163], v150 offset:2048
	ds_read_b128 v[164:167], v150 offset:3072
	ds_read_b128 v[168:171], v151
	ds_read_b128 v[172:175], v151 offset:1024
	ds_read_b128 v[176:179], v151 offset:2048
	ds_read_b128 v[184:187], v151 offset:3072
	v_lshl_add_u64 v[180:181], s[40:41], 0, v[2:3]
	s_add_i32 s37, s47, 0xc000
	v_lshl_add_u64 v[180:181], v[180:181], 0, s[24:25]
	s_mov_b32 m0, s37
	ds_read_b128 v[188:191], v149
	ds_read_b128 v[192:195], v149 offset:1024
	ds_read_b128 v[196:199], v149 offset:2048
	ds_read_b128 v[200:203], v149 offset:3072
	ds_read_b128 v[204:207], v149 offset:4096
	ds_read_b128 v[230:233], v149 offset:5120
	ds_read_b128 v[234:237], v149 offset:6144
	ds_read_b128 v[238:241], v149 offset:7168
	global_load_lds_dwordx4 v[180:181], off
	v_lshl_add_u64 v[180:181], s[40:41], 0, v[136:137]
	s_add_i32 s80, s47, 0xe000
	v_lshl_add_u64 v[180:181], v[180:181], 0, s[24:25]
	s_mov_b32 m0, s80
	s_nop 0
	global_load_lds_dwordx4 v[180:181], off
	s_waitcnt vmcnt(8)
	s_waitcnt lgkmcnt(0)
	s_barrier
	s_setprio 1
	s_waitcnt lgkmcnt(0)
	v_mfma_f32_16x16x32_bf16 v[132:135], v[152:155], v[188:191], v[132:135]
	v_mfma_f32_16x16x32_bf16 v[132:135], v[156:159], v[192:195], v[132:135]
	v_mfma_f32_16x16x32_bf16 v[128:131], v[160:163], v[188:191], v[128:131]
	v_mfma_f32_16x16x32_bf16 v[128:131], v[164:167], v[192:195], v[128:131]
	v_mfma_f32_16x16x32_bf16 v[112:115], v[160:163], v[196:199], v[112:115]
	v_mfma_f32_16x16x32_bf16 v[112:115], v[164:167], v[200:203], v[112:115]
	v_mfma_f32_16x16x32_bf16 v[116:119], v[152:155], v[196:199], v[116:119]
	v_mfma_f32_16x16x32_bf16 v[116:119], v[156:159], v[200:203], v[116:119]
	v_mfma_f32_16x16x32_bf16 v[100:103], v[152:155], v[204:207], v[100:103]
	v_mfma_f32_16x16x32_bf16 v[100:103], v[156:159], v[230:233], v[100:103]
	v_mfma_f32_16x16x32_bf16 v[96:99], v[160:163], v[204:207], v[96:99]
	v_mfma_f32_16x16x32_bf16 v[96:99], v[164:167], v[230:233], v[96:99]
	v_mfma_f32_16x16x32_bf16 v[80:83], v[160:163], v[234:237], v[80:83]
	v_mfma_f32_16x16x32_bf16 v[80:83], v[164:167], v[238:241], v[80:83]
	v_mfma_f32_16x16x32_bf16 v[84:87], v[152:155], v[234:237], v[84:87]
	v_mfma_f32_16x16x32_bf16 v[84:87], v[156:159], v[238:241], v[84:87]
	s_setprio 0
	s_setprio 1
	v_mfma_f32_16x16x32_bf16 v[124:127], v[168:171], v[188:191], v[124:127]
	v_mfma_f32_16x16x32_bf16 v[124:127], v[172:175], v[192:195], v[124:127]
	v_mfma_f32_16x16x32_bf16 v[120:123], v[176:179], v[188:191], v[120:123]
	v_mfma_f32_16x16x32_bf16 v[120:123], v[184:187], v[192:195], v[120:123]
	v_mfma_f32_16x16x32_bf16 v[104:107], v[176:179], v[196:199], v[104:107]
	v_mfma_f32_16x16x32_bf16 v[104:107], v[184:187], v[200:203], v[104:107]
	v_mfma_f32_16x16x32_bf16 v[108:111], v[168:171], v[196:199], v[108:111]
	v_mfma_f32_16x16x32_bf16 v[108:111], v[172:175], v[200:203], v[108:111]
	v_mfma_f32_16x16x32_bf16 v[92:95], v[168:171], v[204:207], v[92:95]
	v_mfma_f32_16x16x32_bf16 v[92:95], v[172:175], v[230:233], v[92:95]
	v_mfma_f32_16x16x32_bf16 v[88:91], v[176:179], v[204:207], v[88:91]
	v_mfma_f32_16x16x32_bf16 v[88:91], v[184:187], v[230:233], v[88:91]
	v_mfma_f32_16x16x32_bf16 v[72:75], v[176:179], v[234:237], v[72:75]
	v_mfma_f32_16x16x32_bf16 v[72:75], v[184:187], v[238:241], v[72:75]
	v_mfma_f32_16x16x32_bf16 v[76:79], v[168:171], v[234:237], v[76:79]
	v_mfma_f32_16x16x32_bf16 v[76:79], v[172:175], v[238:241], v[76:79]
	s_setprio 0
	s_barrier
	s_add_i32 s81, s19, s46
	s_add_i32 s82, s81, 0x2000
	v_lshl_add_u64 v[208:209], s[84:85], 0, v[0:1]
	s_mov_b32 m0, s81
	s_add_u32 s40, s84, s48
	ds_read_b128 v[188:191], v149 offset:16384
	ds_read_b128 v[192:195], v149 offset:17408
	ds_read_b128 v[196:199], v149 offset:18432
	ds_read_b128 v[200:203], v149 offset:19456
	ds_read_b128 v[204:207], v149 offset:20480
	ds_read_b128 v[230:233], v149 offset:21504
	ds_read_b128 v[234:237], v149 offset:22528
	ds_read_b128 v[238:241], v149 offset:23552
	global_load_lds_dwordx4 v[208:209], off
	v_lshl_add_u64 v[216:217], s[84:85], 0, v[138:139]
	s_mov_b32 m0, s82
	s_addc_u32 s41, s85, s49
	s_add_i32 s83, s83, s46
	global_load_lds_dwordx4 v[216:217], off
	v_lshl_add_u64 v[224:225], s[40:41], 0, v[0:1]
	s_mov_b32 m0, s83
	s_add_i32 s84, s83, 0x2000
	global_load_lds_dwordx4 v[224:225], off
	v_lshl_add_u64 v[226:227], s[40:41], 0, v[138:139]
	s_mov_b32 m0, s84
	v_lshl_add_u64 v[228:229], s[22:23], 0, v[2:3]
	global_load_lds_dwordx4 v[226:227], off
	s_mov_b32 m0, s47
	v_lshl_add_u64 v[242:243], s[22:23], 0, v[136:137]
	global_load_lds_dwordx4 v[228:229], off
	s_mov_b32 m0, s52
	s_nop 0
	global_load_lds_dwordx4 v[242:243], off
	s_waitcnt vmcnt(8)
	s_waitcnt lgkmcnt(0)
	s_barrier
; #define PG8_STAGE(bufoff, gbase, voff) do { _Pragma("unroll") for (int _i = 0; _i < 2; ++_i) \
;         __builtin_amdgcn_global_load_lds((const unsigned*)((const char*)(gbase) + (voff)[_i]), (PG8_LAS unsigned*)(lds + (bufoff) + ldsw + _i * 8192), 16, 0, 0); } while (0)
; #define PG8_LDA(dst, b, h) do { _Pragma("unroll") for (int m = 0; m < 4; ++m) _Pragma("unroll") for (int k = 0; k < 2; ++k) dst[m][k] = *(const PG8_LAS bf16x8*)(lds + PG8_SA(b, h) + aoff + m * 2048 + k * 1024); } while (0)
; #define PG8_LDB(dst, b, h) do { _Pragma("unroll") for (int n = 0; n < 2; ++n) _Pragma("unroll") for (int k = 0; k < 2; ++k) dst[n][k] = *(const PG8_LAS bf16x8*)(lds + PG8_SB(b, h) + boff + n * 2048 + k * 1024); } while (0)
; #define PG8_MMA(ai, bj, At, Bt) do { __builtin_amdgcn_s_setprio(1); _Pragma("unroll") for (int m = 0; m < 4; ++m) _Pragma("unroll") for (int n = 0; n < 2; ++n) _Pragma("unroll") for (int k = 0; k < 2; ++k) \
;         acc[ai][bj][m][n] = __builtin_amdgcn_mfma_f32_16x16x32_bf16(Bt[n][k], At[m][k], acc[ai][bj][m][n], 0, 0, 0); __builtin_amdgcn_s_setprio(0); } while (0)
; #define PG8_WAIT_V(n) asm volatile("s_waitcnt vmcnt(" #n ")" ::: "memory")
; #define PG8_WAIT_L(n) asm volatile("s_waitcnt lgkmcnt(" #n ")" ::: "memory")
; #define PG8_BAR __builtin_amdgcn_s_barrier()
; #define PG8_SCHED __builtin_amdgcn_sched_barrier(0)
; template <class Epi, class Sched, bool ALIGN_EPI = false, bool SP2 = false>
; __device__ __forceinline__ void gemm_phase(PG8_LAS unsigned char* lds, const Gemm g, const Sched& S, const Epi& E) {
;     ...
;             PG8_WAIT_V(8); PG8_WAIT_L(0); PG8_BAR; PG8_MMA(1, 0, At, B0); PG8_MMA(1, 1, At, B1); PG8_BAR; PG8_SCHED;
;             PG8_LDB(B0, 1, 0); PG8_LDB(B1, 1, 1); PG8_SCHED; PG8_LDA(At, 1, 0); PG8_STAGE(PG8_SA(0, 1), a2 + hstep, voffA);
;             PG8_WAIT_V(8); PG8_WAIT_L(0); PG8_BAR; PG8_MMA(0, 0, At, B0); PG8_MMA(0, 1, At, B1); PG8_BAR; PG8_SCHED;
	s_setprio 1
	s_waitcnt lgkmcnt(0)
	v_mfma_f32_16x16x32_bf16 v[68:71], v[152:155], v[188:191], v[68:71]
	v_mfma_f32_16x16x32_bf16 v[68:71], v[156:159], v[192:195], v[68:71]
	v_mfma_f32_16x16x32_bf16 v[64:67], v[160:163], v[188:191], v[64:67]
	v_mfma_f32_16x16x32_bf16 v[64:67], v[164:167], v[192:195], v[64:67]
	v_mfma_f32_16x16x32_bf16 v[48:51], v[160:163], v[196:199], v[48:51]
	v_mfma_f32_16x16x32_bf16 v[48:51], v[164:167], v[200:203], v[48:51]
	v_mfma_f32_16x16x32_bf16 v[52:55], v[152:155], v[196:199], v[52:55]
	v_mfma_f32_16x16x32_bf16 v[52:55], v[156:159], v[200:203], v[52:55]
	v_mfma_f32_16x16x32_bf16 v[36:39], v[152:155], v[204:207], v[36:39]
	v_mfma_f32_16x16x32_bf16 v[36:39], v[156:159], v[230:233], v[36:39]
	v_mfma_f32_16x16x32_bf16 v[32:35], v[160:163], v[204:207], v[32:35]
	v_mfma_f32_16x16x32_bf16 v[32:35], v[164:167], v[230:233], v[32:35]
	v_mfma_f32_16x16x32_bf16 v[16:19], v[160:163], v[234:237], v[16:19]
	v_mfma_f32_16x16x32_bf16 v[16:19], v[164:167], v[238:241], v[16:19]
	v_mfma_f32_16x16x32_bf16 v[20:23], v[152:155], v[234:237], v[20:23]
	v_mfma_f32_16x16x32_bf16 v[20:23], v[156:159], v[238:241], v[20:23]
	s_setprio 0
	s_setprio 1
	v_mfma_f32_16x16x32_bf16 v[60:63], v[168:171], v[188:191], v[60:63]
	v_mfma_f32_16x16x32_bf16 v[60:63], v[172:175], v[192:195], v[60:63]
	v_mfma_f32_16x16x32_bf16 v[56:59], v[176:179], v[188:191], v[56:59]
	v_mfma_f32_16x16x32_bf16 v[56:59], v[184:187], v[192:195], v[56:59]
	v_mfma_f32_16x16x32_bf16 v[40:43], v[176:179], v[196:199], v[40:43]
	v_mfma_f32_16x16x32_bf16 v[40:43], v[184:187], v[200:203], v[40:43]
	v_mfma_f32_16x16x32_bf16 v[44:47], v[168:171], v[196:199], v[44:47]
	v_mfma_f32_16x16x32_bf16 v[44:47], v[172:175], v[200:203], v[44:47]
	v_mfma_f32_16x16x32_bf16 v[28:31], v[168:171], v[204:207], v[28:31]
	v_mfma_f32_16x16x32_bf16 v[28:31], v[172:175], v[230:233], v[28:31]
	v_mfma_f32_16x16x32_bf16 v[24:27], v[176:179], v[204:207], v[24:27]
	v_mfma_f32_16x16x32_bf16 v[24:27], v[184:187], v[230:233], v[24:27]
	v_mfma_f32_16x16x32_bf16 v[8:11], v[176:179], v[234:237], v[8:11]
	v_mfma_f32_16x16x32_bf16 v[8:11], v[184:187], v[238:241], v[8:11]
	v_mfma_f32_16x16x32_bf16 v[12:15], v[168:171], v[234:237], v[12:15]
	v_mfma_f32_16x16x32_bf16 v[12:15], v[172:175], v[238:241], v[12:15]
	s_setprio 0
	s_barrier
	s_add_i32 s87, 0, 0x1c000
	v_add_u32_e32 v152, s91, v147
	v_add_u32_e32 v153, s87, v147
	ds_read_b128 v[154:157], v152
	ds_read_b128 v[158:161], v152 offset:1024
	ds_read_b128 v[162:165], v152 offset:2048
	ds_read_b128 v[166:169], v152 offset:3072
	ds_read_b128 v[170:173], v153
	ds_read_b128 v[174:177], v153 offset:1024
	ds_read_b128 v[178:181], v153 offset:2048
	ds_read_b128 v[184:187], v153 offset:3072
	s_add_u32 s22, s22, s48
	s_addc_u32 s23, s23, s49
	s_mov_b32 m0, s53
	v_lshl_add_u64 v[244:245], s[22:23], 0, v[2:3]
	ds_read_b128 v[188:191], v149 offset:32768
	ds_read_b128 v[192:195], v149 offset:33792
	ds_read_b128 v[196:199], v149 offset:34816
	ds_read_b128 v[200:203], v149 offset:35840
	ds_read_b128 v[204:207], v149 offset:36864
	ds_read_b128 v[230:233], v149 offset:37888
	ds_read_b128 v[234:237], v149 offset:38912
	ds_read_b128 v[238:241], v149 offset:39936
	global_load_lds_dwordx4 v[244:245], off
	v_lshl_add_u64 v[244:245], s[22:23], 0, v[136:137]
	s_mov_b32 m0, s72
	s_nop 0
	global_load_lds_dwordx4 v[244:245], off
	s_waitcnt vmcnt(8)
	s_waitcnt lgkmcnt(0)
	s_barrier
	s_setprio 1
	s_waitcnt lgkmcnt(0)
	v_mfma_f32_16x16x32_bf16 v[132:135], v[154:157], v[188:191], v[132:135]
	v_mfma_f32_16x16x32_bf16 v[132:135], v[158:161], v[192:195], v[132:135]
	v_mfma_f32_16x16x32_bf16 v[128:131], v[162:165], v[188:191], v[128:131]
	v_mfma_f32_16x16x32_bf16 v[128:131], v[166:169], v[192:195], v[128:131]
	v_mfma_f32_16x16x32_bf16 v[112:115], v[162:165], v[196:199], v[112:115]
	v_mfma_f32_16x16x32_bf16 v[112:115], v[166:169], v[200:203], v[112:115]
	v_mfma_f32_16x16x32_bf16 v[116:119], v[154:157], v[196:199], v[116:119]
	v_mfma_f32_16x16x32_bf16 v[116:119], v[158:161], v[200:203], v[116:119]
	v_mfma_f32_16x16x32_bf16 v[100:103], v[154:157], v[204:207], v[100:103]
	v_mfma_f32_16x16x32_bf16 v[100:103], v[158:161], v[230:233], v[100:103]
	v_mfma_f32_16x16x32_bf16 v[96:99], v[162:165], v[204:207], v[96:99]
	v_mfma_f32_16x16x32_bf16 v[96:99], v[166:169], v[230:233], v[96:99]
	v_mfma_f32_16x16x32_bf16 v[80:83], v[162:165], v[234:237], v[80:83]
	v_mfma_f32_16x16x32_bf16 v[80:83], v[166:169], v[238:241], v[80:83]
	v_mfma_f32_16x16x32_bf16 v[84:87], v[154:157], v[234:237], v[84:87]
	v_mfma_f32_16x16x32_bf16 v[84:87], v[158:161], v[238:241], v[84:87]
	s_setprio 0
	s_setprio 1
	v_mfma_f32_16x16x32_bf16 v[124:127], v[170:173], v[188:191], v[124:127]
	v_mfma_f32_16x16x32_bf16 v[124:127], v[174:177], v[192:195], v[124:127]
	v_mfma_f32_16x16x32_bf16 v[120:123], v[178:181], v[188:191], v[120:123]
	v_mfma_f32_16x16x32_bf16 v[120:123], v[184:187], v[192:195], v[120:123]
	v_mfma_f32_16x16x32_bf16 v[104:107], v[178:181], v[196:199], v[104:107]
	v_mfma_f32_16x16x32_bf16 v[104:107], v[184:187], v[200:203], v[104:107]
	v_mfma_f32_16x16x32_bf16 v[108:111], v[170:173], v[196:199], v[108:111]
	v_mfma_f32_16x16x32_bf16 v[108:111], v[174:177], v[200:203], v[108:111]
	v_mfma_f32_16x16x32_bf16 v[92:95], v[170:173], v[204:207], v[92:95]
	v_mfma_f32_16x16x32_bf16 v[92:95], v[174:177], v[230:233], v[92:95]
	v_mfma_f32_16x16x32_bf16 v[88:91], v[178:181], v[204:207], v[88:91]
	v_mfma_f32_16x16x32_bf16 v[88:91], v[184:187], v[230:233], v[88:91]
	v_mfma_f32_16x16x32_bf16 v[72:75], v[178:181], v[234:237], v[72:75]
	v_mfma_f32_16x16x32_bf16 v[72:75], v[184:187], v[238:241], v[72:75]
	v_mfma_f32_16x16x32_bf16 v[76:79], v[170:173], v[234:237], v[76:79]
	v_mfma_f32_16x16x32_bf16 v[76:79], v[174:177], v[238:241], v[76:79]
	s_setprio 0
	s_barrier
; #define PG8_STAGE(bufoff, gbase, voff) do { _Pragma("unroll") for (int _i = 0; _i < 2; ++_i) \
;         __builtin_amdgcn_global_load_lds((const unsigned*)((const char*)(gbase) + (voff)[_i]), (PG8_LAS unsigned*)(lds + (bufoff) + ldsw + _i * 8192), 16, 0, 0); } while (0)
; #define PG8_LDA(dst, b, h) do { _Pragma("unroll") for (int m = 0; m < 4; ++m) _Pragma("unroll") for (int k = 0; k < 2; ++k) dst[m][k] = *(const PG8_LAS bf16x8*)(lds + PG8_SA(b, h) + aoff + m * 2048 + k * 1024); } while (0)
; #define PG8_MMA(ai, bj, At, Bt) do { __builtin_amdgcn_s_setprio(1); _Pragma("unroll") for (int m = 0; m < 4; ++m) _Pragma("unroll") for (int n = 0; n < 2; ++n) _Pragma("unroll") for (int k = 0; k < 2; ++k) \
;         acc[ai][bj][m][n] = __builtin_amdgcn_mfma_f32_16x16x32_bf16(Bt[n][k], At[m][k], acc[ai][bj][m][n], 0, 0, 0); __builtin_amdgcn_s_setprio(0); } while (0)
; #define PG8_WAIT_V(n) asm volatile("s_waitcnt vmcnt(" #n ")" ::: "memory")
; #define PG8_WAIT_L(n) asm volatile("s_waitcnt lgkmcnt(" #n ")" ::: "memory")
; #define PG8_BAR __builtin_amdgcn_s_barrier()
; #define PG8_SCHED __builtin_amdgcn_sched_barrier(0)
; template <class Epi, class Sched, bool ALIGN_EPI = false, bool SP2 = false>
; __device__ __forceinline__ void gemm_phase(PG8_LAS unsigned char* lds, const Gemm g, const Sched& S, const Epi& E) {
;     ...
;             if constexpr (Epi::KHOOK) { if ((t & 7) == 0 && t != 0) E.khook(acc, t >> 3, wr, fr, lds); }
;             const bool last = (t == nt - 2);
;     ...
;             PG8_LDA(At, 1, 1); PG8_STAGE(PG8_SB(1, 0), b3, voffB); PG8_STAGE(PG8_SB(1, 1), b3 + hstep, voffB); PG8_STAGE(PG8_SA(1, 0), a3, voffA);
;             PG8_WAIT_V(8); PG8_WAIT_L(0); PG8_BAR; PG8_MMA(1, 0, At, B0); PG8_MMA(1, 1, At, B1); PG8_BAR; PG8_SCHED;
	s_add_i32 s85, s91, s46
	v_lshl_add_u64 v[208:209], v[208:209], 0, s[24:25]
	s_mov_b32 m0, s85
	s_add_i32 s86, s85, 0x2000
	ds_read_b128 v[188:191], v149 offset:49152
	ds_read_b128 v[192:195], v149 offset:50176
	ds_read_b128 v[196:199], v149 offset:51200
	ds_read_b128 v[200:203], v149 offset:52224
	ds_read_b128 v[204:207], v149 offset:53248
	ds_read_b128 v[230:233], v149 offset:54272
	ds_read_b128 v[234:237], v149 offset:55296
	ds_read_b128 v[238:241], v149 offset:56320
	global_load_lds_dwordx4 v[208:209], off
	v_lshl_add_u64 v[208:209], v[216:217], 0, s[24:25]
	s_mov_b32 m0, s86
	s_add_i32 s87, s87, s46
	global_load_lds_dwordx4 v[208:209], off
	v_lshl_add_u64 v[208:209], v[224:225], 0, s[24:25]
	s_mov_b32 m0, s87
	s_add_i32 s88, s87, 0x2000
	global_load_lds_dwordx4 v[208:209], off
	v_lshl_add_u64 v[208:209], v[226:227], 0, s[24:25]
	s_mov_b32 m0, s88
	s_nop 0
	global_load_lds_dwordx4 v[208:209], off
	v_lshl_add_u64 v[208:209], v[228:229], 0, s[24:25]
	s_mov_b32 m0, s75
	s_nop 0
	global_load_lds_dwordx4 v[208:209], off
	v_lshl_add_u64 v[208:209], v[242:243], 0, s[24:25]
	s_mov_b32 m0, s76
	s_nop 0
	global_load_lds_dwordx4 v[208:209], off
	s_waitcnt vmcnt(8)
	s_waitcnt lgkmcnt(0)
	s_barrier
	s_setprio 1
	s_waitcnt lgkmcnt(0)
	v_mfma_f32_16x16x32_bf16 v[68:71], v[154:157], v[188:191], v[68:71]
	v_mfma_f32_16x16x32_bf16 v[68:71], v[158:161], v[192:195], v[68:71]
	v_mfma_f32_16x16x32_bf16 v[64:67], v[162:165], v[188:191], v[64:67]
	v_mfma_f32_16x16x32_bf16 v[64:67], v[166:169], v[192:195], v[64:67]
	v_mfma_f32_16x16x32_bf16 v[48:51], v[162:165], v[196:199], v[48:51]
	v_mfma_f32_16x16x32_bf16 v[48:51], v[166:169], v[200:203], v[48:51]
	v_mfma_f32_16x16x32_bf16 v[52:55], v[154:157], v[196:199], v[52:55]
	v_mfma_f32_16x16x32_bf16 v[52:55], v[158:161], v[200:203], v[52:55]
	v_mfma_f32_16x16x32_bf16 v[36:39], v[154:157], v[204:207], v[36:39]
	v_mfma_f32_16x16x32_bf16 v[36:39], v[158:161], v[230:233], v[36:39]
	v_mfma_f32_16x16x32_bf16 v[32:35], v[162:165], v[204:207], v[32:35]
	v_mfma_f32_16x16x32_bf16 v[32:35], v[166:169], v[230:233], v[32:35]
	v_mfma_f32_16x16x32_bf16 v[16:19], v[162:165], v[234:237], v[16:19]
	v_mfma_f32_16x16x32_bf16 v[16:19], v[166:169], v[238:241], v[16:19]
	v_mfma_f32_16x16x32_bf16 v[20:23], v[154:157], v[234:237], v[20:23]
	v_mfma_f32_16x16x32_bf16 v[20:23], v[158:161], v[238:241], v[20:23]
	s_setprio 0
	s_setprio 1
	v_mfma_f32_16x16x32_bf16 v[60:63], v[170:173], v[188:191], v[60:63]
	v_mfma_f32_16x16x32_bf16 v[60:63], v[174:177], v[192:195], v[60:63]
	v_mfma_f32_16x16x32_bf16 v[56:59], v[178:181], v[188:191], v[56:59]
	v_mfma_f32_16x16x32_bf16 v[56:59], v[184:187], v[192:195], v[56:59]
	v_mfma_f32_16x16x32_bf16 v[40:43], v[178:181], v[196:199], v[40:43]
	v_mfma_f32_16x16x32_bf16 v[40:43], v[184:187], v[200:203], v[40:43]
	v_mfma_f32_16x16x32_bf16 v[44:47], v[170:173], v[196:199], v[44:47]
	v_mfma_f32_16x16x32_bf16 v[44:47], v[174:177], v[200:203], v[44:47]
	v_mfma_f32_16x16x32_bf16 v[28:31], v[170:173], v[204:207], v[28:31]
	v_mfma_f32_16x16x32_bf16 v[28:31], v[174:177], v[230:233], v[28:31]
	v_mfma_f32_16x16x32_bf16 v[24:27], v[178:181], v[204:207], v[24:27]
	v_mfma_f32_16x16x32_bf16 v[24:27], v[184:187], v[230:233], v[24:27]
	v_mfma_f32_16x16x32_bf16 v[8:11], v[178:181], v[234:237], v[8:11]
	v_mfma_f32_16x16x32_bf16 v[8:11], v[184:187], v[238:241], v[8:11]
	v_mfma_f32_16x16x32_bf16 v[12:15], v[170:173], v[234:237], v[12:15]
	v_mfma_f32_16x16x32_bf16 v[12:15], v[174:177], v[238:241], v[12:15]
	s_setprio 0
	s_barrier
	v_readlane_b32 s22, v252, 42
	v_readlane_b32 s23, v252, 43
	s_andn2_b64 vcc, exec, s[22:23]
	s_cbranch_vccnz .LBB0_251
	s_add_u32 s22, s6, 0x180
	s_addc_u32 s23, s7, 0
	s_add_u32 s89, s10, 0x200
	s_addc_u32 s92, s11, 0
	s_mov_b32 s93, 4
	v_mov_b32_e32 v154, v148
	s_add_i32 s40, s93, -2
	s_and_b32 s40, s40, 6
	s_cmp_lg_u32 s40, 0
	s_cbranch_scc1 .LBB0_250
	s_branch .LBB0_249

; #define PG8_STAGE(bufoff, gbase, voff) do { _Pragma("unroll") for (int _i = 0; _i < 2; ++_i) \
;         __builtin_amdgcn_global_load_lds((const unsigned*)((const char*)(gbase) + (voff)[_i]), (PG8_LAS unsigned*)(lds + (bufoff) + ldsw + _i * 8192), 16, 0, 0); } while (0)
; #define PG8_LDA(dst, b, h) do { _Pragma("unroll") for (int m = 0; m < 4; ++m) _Pragma("unroll") for (int k = 0; k < 2; ++k) dst[m][k] = *(const PG8_LAS bf16x8*)(lds + PG8_SA(b, h) + aoff + m * 2048 + k * 1024); } while (0)
; #define PG8_LDB(dst, b, h) do { _Pragma("unroll") for (int n = 0; n < 2; ++n) _Pragma("unroll") for (int k = 0; k < 2; ++k) dst[n][k] = *(const PG8_LAS bf16x8*)(lds + PG8_SB(b, h) + boff + n * 2048 + k * 1024); } while (0)
; #define PG8_MMA(ai, bj, At, Bt) do { __builtin_amdgcn_s_setprio(1); _Pragma("unroll") for (int m = 0; m < 4; ++m) _Pragma("unroll") for (int n = 0; n < 2; ++n) _Pragma("unroll") for (int k = 0; k < 2; ++k) \
;         acc[ai][bj][m][n] = __builtin_amdgcn_mfma_f32_16x16x32_bf16(Bt[n][k], At[m][k], acc[ai][bj][m][n], 0, 0, 0); __builtin_amdgcn_s_setprio(0); } while (0)
; #define PG8_WAIT_V(n) asm volatile("s_waitcnt vmcnt(" #n ")" ::: "memory")
; #define PG8_WAIT_L(n) asm volatile("s_waitcnt lgkmcnt(" #n ")" ::: "memory")
; #define PG8_BAR __builtin_amdgcn_s_barrier()
; #define PG8_SCHED __builtin_amdgcn_sched_barrier(0)
; template <class Epi, class Sched, bool ALIGN_EPI = false, bool SP2 = false>
; __device__ __forceinline__ void gemm_phase(PG8_LAS unsigned char* lds, const Gemm g, const Sched& S, const Epi& E) {
;     ...
;             const bool last = (t == nt - 2);
;             const char* a1 = cA + (size_t)(t + 1) * kstep;
;             const char* a2 = last ? nA : cA + (size_t)(t + 2) * kstep; const char* b2 = last ? nB : cB + (size_t)(t + 2) * kstep;
;             const char* a3 = a2 + kstep; const char* b3 = b2 + kstep;
;             if (last && has_next) S.a_ready(nxt);
;             if constexpr (SP2) {
;             PG8_LDB(B0, 0, 0); PG8_LDB(B1, 0, 1); PG8_SCHED; PG8_LDA(At, 0, 0); PG8_STAGE(PG8_SA(1, 1), a1 + hstep, voffA);
;             PG8_WAIT_V(8); PG8_WAIT_L(0); PG8_BAR; PG8_MMA(0, 0, At, B0); PG8_MMA(0, 1, At, B1); PG8_BAR; PG8_SCHED;
;             PG8_LDA(At, 0, 1); PG8_STAGE(PG8_SB(0, 0), b2, voffB); PG8_STAGE(PG8_SB(0, 1), b2 + hstep, voffB); PG8_STAGE(PG8_SA(0, 0), a2, voffA);
.LBB0_250:
	ds_read_b128 v[156:159], v150
	ds_read_b128 v[160:163], v150 offset:1024
	ds_read_b128 v[164:167], v150 offset:2048
	ds_read_b128 v[168:171], v150 offset:3072
	ds_read_b128 v[172:175], v151
	ds_read_b128 v[176:179], v151 offset:1024
	ds_read_b128 v[184:187], v151 offset:2048
	ds_read_b128 v[188:191], v151 offset:3072
	s_add_u32 s40, s22, 0x80
	s_addc_u32 s41, s23, 0
	s_cmp_eq_u32 s9, s93
	s_cselect_b32 s40, s4, s40
	s_cselect_b32 s41, s5, s41
	s_cselect_b32 s95, s17, s92
	s_cselect_b32 s94, s16, s89
	s_mov_b32 m0, s37
	v_lshl_add_u64 v[180:181], s[22:23], 0, v[140:141]
	ds_read_b128 v[192:195], v149
	ds_read_b128 v[196:199], v149 offset:1024
	ds_read_b128 v[200:203], v149 offset:2048
	ds_read_b128 v[204:207], v149 offset:3072
	ds_read_b128 v[230:233], v149 offset:4096
	ds_read_b128 v[234:237], v149 offset:5120
	ds_read_b128 v[238:241], v149 offset:6144
	ds_read_b128 v[242:245], v149 offset:7168
	global_load_lds_dwordx4 v[180:181], off
	v_lshl_add_u64 v[180:181], s[22:23], 0, v[142:143]
	s_mov_b32 m0, s80
	s_nop 0
	global_load_lds_dwordx4 v[180:181], off
	s_waitcnt vmcnt(8)
	s_waitcnt lgkmcnt(0)
	s_barrier
	s_setprio 1
	s_waitcnt lgkmcnt(0)
	v_mfma_f32_16x16x32_bf16 v[132:135], v[156:159], v[192:195], v[132:135]
	v_mfma_f32_16x16x32_bf16 v[132:135], v[160:163], v[196:199], v[132:135]
	v_mfma_f32_16x16x32_bf16 v[128:131], v[164:167], v[192:195], v[128:131]
	v_mfma_f32_16x16x32_bf16 v[128:131], v[168:171], v[196:199], v[128:131]
	v_mfma_f32_16x16x32_bf16 v[112:115], v[164:167], v[200:203], v[112:115]
	v_mfma_f32_16x16x32_bf16 v[112:115], v[168:171], v[204:207], v[112:115]
	v_mfma_f32_16x16x32_bf16 v[116:119], v[156:159], v[200:203], v[116:119]
	v_mfma_f32_16x16x32_bf16 v[116:119], v[160:163], v[204:207], v[116:119]
	v_mfma_f32_16x16x32_bf16 v[100:103], v[156:159], v[230:233], v[100:103]
	v_mfma_f32_16x16x32_bf16 v[100:103], v[160:163], v[234:237], v[100:103]
	v_mfma_f32_16x16x32_bf16 v[96:99], v[164:167], v[230:233], v[96:99]
	v_mfma_f32_16x16x32_bf16 v[96:99], v[168:171], v[234:237], v[96:99]
	v_mfma_f32_16x16x32_bf16 v[80:83], v[164:167], v[238:241], v[80:83]
	v_mfma_f32_16x16x32_bf16 v[80:83], v[168:171], v[242:245], v[80:83]
	v_mfma_f32_16x16x32_bf16 v[84:87], v[156:159], v[238:241], v[84:87]
	v_mfma_f32_16x16x32_bf16 v[84:87], v[160:163], v[242:245], v[84:87]
	s_setprio 0
	s_setprio 1
	v_mfma_f32_16x16x32_bf16 v[124:127], v[172:175], v[192:195], v[124:127]
	v_mfma_f32_16x16x32_bf16 v[124:127], v[176:179], v[196:199], v[124:127]
	v_mfma_f32_16x16x32_bf16 v[120:123], v[184:187], v[192:195], v[120:123]
	v_mfma_f32_16x16x32_bf16 v[120:123], v[188:191], v[196:199], v[120:123]
	v_mfma_f32_16x16x32_bf16 v[104:107], v[184:187], v[200:203], v[104:107]
	v_mfma_f32_16x16x32_bf16 v[104:107], v[188:191], v[204:207], v[104:107]
	v_mfma_f32_16x16x32_bf16 v[108:111], v[172:175], v[200:203], v[108:111]
	v_mfma_f32_16x16x32_bf16 v[108:111], v[176:179], v[204:207], v[108:111]
	v_mfma_f32_16x16x32_bf16 v[92:95], v[172:175], v[230:233], v[92:95]
	v_mfma_f32_16x16x32_bf16 v[92:95], v[176:179], v[234:237], v[92:95]
	v_mfma_f32_16x16x32_bf16 v[88:91], v[184:187], v[230:233], v[88:91]
	v_mfma_f32_16x16x32_bf16 v[88:91], v[188:191], v[234:237], v[88:91]
	v_mfma_f32_16x16x32_bf16 v[72:75], v[184:187], v[238:241], v[72:75]
	v_mfma_f32_16x16x32_bf16 v[72:75], v[188:191], v[242:245], v[72:75]
	v_mfma_f32_16x16x32_bf16 v[76:79], v[172:175], v[238:241], v[76:79]
	v_mfma_f32_16x16x32_bf16 v[76:79], v[176:179], v[242:245], v[76:79]
	s_setprio 0
	s_barrier
	s_mov_b32 m0, s81
	v_lshl_add_u64 v[180:181], s[94:95], 0, v[0:1]
	v_lshl_add_u64 v[208:209], s[94:95], 0, v[138:139]
	s_add_u32 s94, s94, s48
	ds_read_b128 v[192:195], v149 offset:16384
	ds_read_b128 v[196:199], v149 offset:17408
	ds_read_b128 v[200:203], v149 offset:18432
	ds_read_b128 v[204:207], v149 offset:19456
	ds_read_b128 v[230:233], v149 offset:20480
	ds_read_b128 v[234:237], v149 offset:21504
	ds_read_b128 v[238:241], v149 offset:22528
	ds_read_b128 v[242:245], v149 offset:23552
	global_load_lds_dwordx4 v[180:181], off
	s_mov_b32 m0, s82
	s_addc_u32 s95, s95, s49
	global_load_lds_dwordx4 v[208:209], off
	v_lshl_add_u64 v[216:217], s[94:95], 0, v[0:1]
	s_mov_b32 m0, s83
	v_lshl_add_u64 v[224:225], s[94:95], 0, v[138:139]
	global_load_lds_dwordx4 v[216:217], off
	s_mov_b32 m0, s84
	v_lshl_add_u64 v[226:227], s[40:41], 0, v[2:3]
	global_load_lds_dwordx4 v[224:225], off
	s_mov_b32 m0, s47
	v_lshl_add_u64 v[228:229], s[40:41], 0, v[136:137]
	global_load_lds_dwordx4 v[226:227], off
	s_mov_b32 m0, s52
	s_nop 0
	global_load_lds_dwordx4 v[228:229], off
	s_waitcnt vmcnt(8)
	s_waitcnt lgkmcnt(0)
	s_barrier
; #define PG8_STAGE(bufoff, gbase, voff) do { _Pragma("unroll") for (int _i = 0; _i < 2; ++_i) \
;         __builtin_amdgcn_global_load_lds((const unsigned*)((const char*)(gbase) + (voff)[_i]), (PG8_LAS unsigned*)(lds + (bufoff) + ldsw + _i * 8192), 16, 0, 0); } while (0)
; #define PG8_LDA(dst, b, h) do { _Pragma("unroll") for (int m = 0; m < 4; ++m) _Pragma("unroll") for (int k = 0; k < 2; ++k) dst[m][k] = *(const PG8_LAS bf16x8*)(lds + PG8_SA(b, h) + aoff + m * 2048 + k * 1024); } while (0)
; #define PG8_LDB(dst, b, h) do { _Pragma("unroll") for (int n = 0; n < 2; ++n) _Pragma("unroll") for (int k = 0; k < 2; ++k) dst[n][k] = *(const PG8_LAS bf16x8*)(lds + PG8_SB(b, h) + boff + n * 2048 + k * 1024); } while (0)
; #define PG8_MMA(ai, bj, At, Bt) do { __builtin_amdgcn_s_setprio(1); _Pragma("unroll") for (int m = 0; m < 4; ++m) _Pragma("unroll") for (int n = 0; n < 2; ++n) _Pragma("unroll") for (int k = 0; k < 2; ++k) \
;         acc[ai][bj][m][n] = __builtin_amdgcn_mfma_f32_16x16x32_bf16(Bt[n][k], At[m][k], acc[ai][bj][m][n], 0, 0, 0); __builtin_amdgcn_s_setprio(0); } while (0)
; #define PG8_WAIT_V(n) asm volatile("s_waitcnt vmcnt(" #n ")" ::: "memory")
; #define PG8_WAIT_L(n) asm volatile("s_waitcnt lgkmcnt(" #n ")" ::: "memory")
; #define PG8_BAR __builtin_amdgcn_s_barrier()
; #define PG8_SCHED __builtin_amdgcn_sched_barrier(0)
; template <class Epi, class Sched, bool ALIGN_EPI = false, bool SP2 = false>
; __device__ __forceinline__ void gemm_phase(PG8_LAS unsigned char* lds, const Gemm g, const Sched& S, const Epi& E) {
;     ...
;             PG8_WAIT_V(8); PG8_WAIT_L(0); PG8_BAR; PG8_MMA(1, 0, At, B0); PG8_MMA(1, 1, At, B1); PG8_BAR; PG8_SCHED;
;             PG8_LDB(B0, 1, 0); PG8_LDB(B1, 1, 1); PG8_SCHED; PG8_LDA(At, 1, 0); PG8_STAGE(PG8_SA(0, 1), a2 + hstep, voffA);
;             PG8_WAIT_V(8); PG8_WAIT_L(0); PG8_BAR; PG8_MMA(0, 0, At, B0); PG8_MMA(0, 1, At, B1); PG8_BAR; PG8_SCHED;
	s_setprio 1
	s_waitcnt lgkmcnt(0)
	v_mfma_f32_16x16x32_bf16 v[68:71], v[156:159], v[192:195], v[68:71]
	v_mfma_f32_16x16x32_bf16 v[68:71], v[160:163], v[196:199], v[68:71]
	v_mfma_f32_16x16x32_bf16 v[64:67], v[164:167], v[192:195], v[64:67]
	v_mfma_f32_16x16x32_bf16 v[64:67], v[168:171], v[196:199], v[64:67]
	v_mfma_f32_16x16x32_bf16 v[48:51], v[164:167], v[200:203], v[48:51]
	v_mfma_f32_16x16x32_bf16 v[48:51], v[168:171], v[204:207], v[48:51]
	v_mfma_f32_16x16x32_bf16 v[52:55], v[156:159], v[200:203], v[52:55]
	v_mfma_f32_16x16x32_bf16 v[52:55], v[160:163], v[204:207], v[52:55]
	v_mfma_f32_16x16x32_bf16 v[36:39], v[156:159], v[230:233], v[36:39]
	v_mfma_f32_16x16x32_bf16 v[36:39], v[160:163], v[234:237], v[36:39]
	v_mfma_f32_16x16x32_bf16 v[32:35], v[164:167], v[230:233], v[32:35]
	v_mfma_f32_16x16x32_bf16 v[32:35], v[168:171], v[234:237], v[32:35]
	v_mfma_f32_16x16x32_bf16 v[16:19], v[164:167], v[238:241], v[16:19]
	v_mfma_f32_16x16x32_bf16 v[16:19], v[168:171], v[242:245], v[16:19]
	v_mfma_f32_16x16x32_bf16 v[20:23], v[156:159], v[238:241], v[20:23]
	v_mfma_f32_16x16x32_bf16 v[20:23], v[160:163], v[242:245], v[20:23]
	s_setprio 0
	s_setprio 1
	v_mfma_f32_16x16x32_bf16 v[60:63], v[172:175], v[192:195], v[60:63]
	v_mfma_f32_16x16x32_bf16 v[60:63], v[176:179], v[196:199], v[60:63]
	v_mfma_f32_16x16x32_bf16 v[56:59], v[184:187], v[192:195], v[56:59]
	v_mfma_f32_16x16x32_bf16 v[56:59], v[188:191], v[196:199], v[56:59]
	v_mfma_f32_16x16x32_bf16 v[40:43], v[184:187], v[200:203], v[40:43]
	v_mfma_f32_16x16x32_bf16 v[40:43], v[188:191], v[204:207], v[40:43]
	v_mfma_f32_16x16x32_bf16 v[44:47], v[172:175], v[200:203], v[44:47]
	v_mfma_f32_16x16x32_bf16 v[44:47], v[176:179], v[204:207], v[44:47]
	v_mfma_f32_16x16x32_bf16 v[28:31], v[172:175], v[230:233], v[28:31]
	v_mfma_f32_16x16x32_bf16 v[28:31], v[176:179], v[234:237], v[28:31]
	v_mfma_f32_16x16x32_bf16 v[24:27], v[184:187], v[230:233], v[24:27]
	v_mfma_f32_16x16x32_bf16 v[24:27], v[188:191], v[234:237], v[24:27]
	v_mfma_f32_16x16x32_bf16 v[8:11], v[184:187], v[238:241], v[8:11]
	v_mfma_f32_16x16x32_bf16 v[8:11], v[188:191], v[242:245], v[8:11]
	v_mfma_f32_16x16x32_bf16 v[12:15], v[172:175], v[238:241], v[12:15]
	v_mfma_f32_16x16x32_bf16 v[12:15], v[176:179], v[242:245], v[12:15]
	s_setprio 0
	s_barrier
	ds_read_b128 v[156:159], v152
	ds_read_b128 v[160:163], v152 offset:1024
	ds_read_b128 v[164:167], v152 offset:2048
	ds_read_b128 v[168:171], v152 offset:3072
	ds_read_b128 v[172:175], v153
	ds_read_b128 v[176:179], v153 offset:1024
	ds_read_b128 v[184:187], v153 offset:2048
	ds_read_b128 v[188:191], v153 offset:3072
	s_add_u32 s40, s40, s48
	s_addc_u32 s41, s41, s49
	s_mov_b32 m0, s53
	v_lshl_add_u64 v[246:247], s[40:41], 0, v[2:3]
	ds_read_b128 v[192:195], v149 offset:32768
	ds_read_b128 v[196:199], v149 offset:33792
	ds_read_b128 v[200:203], v149 offset:34816
	ds_read_b128 v[204:207], v149 offset:35840
	ds_read_b128 v[230:233], v149 offset:36864
	ds_read_b128 v[234:237], v149 offset:37888
	ds_read_b128 v[238:241], v149 offset:38912
	ds_read_b128 v[242:245], v149 offset:39936
	global_load_lds_dwordx4 v[246:247], off
	v_lshl_add_u64 v[246:247], s[40:41], 0, v[136:137]
	s_mov_b32 m0, s72
	s_nop 0
	global_load_lds_dwordx4 v[246:247], off
	s_waitcnt vmcnt(8)
	s_waitcnt lgkmcnt(0)
	s_barrier
	s_setprio 1
	s_waitcnt lgkmcnt(0)
	v_mfma_f32_16x16x32_bf16 v[132:135], v[156:159], v[192:195], v[132:135]
	v_mfma_f32_16x16x32_bf16 v[132:135], v[160:163], v[196:199], v[132:135]
	v_mfma_f32_16x16x32_bf16 v[128:131], v[164:167], v[192:195], v[128:131]
	v_mfma_f32_16x16x32_bf16 v[128:131], v[168:171], v[196:199], v[128:131]
	v_mfma_f32_16x16x32_bf16 v[112:115], v[164:167], v[200:203], v[112:115]
	v_mfma_f32_16x16x32_bf16 v[112:115], v[168:171], v[204:207], v[112:115]
	v_mfma_f32_16x16x32_bf16 v[116:119], v[156:159], v[200:203], v[116:119]
	v_mfma_f32_16x16x32_bf16 v[116:119], v[160:163], v[204:207], v[116:119]
	v_mfma_f32_16x16x32_bf16 v[100:103], v[156:159], v[230:233], v[100:103]
	v_mfma_f32_16x16x32_bf16 v[100:103], v[160:163], v[234:237], v[100:103]
	v_mfma_f32_16x16x32_bf16 v[96:99], v[164:167], v[230:233], v[96:99]
	v_mfma_f32_16x16x32_bf16 v[96:99], v[168:171], v[234:237], v[96:99]
	v_mfma_f32_16x16x32_bf16 v[80:83], v[164:167], v[238:241], v[80:83]
	v_mfma_f32_16x16x32_bf16 v[80:83], v[168:171], v[242:245], v[80:83]
	v_mfma_f32_16x16x32_bf16 v[84:87], v[156:159], v[238:241], v[84:87]
	v_mfma_f32_16x16x32_bf16 v[84:87], v[160:163], v[242:245], v[84:87]
	s_setprio 0
	s_setprio 1
	v_mfma_f32_16x16x32_bf16 v[124:127], v[172:175], v[192:195], v[124:127]
	v_mfma_f32_16x16x32_bf16 v[124:127], v[176:179], v[196:199], v[124:127]
	v_mfma_f32_16x16x32_bf16 v[120:123], v[184:187], v[192:195], v[120:123]
	v_mfma_f32_16x16x32_bf16 v[120:123], v[188:191], v[196:199], v[120:123]
	v_mfma_f32_16x16x32_bf16 v[104:107], v[184:187], v[200:203], v[104:107]
	v_mfma_f32_16x16x32_bf16 v[104:107], v[188:191], v[204:207], v[104:107]
	v_mfma_f32_16x16x32_bf16 v[108:111], v[172:175], v[200:203], v[108:111]
	v_mfma_f32_16x16x32_bf16 v[108:111], v[176:179], v[204:207], v[108:111]
	v_mfma_f32_16x16x32_bf16 v[92:95], v[172:175], v[230:233], v[92:95]
	v_mfma_f32_16x16x32_bf16 v[92:95], v[176:179], v[234:237], v[92:95]
	v_mfma_f32_16x16x32_bf16 v[88:91], v[184:187], v[230:233], v[88:91]
	v_mfma_f32_16x16x32_bf16 v[88:91], v[188:191], v[234:237], v[88:91]
	v_mfma_f32_16x16x32_bf16 v[72:75], v[184:187], v[238:241], v[72:75]
	v_mfma_f32_16x16x32_bf16 v[72:75], v[188:191], v[242:245], v[72:75]
	v_mfma_f32_16x16x32_bf16 v[76:79], v[172:175], v[238:241], v[76:79]
	v_mfma_f32_16x16x32_bf16 v[76:79], v[176:179], v[242:245], v[76:79]
	s_setprio 0
	s_barrier
; #define PG8_STAGE(bufoff, gbase, voff) do { _Pragma("unroll") for (int _i = 0; _i < 2; ++_i) \
;         __builtin_amdgcn_global_load_lds((const unsigned*)((const char*)(gbase) + (voff)[_i]), (PG8_LAS unsigned*)(lds + (bufoff) + ldsw + _i * 8192), 16, 0, 0); } while (0)
; #define PG8_LDA(dst, b, h) do { _Pragma("unroll") for (int m = 0; m < 4; ++m) _Pragma("unroll") for (int k = 0; k < 2; ++k) dst[m][k] = *(const PG8_LAS bf16x8*)(lds + PG8_SA(b, h) + aoff + m * 2048 + k * 1024); } while (0)
; #define PG8_MMA(ai, bj, At, Bt) do { __builtin_amdgcn_s_setprio(1); _Pragma("unroll") for (int m = 0; m < 4; ++m) _Pragma("unroll") for (int n = 0; n < 2; ++n) _Pragma("unroll") for (int k = 0; k < 2; ++k) \
;         acc[ai][bj][m][n] = __builtin_amdgcn_mfma_f32_16x16x32_bf16(Bt[n][k], At[m][k], acc[ai][bj][m][n], 0, 0, 0); __builtin_amdgcn_s_setprio(0); } while (0)
; #define PG8_WAIT_V(n) asm volatile("s_waitcnt vmcnt(" #n ")" ::: "memory")
; #define PG8_WAIT_L(n) asm volatile("s_waitcnt lgkmcnt(" #n ")" ::: "memory")
; #define PG8_BAR __builtin_amdgcn_s_barrier()
; #define PG8_SCHED __builtin_amdgcn_sched_barrier(0)
; template <class Epi, class Sched, bool ALIGN_EPI = false, bool SP2 = false>
; __device__ __forceinline__ void gemm_phase(PG8_LAS unsigned char* lds, const Gemm g, const Sched& S, const Epi& E) {
;     ...
;             PG8_LDA(At, 1, 1); PG8_STAGE(PG8_SB(1, 0), b3, voffB); PG8_STAGE(PG8_SB(1, 1), b3 + hstep, voffB); PG8_STAGE(PG8_SA(1, 0), a3, voffA);
;             PG8_WAIT_V(8); PG8_WAIT_L(0); PG8_BAR; PG8_MMA(1, 0, At, B0); PG8_MMA(1, 1, At, B1); PG8_BAR; PG8_SCHED;
	s_mov_b32 m0, s85
	v_lshl_add_u64 v[180:181], v[180:181], 0, s[24:25]
	ds_read_b128 v[192:195], v149 offset:49152
	ds_read_b128 v[196:199], v149 offset:50176
	ds_read_b128 v[200:203], v149 offset:51200
	ds_read_b128 v[204:207], v149 offset:52224
	ds_read_b128 v[230:233], v149 offset:53248
	ds_read_b128 v[234:237], v149 offset:54272
	ds_read_b128 v[238:241], v149 offset:55296
	ds_read_b128 v[242:245], v149 offset:56320
	global_load_lds_dwordx4 v[180:181], off
	v_lshl_add_u64 v[180:181], v[208:209], 0, s[24:25]
	s_mov_b32 m0, s86
	s_nop 0
	global_load_lds_dwordx4 v[180:181], off
	v_lshl_add_u64 v[180:181], v[216:217], 0, s[24:25]
	s_mov_b32 m0, s87
	s_nop 0
	global_load_lds_dwordx4 v[180:181], off
	v_lshl_add_u64 v[180:181], v[224:225], 0, s[24:25]
	s_mov_b32 m0, s88
	s_nop 0
	global_load_lds_dwordx4 v[180:181], off
	v_lshl_add_u64 v[180:181], v[226:227], 0, s[24:25]
	s_mov_b32 m0, s75
	s_nop 0
	global_load_lds_dwordx4 v[180:181], off
	v_lshl_add_u64 v[180:181], v[228:229], 0, s[24:25]
	s_mov_b32 m0, s76
	s_nop 0
	global_load_lds_dwordx4 v[180:181], off
	s_waitcnt vmcnt(8)
	s_waitcnt lgkmcnt(0)
	s_barrier
	s_setprio 1
	s_waitcnt lgkmcnt(0)
	v_mfma_f32_16x16x32_bf16 v[68:71], v[156:159], v[192:195], v[68:71]
	v_mfma_f32_16x16x32_bf16 v[68:71], v[160:163], v[196:199], v[68:71]
	v_mfma_f32_16x16x32_bf16 v[64:67], v[164:167], v[192:195], v[64:67]
	v_mfma_f32_16x16x32_bf16 v[64:67], v[168:171], v[196:199], v[64:67]
	v_mfma_f32_16x16x32_bf16 v[48:51], v[164:167], v[200:203], v[48:51]
	v_mfma_f32_16x16x32_bf16 v[48:51], v[168:171], v[204:207], v[48:51]
	v_mfma_f32_16x16x32_bf16 v[52:55], v[156:159], v[200:203], v[52:55]
	v_mfma_f32_16x16x32_bf16 v[52:55], v[160:163], v[204:207], v[52:55]
	v_mfma_f32_16x16x32_bf16 v[36:39], v[156:159], v[230:233], v[36:39]
	v_mfma_f32_16x16x32_bf16 v[36:39], v[160:163], v[234:237], v[36:39]
	v_mfma_f32_16x16x32_bf16 v[32:35], v[164:167], v[230:233], v[32:35]
	v_mfma_f32_16x16x32_bf16 v[32:35], v[168:171], v[234:237], v[32:35]
	v_mfma_f32_16x16x32_bf16 v[16:19], v[164:167], v[238:241], v[16:19]
	v_mfma_f32_16x16x32_bf16 v[16:19], v[168:171], v[242:245], v[16:19]
	v_mfma_f32_16x16x32_bf16 v[20:23], v[156:159], v[238:241], v[20:23]
	v_mfma_f32_16x16x32_bf16 v[20:23], v[160:163], v[242:245], v[20:23]
	s_setprio 0
	s_setprio 1
	v_mfma_f32_16x16x32_bf16 v[60:63], v[172:175], v[192:195], v[60:63]
	v_mfma_f32_16x16x32_bf16 v[60:63], v[176:179], v[196:199], v[60:63]
	v_mfma_f32_16x16x32_bf16 v[56:59], v[184:187], v[192:195], v[56:59]
	v_mfma_f32_16x16x32_bf16 v[56:59], v[188:191], v[196:199], v[56:59]
	v_mfma_f32_16x16x32_bf16 v[40:43], v[184:187], v[200:203], v[40:43]
	v_mfma_f32_16x16x32_bf16 v[40:43], v[188:191], v[204:207], v[40:43]
	v_mfma_f32_16x16x32_bf16 v[44:47], v[172:175], v[200:203], v[44:47]
	v_mfma_f32_16x16x32_bf16 v[44:47], v[176:179], v[204:207], v[44:47]
	v_mfma_f32_16x16x32_bf16 v[28:31], v[172:175], v[230:233], v[28:31]
	v_mfma_f32_16x16x32_bf16 v[28:31], v[176:179], v[234:237], v[28:31]
	v_mfma_f32_16x16x32_bf16 v[24:27], v[184:187], v[230:233], v[24:27]
	v_mfma_f32_16x16x32_bf16 v[24:27], v[188:191], v[234:237], v[24:27]
	v_mfma_f32_16x16x32_bf16 v[8:11], v[184:187], v[238:241], v[8:11]
	v_mfma_f32_16x16x32_bf16 v[8:11], v[188:191], v[242:245], v[8:11]
	v_mfma_f32_16x16x32_bf16 v[12:15], v[172:175], v[238:241], v[12:15]
	v_mfma_f32_16x16x32_bf16 v[12:15], v[176:179], v[242:245], v[12:15]
	s_setprio 0
	s_barrier
	s_add_i32 s40, s93, 2
	s_add_u32 s22, s22, 0x100
	s_addc_u32 s23, s23, 0
	s_add_u32 s89, s89, 0x100
	s_addc_u32 s92, s92, 0
	s_cmp_ge_u32 s93, s9
	v_add_u32_e32 v154, 0x100, v154
	s_cbranch_scc0 .LBB0_248

; #define PG8_STAGE(bufoff, gbase, voff) do { _Pragma("unroll") for (int _i = 0; _i < 2; ++_i) \
;         __builtin_amdgcn_global_load_lds((const unsigned*)((const char*)(gbase) + (voff)[_i]), (PG8_LAS unsigned*)(lds + (bufoff) + ldsw + _i * 8192), 16, 0, 0); } while (0)
; #define PG8_LDA(dst, b, h) do { _Pragma("unroll") for (int m = 0; m < 4; ++m) _Pragma("unroll") for (int k = 0; k < 2; ++k) dst[m][k] = *(const PG8_LAS bf16x8*)(lds + PG8_SA(b, h) + aoff + m * 2048 + k * 1024); } while (0)
; #define PG8_LDB(dst, b, h) do { _Pragma("unroll") for (int n = 0; n < 2; ++n) _Pragma("unroll") for (int k = 0; k < 2; ++k) dst[n][k] = *(const PG8_LAS bf16x8*)(lds + PG8_SB(b, h) + boff + n * 2048 + k * 1024); } while (0)
; #define PG8_MMA(ai, bj, At, Bt) do { __builtin_amdgcn_s_setprio(1); _Pragma("unroll") for (int m = 0; m < 4; ++m) _Pragma("unroll") for (int n = 0; n < 2; ++n) _Pragma("unroll") for (int k = 0; k < 2; ++k) \
;         acc[ai][bj][m][n] = __builtin_amdgcn_mfma_f32_16x16x32_bf16(Bt[n][k], At[m][k], acc[ai][bj][m][n], 0, 0, 0); __builtin_amdgcn_s_setprio(0); } while (0)
; #define PG8_WAIT_V(n) asm volatile("s_waitcnt vmcnt(" #n ")" ::: "memory")
; #define PG8_WAIT_L(n) asm volatile("s_waitcnt lgkmcnt(" #n ")" ::: "memory")
; #define PG8_BAR __builtin_amdgcn_s_barrier()
; #define PG8_SCHED __builtin_amdgcn_sched_barrier(0)
; template <class Epi, class Sched, bool ALIGN_EPI = false, bool SP2 = false>
; __device__ __forceinline__ void gemm_phase(PG8_LAS unsigned char* lds, const Gemm g, const Sched& S, const Epi& E) {
;     ...
;             const bool last = (t == nt - 2);
;             const char* a1 = cA + (size_t)(t + 1) * kstep;
;             const char* a2 = last ? nA : cA + (size_t)(t + 2) * kstep; const char* b2 = last ? nB : cB + (size_t)(t + 2) * kstep;
;             const char* a3 = a2 + kstep; const char* b3 = b2 + kstep;
;             if (last && has_next) S.a_ready(nxt);
;             if constexpr (SP2) {
;             PG8_LDB(B0, 0, 0); PG8_LDB(B1, 0, 1); PG8_SCHED; PG8_LDA(At, 0, 0); PG8_STAGE(PG8_SA(1, 1), a1 + hstep, voffA);
;             PG8_WAIT_V(8); PG8_WAIT_L(0); PG8_BAR; PG8_MMA(0, 0, At, B0); PG8_MMA(0, 1, At, B1); PG8_BAR; PG8_SCHED;
;             PG8_LDA(At, 0, 1); PG8_STAGE(PG8_SB(0, 0), b2, voffB); PG8_STAGE(PG8_SB(0, 1), b2 + hstep, voffB); PG8_STAGE(PG8_SA(0, 0), a2, voffA);
.LBB0_294:
	s_add_i32 s81, s40, 2
	s_add_u32 s82, s38, 0x80
	s_addc_u32 s41, s39, 0
	s_cmp_eq_u32 s33, s40
	s_cselect_b32 s41, s7, s41
	s_cselect_b32 s40, s6, s82
	v_add_u32_e32 v0, s19, v151
	s_cselect_b32 s83, s23, s80
	s_cselect_b32 s82, s22, s79
	s_add_i32 s84, 0, 0x14000
	ds_read_b128 v[154:157], v0
	ds_read_b128 v[158:161], v0 offset:1024
	ds_read_b128 v[162:165], v0 offset:2048
	ds_read_b128 v[166:169], v0 offset:3072
	v_add_u32_e32 v0, s84, v151
	ds_read_b128 v[170:173], v0
	ds_read_b128 v[174:177], v0 offset:1024
	ds_read_b128 v[178:181], v0 offset:2048
	ds_read_b128 v[184:187], v0 offset:3072
	v_lshl_add_u64 v[2:3], s[38:39], 0, v[144:145]
	s_add_i32 m0, s46, 0xc000
	ds_read_b128 v[188:191], v152
	ds_read_b128 v[192:195], v152 offset:1024
	ds_read_b128 v[196:199], v152 offset:2048
	ds_read_b128 v[200:203], v152 offset:3072
	ds_read_b128 v[204:207], v152 offset:4096
	ds_read_b128 v[230:233], v152 offset:5120
	ds_read_b128 v[234:237], v152 offset:6144
	ds_read_b128 v[238:241], v152 offset:7168
	global_load_lds_dwordx4 v[2:3], off
	v_lshl_add_u64 v[2:3], s[38:39], 0, v[146:147]
	s_add_i32 m0, s46, 0xe000
	s_nop 0
	global_load_lds_dwordx4 v[2:3], off
	s_waitcnt vmcnt(8)
	s_waitcnt lgkmcnt(0)
	s_barrier
	s_setprio 1
	s_waitcnt lgkmcnt(0)
	v_mfma_f32_16x16x32_bf16 v[8:11], v[154:157], v[188:191], v[8:11]
	v_mfma_f32_16x16x32_bf16 v[8:11], v[158:161], v[192:195], v[8:11]
	v_mfma_f32_16x16x32_bf16 v[12:15], v[162:165], v[188:191], v[12:15]
	v_mfma_f32_16x16x32_bf16 v[12:15], v[166:169], v[192:195], v[12:15]
	v_mfma_f32_16x16x32_bf16 v[52:55], v[162:165], v[196:199], v[52:55]
	v_mfma_f32_16x16x32_bf16 v[52:55], v[166:169], v[200:203], v[52:55]
	v_mfma_f32_16x16x32_bf16 v[48:51], v[154:157], v[196:199], v[48:51]
	v_mfma_f32_16x16x32_bf16 v[48:51], v[158:161], v[200:203], v[48:51]
	v_mfma_f32_16x16x32_bf16 v[96:99], v[154:157], v[204:207], v[96:99]
	v_mfma_f32_16x16x32_bf16 v[96:99], v[158:161], v[230:233], v[96:99]
	v_mfma_f32_16x16x32_bf16 v[100:103], v[162:165], v[204:207], v[100:103]
	v_mfma_f32_16x16x32_bf16 v[100:103], v[166:169], v[230:233], v[100:103]
	v_mfma_f32_16x16x32_bf16 v[124:127], v[162:165], v[234:237], v[124:127]
	v_mfma_f32_16x16x32_bf16 v[124:127], v[166:169], v[238:241], v[124:127]
	v_mfma_f32_16x16x32_bf16 v[120:123], v[154:157], v[234:237], v[120:123]
	v_mfma_f32_16x16x32_bf16 v[120:123], v[158:161], v[238:241], v[120:123]
	s_setprio 0
	s_setprio 1
	v_mfma_f32_16x16x32_bf16 v[24:27], v[170:173], v[188:191], v[24:27]
	v_mfma_f32_16x16x32_bf16 v[24:27], v[174:177], v[192:195], v[24:27]
	v_mfma_f32_16x16x32_bf16 v[28:31], v[178:181], v[188:191], v[28:31]
	v_mfma_f32_16x16x32_bf16 v[28:31], v[184:187], v[192:195], v[28:31]
	v_mfma_f32_16x16x32_bf16 v[76:79], v[178:181], v[196:199], v[76:79]
	v_mfma_f32_16x16x32_bf16 v[76:79], v[184:187], v[200:203], v[76:79]
	v_mfma_f32_16x16x32_bf16 v[72:75], v[170:173], v[196:199], v[72:75]
	v_mfma_f32_16x16x32_bf16 v[72:75], v[174:177], v[200:203], v[72:75]
	v_mfma_f32_16x16x32_bf16 v[112:115], v[170:173], v[204:207], v[112:115]
	v_mfma_f32_16x16x32_bf16 v[112:115], v[174:177], v[230:233], v[112:115]
	v_mfma_f32_16x16x32_bf16 v[116:119], v[178:181], v[204:207], v[116:119]
	v_mfma_f32_16x16x32_bf16 v[116:119], v[184:187], v[230:233], v[116:119]
	v_mfma_f32_16x16x32_bf16 v[132:135], v[178:181], v[234:237], v[132:135]
	v_mfma_f32_16x16x32_bf16 v[132:135], v[184:187], v[238:241], v[132:135]
	v_mfma_f32_16x16x32_bf16 v[128:131], v[170:173], v[234:237], v[128:131]
	v_mfma_f32_16x16x32_bf16 v[128:131], v[174:177], v[238:241], v[128:131]
	s_setprio 0
	s_barrier
	s_add_i32 s85, s19, s37
	v_lshl_add_u64 v[2:3], s[82:83], 0, v[140:141]
	s_mov_b32 m0, s85
	ds_read_b128 v[188:191], v152 offset:16384
	ds_read_b128 v[192:195], v152 offset:17408
	ds_read_b128 v[196:199], v152 offset:18432
	ds_read_b128 v[200:203], v152 offset:19456
	ds_read_b128 v[204:207], v152 offset:20480
	ds_read_b128 v[230:233], v152 offset:21504
	ds_read_b128 v[234:237], v152 offset:22528
	ds_read_b128 v[238:241], v152 offset:23552
	global_load_lds_dwordx4 v[2:3], off
	s_add_i32 m0, s85, 0x2000
	v_lshl_add_u64 v[208:209], s[82:83], 0, v[136:137]
	s_add_u32 s82, s82, s48
	s_addc_u32 s83, s83, s49
	s_add_i32 s84, s84, s37
	global_load_lds_dwordx4 v[208:209], off
	v_lshl_add_u64 v[216:217], s[82:83], 0, v[140:141]
	s_mov_b32 m0, s84
	v_lshl_add_u64 v[224:225], s[82:83], 0, v[136:137]
	global_load_lds_dwordx4 v[216:217], off
	s_add_i32 m0, s84, 0x2000
	v_lshl_add_u64 v[226:227], s[40:41], 0, v[142:143]
	global_load_lds_dwordx4 v[224:225], off
	s_mov_b32 m0, s46
	v_lshl_add_u64 v[228:229], s[40:41], 0, v[138:139]
	global_load_lds_dwordx4 v[226:227], off
	s_mov_b32 m0, s47
	s_nop 0
	global_load_lds_dwordx4 v[228:229], off
	s_waitcnt vmcnt(8)
	s_waitcnt lgkmcnt(0)
	s_barrier
; #define PG8_STAGE(bufoff, gbase, voff) do { _Pragma("unroll") for (int _i = 0; _i < 2; ++_i) \
;         __builtin_amdgcn_global_load_lds((const unsigned*)((const char*)(gbase) + (voff)[_i]), (PG8_LAS unsigned*)(lds + (bufoff) + ldsw + _i * 8192), 16, 0, 0); } while (0)
; #define PG8_LDA(dst, b, h) do { _Pragma("unroll") for (int m = 0; m < 4; ++m) _Pragma("unroll") for (int k = 0; k < 2; ++k) dst[m][k] = *(const PG8_LAS bf16x8*)(lds + PG8_SA(b, h) + aoff + m * 2048 + k * 1024); } while (0)
; #define PG8_LDB(dst, b, h) do { _Pragma("unroll") for (int n = 0; n < 2; ++n) _Pragma("unroll") for (int k = 0; k < 2; ++k) dst[n][k] = *(const PG8_LAS bf16x8*)(lds + PG8_SB(b, h) + boff + n * 2048 + k * 1024); } while (0)
; #define PG8_MMA(ai, bj, At, Bt) do { __builtin_amdgcn_s_setprio(1); _Pragma("unroll") for (int m = 0; m < 4; ++m) _Pragma("unroll") for (int n = 0; n < 2; ++n) _Pragma("unroll") for (int k = 0; k < 2; ++k) \
;         acc[ai][bj][m][n] = __builtin_amdgcn_mfma_f32_16x16x32_bf16(Bt[n][k], At[m][k], acc[ai][bj][m][n], 0, 0, 0); __builtin_amdgcn_s_setprio(0); } while (0)
; #define PG8_WAIT_V(n) asm volatile("s_waitcnt vmcnt(" #n ")" ::: "memory")
; #define PG8_WAIT_L(n) asm volatile("s_waitcnt lgkmcnt(" #n ")" ::: "memory")
; #define PG8_BAR __builtin_amdgcn_s_barrier()
; #define PG8_SCHED __builtin_amdgcn_sched_barrier(0)
; template <class Epi, class Sched, bool ALIGN_EPI = false, bool SP2 = false>
; __device__ __forceinline__ void gemm_phase(PG8_LAS unsigned char* lds, const Gemm g, const Sched& S, const Epi& E) {
;     ...
;             PG8_WAIT_V(8); PG8_WAIT_L(0); PG8_BAR; PG8_MMA(1, 0, At, B0); PG8_MMA(1, 1, At, B1); PG8_BAR; PG8_SCHED;
;             PG8_LDB(B0, 1, 0); PG8_LDB(B1, 1, 1); PG8_SCHED; PG8_LDA(At, 1, 0); PG8_STAGE(PG8_SA(0, 1), a2 + hstep, voffA);
;             PG8_WAIT_V(8); PG8_WAIT_L(0); PG8_BAR; PG8_MMA(0, 0, At, B0); PG8_MMA(0, 1, At, B1); PG8_BAR; PG8_SCHED;
	s_setprio 1
	s_waitcnt lgkmcnt(0)
	v_mfma_f32_16x16x32_bf16 v[16:19], v[154:157], v[188:191], v[16:19]
	v_mfma_f32_16x16x32_bf16 v[16:19], v[158:161], v[192:195], v[16:19]
	v_mfma_f32_16x16x32_bf16 v[20:23], v[162:165], v[188:191], v[20:23]
	v_mfma_f32_16x16x32_bf16 v[20:23], v[166:169], v[192:195], v[20:23]
	v_mfma_f32_16x16x32_bf16 v[60:63], v[162:165], v[196:199], v[60:63]
	v_mfma_f32_16x16x32_bf16 v[60:63], v[166:169], v[200:203], v[60:63]
	v_mfma_f32_16x16x32_bf16 v[56:59], v[154:157], v[196:199], v[56:59]
	v_mfma_f32_16x16x32_bf16 v[56:59], v[158:161], v[200:203], v[56:59]
	v_mfma_f32_16x16x32_bf16 v[104:107], v[154:157], v[204:207], v[104:107]
	v_mfma_f32_16x16x32_bf16 v[104:107], v[158:161], v[230:233], v[104:107]
	v_mfma_f32_16x16x32_bf16 v[108:111], v[162:165], v[204:207], v[108:111]
	v_mfma_f32_16x16x32_bf16 v[108:111], v[166:169], v[230:233], v[108:111]
	v_mfma_f32_16x16x32_bf16 v[64:67], v[162:165], v[234:237], v[64:67]
	v_mfma_f32_16x16x32_bf16 v[64:67], v[166:169], v[238:241], v[64:67]
	v_mfma_f32_16x16x32_bf16 v[68:71], v[154:157], v[234:237], v[68:71]
	v_mfma_f32_16x16x32_bf16 v[68:71], v[158:161], v[238:241], v[68:71]
	s_setprio 0
	s_setprio 1
	v_mfma_f32_16x16x32_bf16 v[40:43], v[170:173], v[188:191], v[40:43]
	v_mfma_f32_16x16x32_bf16 v[40:43], v[174:177], v[192:195], v[40:43]
	v_mfma_f32_16x16x32_bf16 v[44:47], v[178:181], v[188:191], v[44:47]
	v_mfma_f32_16x16x32_bf16 v[44:47], v[184:187], v[192:195], v[44:47]
	v_mfma_f32_16x16x32_bf16 v[92:95], v[178:181], v[196:199], v[92:95]
	v_mfma_f32_16x16x32_bf16 v[92:95], v[184:187], v[200:203], v[92:95]
	v_mfma_f32_16x16x32_bf16 v[88:91], v[170:173], v[196:199], v[88:91]
	v_mfma_f32_16x16x32_bf16 v[88:91], v[174:177], v[200:203], v[88:91]
	v_mfma_f32_16x16x32_bf16 v[84:87], v[170:173], v[204:207], v[84:87]
	v_mfma_f32_16x16x32_bf16 v[84:87], v[174:177], v[230:233], v[84:87]
	v_mfma_f32_16x16x32_bf16 v[80:83], v[178:181], v[204:207], v[80:83]
	v_mfma_f32_16x16x32_bf16 v[80:83], v[184:187], v[230:233], v[80:83]
	v_mfma_f32_16x16x32_bf16 v[32:35], v[178:181], v[234:237], v[32:35]
	v_mfma_f32_16x16x32_bf16 v[32:35], v[184:187], v[238:241], v[32:35]
	v_mfma_f32_16x16x32_bf16 v[36:39], v[170:173], v[234:237], v[36:39]
	v_mfma_f32_16x16x32_bf16 v[36:39], v[174:177], v[238:241], v[36:39]
	s_setprio 0
	s_barrier
	v_add_u32_e32 v0, s91, v151
	s_add_i32 s82, 0, 0x1c000
	ds_read_b128 v[154:157], v0
	ds_read_b128 v[158:161], v0 offset:1024
	ds_read_b128 v[162:165], v0 offset:2048
	ds_read_b128 v[166:169], v0 offset:3072
	v_add_u32_e32 v0, s82, v151
	ds_read_b128 v[170:173], v0
	ds_read_b128 v[174:177], v0 offset:1024
	ds_read_b128 v[178:181], v0 offset:2048
	ds_read_b128 v[184:187], v0 offset:3072
	s_add_u32 s40, s40, s48
	s_addc_u32 s41, s41, s49
	s_mov_b32 m0, s52
	v_lshl_add_u64 v[242:243], s[40:41], 0, v[142:143]
	ds_read_b128 v[188:191], v152 offset:32768
	ds_read_b128 v[192:195], v152 offset:33792
	ds_read_b128 v[196:199], v152 offset:34816
	ds_read_b128 v[200:203], v152 offset:35840
	ds_read_b128 v[204:207], v152 offset:36864
	ds_read_b128 v[230:233], v152 offset:37888
	ds_read_b128 v[234:237], v152 offset:38912
	ds_read_b128 v[238:241], v152 offset:39936
	global_load_lds_dwordx4 v[242:243], off
	v_lshl_add_u64 v[242:243], s[40:41], 0, v[138:139]
	s_mov_b32 m0, s53
	s_nop 0
	global_load_lds_dwordx4 v[242:243], off
	s_waitcnt vmcnt(8)
	s_waitcnt lgkmcnt(0)
	s_barrier
	s_setprio 1
	s_waitcnt lgkmcnt(0)
	v_mfma_f32_16x16x32_bf16 v[8:11], v[154:157], v[188:191], v[8:11]
	v_mfma_f32_16x16x32_bf16 v[8:11], v[158:161], v[192:195], v[8:11]
	v_mfma_f32_16x16x32_bf16 v[12:15], v[162:165], v[188:191], v[12:15]
	v_mfma_f32_16x16x32_bf16 v[12:15], v[166:169], v[192:195], v[12:15]
	v_mfma_f32_16x16x32_bf16 v[52:55], v[162:165], v[196:199], v[52:55]
	v_mfma_f32_16x16x32_bf16 v[52:55], v[166:169], v[200:203], v[52:55]
	v_mfma_f32_16x16x32_bf16 v[48:51], v[154:157], v[196:199], v[48:51]
	v_mfma_f32_16x16x32_bf16 v[48:51], v[158:161], v[200:203], v[48:51]
	v_mfma_f32_16x16x32_bf16 v[96:99], v[154:157], v[204:207], v[96:99]
	v_mfma_f32_16x16x32_bf16 v[96:99], v[158:161], v[230:233], v[96:99]
	v_mfma_f32_16x16x32_bf16 v[100:103], v[162:165], v[204:207], v[100:103]
	v_mfma_f32_16x16x32_bf16 v[100:103], v[166:169], v[230:233], v[100:103]
	v_mfma_f32_16x16x32_bf16 v[124:127], v[162:165], v[234:237], v[124:127]
	v_mfma_f32_16x16x32_bf16 v[124:127], v[166:169], v[238:241], v[124:127]
	v_mfma_f32_16x16x32_bf16 v[120:123], v[154:157], v[234:237], v[120:123]
	v_mfma_f32_16x16x32_bf16 v[120:123], v[158:161], v[238:241], v[120:123]
	s_setprio 0
	s_setprio 1
	v_mfma_f32_16x16x32_bf16 v[24:27], v[170:173], v[188:191], v[24:27]
	v_mfma_f32_16x16x32_bf16 v[24:27], v[174:177], v[192:195], v[24:27]
	v_mfma_f32_16x16x32_bf16 v[28:31], v[178:181], v[188:191], v[28:31]
	v_mfma_f32_16x16x32_bf16 v[28:31], v[184:187], v[192:195], v[28:31]
	v_mfma_f32_16x16x32_bf16 v[76:79], v[178:181], v[196:199], v[76:79]
	v_mfma_f32_16x16x32_bf16 v[76:79], v[184:187], v[200:203], v[76:79]
	v_mfma_f32_16x16x32_bf16 v[72:75], v[170:173], v[196:199], v[72:75]
	v_mfma_f32_16x16x32_bf16 v[72:75], v[174:177], v[200:203], v[72:75]
	v_mfma_f32_16x16x32_bf16 v[112:115], v[170:173], v[204:207], v[112:115]
	v_mfma_f32_16x16x32_bf16 v[112:115], v[174:177], v[230:233], v[112:115]
	v_mfma_f32_16x16x32_bf16 v[116:119], v[178:181], v[204:207], v[116:119]
	v_mfma_f32_16x16x32_bf16 v[116:119], v[184:187], v[230:233], v[116:119]
	v_mfma_f32_16x16x32_bf16 v[132:135], v[178:181], v[234:237], v[132:135]
	v_mfma_f32_16x16x32_bf16 v[132:135], v[184:187], v[238:241], v[132:135]
	v_mfma_f32_16x16x32_bf16 v[128:131], v[170:173], v[234:237], v[128:131]
	v_mfma_f32_16x16x32_bf16 v[128:131], v[174:177], v[238:241], v[128:131]
	s_setprio 0
	s_barrier
; #define PG8_STAGE(bufoff, gbase, voff) do { _Pragma("unroll") for (int _i = 0; _i < 2; ++_i) \
;         __builtin_amdgcn_global_load_lds((const unsigned*)((const char*)(gbase) + (voff)[_i]), (PG8_LAS unsigned*)(lds + (bufoff) + ldsw + _i * 8192), 16, 0, 0); } while (0)
; #define PG8_LDA(dst, b, h) do { _Pragma("unroll") for (int m = 0; m < 4; ++m) _Pragma("unroll") for (int k = 0; k < 2; ++k) dst[m][k] = *(const PG8_LAS bf16x8*)(lds + PG8_SA(b, h) + aoff + m * 2048 + k * 1024); } while (0)
; #define PG8_MMA(ai, bj, At, Bt) do { __builtin_amdgcn_s_setprio(1); _Pragma("unroll") for (int m = 0; m < 4; ++m) _Pragma("unroll") for (int n = 0; n < 2; ++n) _Pragma("unroll") for (int k = 0; k < 2; ++k) \
;         acc[ai][bj][m][n] = __builtin_amdgcn_mfma_f32_16x16x32_bf16(Bt[n][k], At[m][k], acc[ai][bj][m][n], 0, 0, 0); __builtin_amdgcn_s_setprio(0); } while (0)
; #define PG8_WAIT_V(n) asm volatile("s_waitcnt vmcnt(" #n ")" ::: "memory")
; #define PG8_WAIT_L(n) asm volatile("s_waitcnt lgkmcnt(" #n ")" ::: "memory")
; #define PG8_BAR __builtin_amdgcn_s_barrier()
; #define PG8_SCHED __builtin_amdgcn_sched_barrier(0)
; template <class Epi, class Sched, bool ALIGN_EPI = false, bool SP2 = false>
; __device__ __forceinline__ void gemm_phase(PG8_LAS unsigned char* lds, const Gemm g, const Sched& S, const Epi& E) {
;     ...
;             PG8_LDA(At, 1, 1); PG8_STAGE(PG8_SB(1, 0), b3, voffB); PG8_STAGE(PG8_SB(1, 1), b3 + hstep, voffB); PG8_STAGE(PG8_SA(1, 0), a3, voffA);
;             PG8_WAIT_V(8); PG8_WAIT_L(0); PG8_BAR; PG8_MMA(1, 0, At, B0); PG8_MMA(1, 1, At, B1); PG8_BAR; PG8_SCHED;
	s_add_i32 s40, s91, s37
	v_lshl_add_u64 v[2:3], v[2:3], 0, s[24:25]
	s_mov_b32 m0, s40
	ds_read_b128 v[188:191], v152 offset:49152
	ds_read_b128 v[192:195], v152 offset:50176
	ds_read_b128 v[196:199], v152 offset:51200
	ds_read_b128 v[200:203], v152 offset:52224
	ds_read_b128 v[204:207], v152 offset:53248
	ds_read_b128 v[230:233], v152 offset:54272
	ds_read_b128 v[234:237], v152 offset:55296
	ds_read_b128 v[238:241], v152 offset:56320
	global_load_lds_dwordx4 v[2:3], off
	v_lshl_add_u64 v[2:3], v[208:209], 0, s[24:25]
	s_add_i32 m0, s40, 0x2000
	s_add_i32 s40, s82, s37
	global_load_lds_dwordx4 v[2:3], off
	v_lshl_add_u64 v[2:3], v[216:217], 0, s[24:25]
	s_mov_b32 m0, s40
	s_nop 0
	global_load_lds_dwordx4 v[2:3], off
	v_lshl_add_u64 v[2:3], v[224:225], 0, s[24:25]
	s_add_i32 m0, s40, 0x2000
	s_nop 0
	global_load_lds_dwordx4 v[2:3], off
	v_lshl_add_u64 v[2:3], v[226:227], 0, s[24:25]
	s_mov_b32 m0, s73
	s_nop 0
	global_load_lds_dwordx4 v[2:3], off
	v_lshl_add_u64 v[2:3], v[228:229], 0, s[24:25]
	s_mov_b32 m0, s74
	s_nop 0
	global_load_lds_dwordx4 v[2:3], off
	s_waitcnt vmcnt(8)
	s_waitcnt lgkmcnt(0)
	s_barrier
	s_setprio 1
	s_waitcnt lgkmcnt(0)
	v_mfma_f32_16x16x32_bf16 v[16:19], v[154:157], v[188:191], v[16:19]
	v_mfma_f32_16x16x32_bf16 v[16:19], v[158:161], v[192:195], v[16:19]
	v_mfma_f32_16x16x32_bf16 v[20:23], v[162:165], v[188:191], v[20:23]
	v_mfma_f32_16x16x32_bf16 v[20:23], v[166:169], v[192:195], v[20:23]
	v_mfma_f32_16x16x32_bf16 v[60:63], v[162:165], v[196:199], v[60:63]
	v_mfma_f32_16x16x32_bf16 v[60:63], v[166:169], v[200:203], v[60:63]
	v_mfma_f32_16x16x32_bf16 v[56:59], v[154:157], v[196:199], v[56:59]
	v_mfma_f32_16x16x32_bf16 v[56:59], v[158:161], v[200:203], v[56:59]
	v_mfma_f32_16x16x32_bf16 v[104:107], v[154:157], v[204:207], v[104:107]
	v_mfma_f32_16x16x32_bf16 v[104:107], v[158:161], v[230:233], v[104:107]
	v_mfma_f32_16x16x32_bf16 v[108:111], v[162:165], v[204:207], v[108:111]
	v_mfma_f32_16x16x32_bf16 v[108:111], v[166:169], v[230:233], v[108:111]
	v_mfma_f32_16x16x32_bf16 v[64:67], v[162:165], v[234:237], v[64:67]
	v_mfma_f32_16x16x32_bf16 v[64:67], v[166:169], v[238:241], v[64:67]
	v_mfma_f32_16x16x32_bf16 v[68:71], v[154:157], v[234:237], v[68:71]
	v_mfma_f32_16x16x32_bf16 v[68:71], v[158:161], v[238:241], v[68:71]
	s_setprio 0
	s_setprio 1
	v_mfma_f32_16x16x32_bf16 v[40:43], v[170:173], v[188:191], v[40:43]
	v_mfma_f32_16x16x32_bf16 v[40:43], v[174:177], v[192:195], v[40:43]
	v_mfma_f32_16x16x32_bf16 v[44:47], v[178:181], v[188:191], v[44:47]
	v_mfma_f32_16x16x32_bf16 v[44:47], v[184:187], v[192:195], v[44:47]
	v_mfma_f32_16x16x32_bf16 v[92:95], v[178:181], v[196:199], v[92:95]
	v_mfma_f32_16x16x32_bf16 v[92:95], v[184:187], v[200:203], v[92:95]
	v_mfma_f32_16x16x32_bf16 v[88:91], v[170:173], v[196:199], v[88:91]
	v_mfma_f32_16x16x32_bf16 v[88:91], v[174:177], v[200:203], v[88:91]
	v_mfma_f32_16x16x32_bf16 v[84:87], v[170:173], v[204:207], v[84:87]
	v_mfma_f32_16x16x32_bf16 v[84:87], v[174:177], v[230:233], v[84:87]
	v_mfma_f32_16x16x32_bf16 v[80:83], v[178:181], v[204:207], v[80:83]
	v_mfma_f32_16x16x32_bf16 v[80:83], v[184:187], v[230:233], v[80:83]
	v_mfma_f32_16x16x32_bf16 v[32:35], v[178:181], v[234:237], v[32:35]
	v_mfma_f32_16x16x32_bf16 v[32:35], v[184:187], v[238:241], v[32:35]
	v_mfma_f32_16x16x32_bf16 v[36:39], v[170:173], v[234:237], v[36:39]
	v_mfma_f32_16x16x32_bf16 v[36:39], v[174:177], v[238:241], v[36:39]
	s_setprio 0
	s_barrier
	s_add_u32 s38, s38, 0x100
	s_addc_u32 s39, s39, 0
	s_add_u32 s79, s79, 0x100
	s_addc_u32 s80, s80, 0
	s_cmp_ge_u32 s81, s9
	s_mov_b32 s40, s81
	s_cbranch_scc0 .LBB0_294

; #define PG8_STAGE(bufoff, gbase, voff) do { _Pragma("unroll") for (int _i = 0; _i < 2; ++_i) \
;         __builtin_amdgcn_global_load_lds((const unsigned*)((const char*)(gbase) + (voff)[_i]), (PG8_LAS unsigned*)(lds + (bufoff) + ldsw + _i * 8192), 16, 0, 0); } while (0)
; #define PG8_LDA(dst, b, h) do { _Pragma("unroll") for (int m = 0; m < 4; ++m) _Pragma("unroll") for (int k = 0; k < 2; ++k) dst[m][k] = *(const PG8_LAS bf16x8*)(lds + PG8_SA(b, h) + aoff + m * 2048 + k * 1024); } while (0)
; #define PG8_LDB(dst, b, h) do { _Pragma("unroll") for (int n = 0; n < 2; ++n) _Pragma("unroll") for (int k = 0; k < 2; ++k) dst[n][k] = *(const PG8_LAS bf16x8*)(lds + PG8_SB(b, h) + boff + n * 2048 + k * 1024); } while (0)
; #define PG8_MMA(ai, bj, At, Bt) do { __builtin_amdgcn_s_setprio(1); _Pragma("unroll") for (int m = 0; m < 4; ++m) _Pragma("unroll") for (int n = 0; n < 2; ++n) _Pragma("unroll") for (int k = 0; k < 2; ++k) \
;         acc[ai][bj][m][n] = __builtin_amdgcn_mfma_f32_16x16x32_bf16(Bt[n][k], At[m][k], acc[ai][bj][m][n], 0, 0, 0); __builtin_amdgcn_s_setprio(0); } while (0)
; #define PG8_WAIT_V(n) asm volatile("s_waitcnt vmcnt(" #n ")" ::: "memory")
; #define PG8_WAIT_L(n) asm volatile("s_waitcnt lgkmcnt(" #n ")" ::: "memory")
; #define PG8_BAR __builtin_amdgcn_s_barrier()
; #define PG8_SCHED __builtin_amdgcn_sched_barrier(0)
; template <class Epi, class Sched, bool ALIGN_EPI = false, bool SP2 = false>
; __device__ __forceinline__ void gemm_phase(PG8_LAS unsigned char* lds, const Gemm g, const Sched& S, const Epi& E) {
;     ...
;             const bool last = (t == nt - 2);
;             const char* a1 = cA + (size_t)(t + 1) * kstep;
;             const char* a2 = last ? nA : cA + (size_t)(t + 2) * kstep; const char* b2 = last ? nB : cB + (size_t)(t + 2) * kstep;
;             const char* a3 = a2 + kstep; const char* b3 = b2 + kstep;
;             if (last && has_next) S.a_ready(nxt);
;             if constexpr (SP2) {
;             PG8_LDB(B0, 0, 0); PG8_LDB(B1, 0, 1); PG8_SCHED; PG8_LDA(At, 0, 0); PG8_STAGE(PG8_SA(1, 1), a1 + hstep, voffA);
;             PG8_WAIT_V(8); PG8_WAIT_L(0); PG8_BAR; PG8_MMA(0, 0, At, B0); PG8_MMA(0, 1, At, B1); PG8_BAR; PG8_SCHED;
;             PG8_LDA(At, 0, 1); PG8_STAGE(PG8_SB(0, 0), b2, voffB); PG8_STAGE(PG8_SB(0, 1), b2 + hstep, voffB); PG8_STAGE(PG8_SA(0, 0), a2, voffA);
.LBB0_365:
	s_add_i32 s88, s86, 2
	s_add_u32 s89, s0, 0x80
	s_addc_u32 s87, s1, 0
	s_cmp_eq_u32 s33, s86
	s_cselect_b32 s87, s3, s87
	s_cselect_b32 s86, s2, s89
	v_add_u32_e32 v0, s19, v230
	s_cselect_b32 vcc_hi, s85, s73
	s_cselect_b32 vcc_lo, s84, s72
	s_add_i32 s89, 0, 0x14000
	ds_read_b128 v[120:123], v0
	ds_read_b128 v[124:127], v0 offset:1024
	ds_read_b128 v[128:131], v0 offset:2048
	ds_read_b128 v[132:135], v0 offset:3072
	v_add_u32_e32 v0, s89, v230
	ds_read_b128 v[136:139], v0
	ds_read_b128 v[140:143], v0 offset:1024
	ds_read_b128 v[162:165], v0 offset:2048
	ds_read_b128 v[166:169], v0 offset:3072
	v_lshl_add_u64 v[144:145], s[0:1], 0, v[184:185]
	s_add_i32 m0, s93, 0xc000
	ds_read_b128 v[170:173], v238
	ds_read_b128 v[188:191], v238 offset:1024
	ds_read_b128 v[192:195], v238 offset:2048
	ds_read_b128 v[196:199], v238 offset:3072
	ds_read_b128 v[200:203], v238 offset:4096
	ds_read_b128 v[204:207], v238 offset:5120
	ds_read_b128 v[242:245], v238 offset:6144
	ds_read_b128 v[246:249], v238 offset:7168
	global_load_lds_dwordx4 v[144:145], off
	v_lshl_add_u64 v[144:145], s[0:1], 0, v[186:187]
	s_add_i32 m0, s93, 0xe000
	s_nop 0
	global_load_lds_dwordx4 v[144:145], off
	s_waitcnt vmcnt(8)
	s_waitcnt lgkmcnt(0)
	s_barrier
	s_setprio 1
	s_waitcnt lgkmcnt(0)
	v_mfma_f32_16x16x32_bf16 v[158:161], v[120:123], v[170:173], v[158:161]
	v_mfma_f32_16x16x32_bf16 v[158:161], v[124:127], v[188:191], v[158:161]
	v_mfma_f32_16x16x32_bf16 v[60:63], v[128:131], v[170:173], v[60:63]
	v_mfma_f32_16x16x32_bf16 v[60:63], v[132:135], v[188:191], v[60:63]
	v_mfma_f32_16x16x32_bf16 v[52:55], v[128:131], v[192:195], v[52:55]
	v_mfma_f32_16x16x32_bf16 v[52:55], v[132:135], v[196:199], v[52:55]
	v_mfma_f32_16x16x32_bf16 v[150:153], v[120:123], v[192:195], v[150:153]
	v_mfma_f32_16x16x32_bf16 v[150:153], v[124:127], v[196:199], v[150:153]
	v_mfma_f32_16x16x32_bf16 v[100:103], v[120:123], v[200:203], v[100:103]
	v_mfma_f32_16x16x32_bf16 v[100:103], v[124:127], v[204:207], v[100:103]
	v_mfma_f32_16x16x32_bf16 v[36:39], v[128:131], v[200:203], v[36:39]
	v_mfma_f32_16x16x32_bf16 v[36:39], v[132:135], v[204:207], v[36:39]
	v_mfma_f32_16x16x32_bf16 v[68:71], v[128:131], v[242:245], v[68:71]
	v_mfma_f32_16x16x32_bf16 v[68:71], v[132:135], v[246:249], v[68:71]
	v_mfma_f32_16x16x32_bf16 v[116:119], v[120:123], v[242:245], v[116:119]
	v_mfma_f32_16x16x32_bf16 v[116:119], v[124:127], v[246:249], v[116:119]
	s_setprio 0
	s_setprio 1
	v_mfma_f32_16x16x32_bf16 v[154:157], v[136:139], v[170:173], v[154:157]
	v_mfma_f32_16x16x32_bf16 v[154:157], v[140:143], v[188:191], v[154:157]
	v_mfma_f32_16x16x32_bf16 v[56:59], v[162:165], v[170:173], v[56:59]
	v_mfma_f32_16x16x32_bf16 v[56:59], v[166:169], v[188:191], v[56:59]
	v_mfma_f32_16x16x32_bf16 v[48:51], v[162:165], v[192:195], v[48:51]
	v_mfma_f32_16x16x32_bf16 v[48:51], v[166:169], v[196:199], v[48:51]
	v_mfma_f32_16x16x32_bf16 v[144:147], v[136:139], v[192:195], v[146:149]
	v_mfma_f32_16x16x32_bf16 v[144:147], v[140:143], v[196:199], v[144:147]
	v_mfma_f32_16x16x32_bf16 v[96:99], v[136:139], v[200:203], v[96:99]
	v_mfma_f32_16x16x32_bf16 v[96:99], v[140:143], v[204:207], v[96:99]
	v_mfma_f32_16x16x32_bf16 v[32:35], v[162:165], v[200:203], v[32:35]
	v_mfma_f32_16x16x32_bf16 v[32:35], v[166:169], v[204:207], v[32:35]
	v_mfma_f32_16x16x32_bf16 v[64:67], v[162:165], v[242:245], v[64:67]
	v_mfma_f32_16x16x32_bf16 v[64:67], v[166:169], v[246:249], v[64:67]
	v_mfma_f32_16x16x32_bf16 v[112:115], v[136:139], v[242:245], v[112:115]
	v_mfma_f32_16x16x32_bf16 v[112:115], v[140:143], v[246:249], v[112:115]
	s_setprio 0
	s_barrier
	s_add_i32 s38, s19, s92
	v_lshl_add_u64 v[174:175], vcc, 0, v[176:177]
	s_mov_b32 m0, s38
	ds_read_b128 v[170:173], v238 offset:16384
	ds_read_b128 v[188:191], v238 offset:17408
	ds_read_b128 v[192:195], v238 offset:18432
	ds_read_b128 v[196:199], v238 offset:19456
	ds_read_b128 v[200:203], v238 offset:20480
	ds_read_b128 v[204:207], v238 offset:21504
	ds_read_b128 v[242:245], v238 offset:22528
	ds_read_b128 v[246:249], v238 offset:23552
	global_load_lds_dwordx4 v[174:175], off
	s_add_i32 m0, s38, 0x2000
	v_lshl_add_u64 v[208:209], vcc, 0, v[180:181]
	s_add_u32 vcc_lo, vcc_lo, s48
	s_addc_u32 vcc_hi, vcc_hi, s49
	s_add_i32 s38, s89, s92
	global_load_lds_dwordx4 v[208:209], off
	v_lshl_add_u64 v[216:217], vcc, 0, v[176:177]
	s_mov_b32 m0, s38
	v_lshl_add_u64 v[224:225], vcc, 0, v[180:181]
	global_load_lds_dwordx4 v[216:217], off
	s_add_i32 m0, s38, 0x2000
	v_lshl_add_u64 v[226:227], s[86:87], 0, v[2:3]
	global_load_lds_dwordx4 v[224:225], off
	s_mov_b32 m0, s93
	v_lshl_add_u64 v[228:229], s[86:87], 0, v[178:179]
	global_load_lds_dwordx4 v[226:227], off
	s_mov_b32 m0, s94
	s_nop 0
	global_load_lds_dwordx4 v[228:229], off
	s_waitcnt vmcnt(8)
	s_waitcnt lgkmcnt(0)
	s_barrier
; #define PG8_STAGE(bufoff, gbase, voff) do { _Pragma("unroll") for (int _i = 0; _i < 2; ++_i) \
;         __builtin_amdgcn_global_load_lds((const unsigned*)((const char*)(gbase) + (voff)[_i]), (PG8_LAS unsigned*)(lds + (bufoff) + ldsw + _i * 8192), 16, 0, 0); } while (0)
; #define PG8_LDA(dst, b, h) do { _Pragma("unroll") for (int m = 0; m < 4; ++m) _Pragma("unroll") for (int k = 0; k < 2; ++k) dst[m][k] = *(const PG8_LAS bf16x8*)(lds + PG8_SA(b, h) + aoff + m * 2048 + k * 1024); } while (0)
; #define PG8_LDB(dst, b, h) do { _Pragma("unroll") for (int n = 0; n < 2; ++n) _Pragma("unroll") for (int k = 0; k < 2; ++k) dst[n][k] = *(const PG8_LAS bf16x8*)(lds + PG8_SB(b, h) + boff + n * 2048 + k * 1024); } while (0)
; #define PG8_MMA(ai, bj, At, Bt) do { __builtin_amdgcn_s_setprio(1); _Pragma("unroll") for (int m = 0; m < 4; ++m) _Pragma("unroll") for (int n = 0; n < 2; ++n) _Pragma("unroll") for (int k = 0; k < 2; ++k) \
;         acc[ai][bj][m][n] = __builtin_amdgcn_mfma_f32_16x16x32_bf16(Bt[n][k], At[m][k], acc[ai][bj][m][n], 0, 0, 0); __builtin_amdgcn_s_setprio(0); } while (0)
; #define PG8_BAR __builtin_amdgcn_s_barrier()
; template <class Epi, class Sched, bool ALIGN_EPI = false, bool SP2 = false>
; __device__ __forceinline__ void gemm_phase(PG8_LAS unsigned char* lds, const Gemm g, const Sched& S, const Epi& E) {
;     ...
;             if constexpr (SP2) {
;             PG8_LDB(B0, 0, 0); PG8_LDB(B1, 0, 1); PG8_SCHED; PG8_LDA(At, 0, 0); PG8_STAGE(PG8_SA(1, 1), a1 + hstep, voffA);
;             PG8_WAIT_V(8); PG8_WAIT_L(0); PG8_BAR; PG8_MMA(0, 0, At, B0); PG8_MMA(0, 1, At, B1); PG8_BAR; PG8_SCHED;
;             PG8_LDA(At, 0, 1); PG8_STAGE(PG8_SB(0, 0), b2, voffB); PG8_STAGE(PG8_SB(0, 1), b2 + hstep, voffB); PG8_STAGE(PG8_SA(0, 0), a2, voffA);
;             PG8_WAIT_V(8); PG8_WAIT_L(0); PG8_BAR; PG8_MMA(1, 0, At, B0); PG8_MMA(1, 1, At, B1); PG8_BAR; PG8_SCHED;
;             PG8_LDB(B0, 1, 0); PG8_LDB(B1, 1, 1); PG8_SCHED; PG8_LDA(At, 1, 0); PG8_STAGE(PG8_SA(0, 1), a2 + hstep, voffA);
;             PG8_WAIT_V(8); PG8_WAIT_L(0); PG8_BAR; PG8_MMA(0, 0, At, B0); PG8_MMA(0, 1, At, B1); PG8_BAR; PG8_SCHED;
;             PG8_LDA(At, 1, 1); PG8_STAGE(PG8_SB(1, 0), b3, voffB); PG8_STAGE(PG8_SB(1, 1), b3 + hstep, voffB); PG8_STAGE(PG8_SA(1, 0), a3, voffA);
;             PG8_WAIT_V(8); PG8_WAIT_L(0); PG8_BAR; PG8_MMA(1, 0, At, B0); PG8_MMA(1, 1, At, B1); PG8_BAR; PG8_SCHED;
	s_setprio 1
	s_waitcnt lgkmcnt(0)
	v_mfma_f32_16x16x32_bf16 v[92:95], v[120:123], v[170:173], v[92:95]
	v_mfma_f32_16x16x32_bf16 v[92:95], v[124:127], v[188:191], v[92:95]
	v_mfma_f32_16x16x32_bf16 v[28:31], v[128:131], v[170:173], v[28:31]
	v_mfma_f32_16x16x32_bf16 v[28:31], v[132:135], v[188:191], v[28:31]
	v_mfma_f32_16x16x32_bf16 v[20:23], v[128:131], v[192:195], v[20:23]
	v_mfma_f32_16x16x32_bf16 v[20:23], v[132:135], v[196:199], v[20:23]
	v_mfma_f32_16x16x32_bf16 v[84:87], v[120:123], v[192:195], v[84:87]
	v_mfma_f32_16x16x32_bf16 v[84:87], v[124:127], v[196:199], v[84:87]
	v_mfma_f32_16x16x32_bf16 v[76:79], v[120:123], v[200:203], v[76:79]
	v_mfma_f32_16x16x32_bf16 v[76:79], v[124:127], v[204:207], v[76:79]
	v_mfma_f32_16x16x32_bf16 v[12:15], v[128:131], v[200:203], v[12:15]
	v_mfma_f32_16x16x32_bf16 v[12:15], v[132:135], v[204:207], v[12:15]
	v_mfma_f32_16x16x32_bf16 v[44:47], v[128:131], v[242:245], v[44:47]
	v_mfma_f32_16x16x32_bf16 v[44:47], v[132:135], v[246:249], v[44:47]
	v_mfma_f32_16x16x32_bf16 v[108:111], v[120:123], v[242:245], v[108:111]
	v_mfma_f32_16x16x32_bf16 v[108:111], v[124:127], v[246:249], v[108:111]
	s_setprio 0
	s_setprio 1
	v_mfma_f32_16x16x32_bf16 v[88:91], v[136:139], v[170:173], v[88:91]
	v_mfma_f32_16x16x32_bf16 v[88:91], v[140:143], v[188:191], v[88:91]
	v_mfma_f32_16x16x32_bf16 v[24:27], v[162:165], v[170:173], v[24:27]
	v_mfma_f32_16x16x32_bf16 v[24:27], v[166:169], v[188:191], v[24:27]
	v_mfma_f32_16x16x32_bf16 v[16:19], v[162:165], v[192:195], v[16:19]
	v_mfma_f32_16x16x32_bf16 v[16:19], v[166:169], v[196:199], v[16:19]
	v_mfma_f32_16x16x32_bf16 v[80:83], v[136:139], v[192:195], v[80:83]
	v_mfma_f32_16x16x32_bf16 v[80:83], v[140:143], v[196:199], v[80:83]
	v_mfma_f32_16x16x32_bf16 v[72:75], v[136:139], v[200:203], v[72:75]
	v_mfma_f32_16x16x32_bf16 v[72:75], v[140:143], v[204:207], v[72:75]
	v_mfma_f32_16x16x32_bf16 v[8:11], v[162:165], v[200:203], v[8:11]
	v_mfma_f32_16x16x32_bf16 v[8:11], v[166:169], v[204:207], v[8:11]
	v_mfma_f32_16x16x32_bf16 v[40:43], v[162:165], v[242:245], v[40:43]
	v_mfma_f32_16x16x32_bf16 v[40:43], v[166:169], v[246:249], v[40:43]
	v_mfma_f32_16x16x32_bf16 v[104:107], v[136:139], v[242:245], v[104:107]
	v_mfma_f32_16x16x32_bf16 v[104:107], v[140:143], v[246:249], v[104:107]
	s_setprio 0
	s_barrier
	v_add_u32_e32 v0, s91, v230
	s_add_i32 s38, 0, 0x1c000
	ds_read_b128 v[120:123], v0
	ds_read_b128 v[124:127], v0 offset:1024
	ds_read_b128 v[128:131], v0 offset:2048
	ds_read_b128 v[132:135], v0 offset:3072
	v_add_u32_e32 v0, s38, v230
	ds_read_b128 v[136:139], v0
	ds_read_b128 v[140:143], v0 offset:1024
	ds_read_b128 v[162:165], v0 offset:2048
	ds_read_b128 v[166:169], v0 offset:3072
	s_add_u32 s86, s86, s48
	s_addc_u32 s87, s87, s49
	s_mov_b32 m0, s95
	v_lshl_add_u64 v[148:149], s[86:87], 0, v[2:3]
	ds_read_b128 v[170:173], v238 offset:32768
	ds_read_b128 v[188:191], v238 offset:33792
	ds_read_b128 v[192:195], v238 offset:34816
	ds_read_b128 v[196:199], v238 offset:35840
	ds_read_b128 v[200:203], v238 offset:36864
	ds_read_b128 v[204:207], v238 offset:37888
	ds_read_b128 v[242:245], v238 offset:38912
	ds_read_b128 v[246:249], v238 offset:39936
	global_load_lds_dwordx4 v[148:149], off
	v_lshl_add_u64 v[148:149], s[86:87], 0, v[178:179]
	s_mov_b32 m0, s96
	s_nop 0
	global_load_lds_dwordx4 v[148:149], off
	s_waitcnt vmcnt(8)
	s_waitcnt lgkmcnt(0)
	s_barrier
	s_setprio 1
	s_waitcnt lgkmcnt(0)
	v_mfma_f32_16x16x32_bf16 v[158:161], v[120:123], v[170:173], v[158:161]
	v_mfma_f32_16x16x32_bf16 v[158:161], v[124:127], v[188:191], v[158:161]
	v_mfma_f32_16x16x32_bf16 v[60:63], v[128:131], v[170:173], v[60:63]
	v_mfma_f32_16x16x32_bf16 v[60:63], v[132:135], v[188:191], v[60:63]
	v_mfma_f32_16x16x32_bf16 v[52:55], v[128:131], v[192:195], v[52:55]
	v_mfma_f32_16x16x32_bf16 v[52:55], v[132:135], v[196:199], v[52:55]
	v_mfma_f32_16x16x32_bf16 v[148:151], v[120:123], v[192:195], v[150:153]
	v_mfma_f32_16x16x32_bf16 v[150:153], v[124:127], v[196:199], v[148:151]
	v_mfma_f32_16x16x32_bf16 v[100:103], v[120:123], v[200:203], v[100:103]
	v_mfma_f32_16x16x32_bf16 v[100:103], v[124:127], v[204:207], v[100:103]
	v_mfma_f32_16x16x32_bf16 v[36:39], v[128:131], v[200:203], v[36:39]
	v_mfma_f32_16x16x32_bf16 v[36:39], v[132:135], v[204:207], v[36:39]
	v_mfma_f32_16x16x32_bf16 v[68:71], v[128:131], v[242:245], v[68:71]
	v_mfma_f32_16x16x32_bf16 v[68:71], v[132:135], v[246:249], v[68:71]
	v_mfma_f32_16x16x32_bf16 v[116:119], v[120:123], v[242:245], v[116:119]
	v_mfma_f32_16x16x32_bf16 v[116:119], v[124:127], v[246:249], v[116:119]
	s_setprio 0
	s_setprio 1
	v_mfma_f32_16x16x32_bf16 v[154:157], v[136:139], v[170:173], v[154:157]
	v_mfma_f32_16x16x32_bf16 v[154:157], v[140:143], v[188:191], v[154:157]
	v_mfma_f32_16x16x32_bf16 v[56:59], v[162:165], v[170:173], v[56:59]
	v_mfma_f32_16x16x32_bf16 v[56:59], v[166:169], v[188:191], v[56:59]
	v_mfma_f32_16x16x32_bf16 v[48:51], v[162:165], v[192:195], v[48:51]
	v_mfma_f32_16x16x32_bf16 v[48:51], v[166:169], v[196:199], v[48:51]
	v_mfma_f32_16x16x32_bf16 v[144:147], v[136:139], v[192:195], v[144:147]
	v_mfma_f32_16x16x32_bf16 v[146:149], v[140:143], v[196:199], v[144:147]
	v_mfma_f32_16x16x32_bf16 v[96:99], v[136:139], v[200:203], v[96:99]
	v_mfma_f32_16x16x32_bf16 v[96:99], v[140:143], v[204:207], v[96:99]
	v_mfma_f32_16x16x32_bf16 v[32:35], v[162:165], v[200:203], v[32:35]
	v_mfma_f32_16x16x32_bf16 v[32:35], v[166:169], v[204:207], v[32:35]
	v_mfma_f32_16x16x32_bf16 v[64:67], v[162:165], v[242:245], v[64:67]
	v_mfma_f32_16x16x32_bf16 v[64:67], v[166:169], v[246:249], v[64:67]
	v_mfma_f32_16x16x32_bf16 v[112:115], v[136:139], v[242:245], v[112:115]
	v_mfma_f32_16x16x32_bf16 v[112:115], v[140:143], v[246:249], v[112:115]
	s_setprio 0
	s_barrier
; #define PG8_STAGE(bufoff, gbase, voff) do { _Pragma("unroll") for (int _i = 0; _i < 2; ++_i) \
;         __builtin_amdgcn_global_load_lds((const unsigned*)((const char*)(gbase) + (voff)[_i]), (PG8_LAS unsigned*)(lds + (bufoff) + ldsw + _i * 8192), 16, 0, 0); } while (0)
; #define PG8_LDA(dst, b, h) do { _Pragma("unroll") for (int m = 0; m < 4; ++m) _Pragma("unroll") for (int k = 0; k < 2; ++k) dst[m][k] = *(const PG8_LAS bf16x8*)(lds + PG8_SA(b, h) + aoff + m * 2048 + k * 1024); } while (0)
; #define PG8_WAIT_V(n) asm volatile("s_waitcnt vmcnt(" #n ")" ::: "memory")
; #define PG8_BAR __builtin_amdgcn_s_barrier()
; template <class Epi, class Sched, bool ALIGN_EPI = false, bool SP2 = false>
; __device__ __forceinline__ void gemm_phase(PG8_LAS unsigned char* lds, const Gemm g, const Sched& S, const Epi& E) {
;     ...
;         for (int t = 0; t < nt; t += 2) {
;             if constexpr (Epi::KHOOK) { if ((t & 7) == 0 && t != 0) E.khook(acc, t >> 3, wr, fr, lds); }
;             const bool last = (t == nt - 2);
;             const char* a1 = cA + (size_t)(t + 1) * kstep;
;             const char* a2 = last ? nA : cA + (size_t)(t + 2) * kstep; const char* b2 = last ? nB : cB + (size_t)(t + 2) * kstep;
;             const char* a3 = a2 + kstep; const char* b3 = b2 + kstep;
;             if (last && has_next) S.a_ready(nxt);
;             if constexpr (SP2) {
;             PG8_LDB(B0, 0, 0); PG8_LDB(B1, 0, 1); PG8_SCHED; PG8_LDA(At, 0, 0); PG8_STAGE(PG8_SA(1, 1), a1 + hstep, voffA);
;             PG8_WAIT_V(8); PG8_WAIT_L(0); PG8_BAR; PG8_MMA(0, 0, At, B0); PG8_MMA(0, 1, At, B1); PG8_BAR; PG8_SCHED;
;             PG8_LDA(At, 0, 1); PG8_STAGE(PG8_SB(0, 0), b2, voffB); PG8_STAGE(PG8_SB(0, 1), b2 + hstep, voffB); PG8_STAGE(PG8_SA(0, 0), a2, voffA);
;             PG8_WAIT_V(8); PG8_WAIT_L(0); PG8_BAR; PG8_MMA(1, 0, At, B0); PG8_MMA(1, 1, At, B1); PG8_BAR; PG8_SCHED;
;             PG8_LDB(B0, 1, 0); PG8_LDB(B1, 1, 1); PG8_SCHED; PG8_LDA(At, 1, 0); PG8_STAGE(PG8_SA(0, 1), a2 + hstep, voffA);
;             PG8_WAIT_V(8); PG8_WAIT_L(0); PG8_BAR; PG8_MMA(0, 0, At, B0); PG8_MMA(0, 1, At, B1); PG8_BAR; PG8_SCHED;
;             PG8_LDA(At, 1, 1); PG8_STAGE(PG8_SB(1, 0), b3, voffB); PG8_STAGE(PG8_SB(1, 1), b3 + hstep, voffB); PG8_STAGE(PG8_SA(1, 0), a3, voffA);
;             PG8_WAIT_V(8); PG8_WAIT_L(0); PG8_BAR; PG8_MMA(1, 0, At, B0); PG8_MMA(1, 1, At, B1); PG8_BAR; PG8_SCHED;
	s_add_i32 s39, s91, s92
	v_lshl_add_u64 v[144:145], v[174:175], 0, s[24:25]
	s_mov_b32 m0, s39
	ds_read_b128 v[170:173], v238 offset:49152
	ds_read_b128 v[188:191], v238 offset:50176
	ds_read_b128 v[192:195], v238 offset:51200
	ds_read_b128 v[196:199], v238 offset:52224
	ds_read_b128 v[200:203], v238 offset:53248
	ds_read_b128 v[204:207], v238 offset:54272
	ds_read_b128 v[242:245], v238 offset:55296
	ds_read_b128 v[246:249], v238 offset:56320
	global_load_lds_dwordx4 v[144:145], off
	v_lshl_add_u64 v[144:145], v[208:209], 0, s[24:25]
	s_add_i32 m0, s39, 0x2000
	s_add_i32 s38, s38, s92
	global_load_lds_dwordx4 v[144:145], off
	v_lshl_add_u64 v[144:145], v[216:217], 0, s[24:25]
	s_mov_b32 m0, s38
	s_nop 0
	global_load_lds_dwordx4 v[144:145], off
	v_lshl_add_u64 v[144:145], v[224:225], 0, s[24:25]
	s_add_i32 m0, s38, 0x2000
	s_nop 0
	global_load_lds_dwordx4 v[144:145], off
	v_lshl_add_u64 v[144:145], v[226:227], 0, s[24:25]
	s_mov_b32 m0, s10
	s_nop 0
	global_load_lds_dwordx4 v[144:145], off
	v_lshl_add_u64 v[144:145], v[228:229], 0, s[24:25]
	s_mov_b32 m0, s11
	s_nop 0
	global_load_lds_dwordx4 v[144:145], off
	s_waitcnt vmcnt(8)
	s_waitcnt lgkmcnt(0)
	s_barrier
	s_setprio 1
	s_waitcnt lgkmcnt(0)
	v_mfma_f32_16x16x32_bf16 v[92:95], v[120:123], v[170:173], v[92:95]
	v_mfma_f32_16x16x32_bf16 v[92:95], v[124:127], v[188:191], v[92:95]
	v_mfma_f32_16x16x32_bf16 v[28:31], v[128:131], v[170:173], v[28:31]
	v_mfma_f32_16x16x32_bf16 v[28:31], v[132:135], v[188:191], v[28:31]
	v_mfma_f32_16x16x32_bf16 v[20:23], v[128:131], v[192:195], v[20:23]
	v_mfma_f32_16x16x32_bf16 v[20:23], v[132:135], v[196:199], v[20:23]
	v_mfma_f32_16x16x32_bf16 v[84:87], v[120:123], v[192:195], v[84:87]
	v_mfma_f32_16x16x32_bf16 v[84:87], v[124:127], v[196:199], v[84:87]
	v_mfma_f32_16x16x32_bf16 v[76:79], v[120:123], v[200:203], v[76:79]
	v_mfma_f32_16x16x32_bf16 v[76:79], v[124:127], v[204:207], v[76:79]
	v_mfma_f32_16x16x32_bf16 v[12:15], v[128:131], v[200:203], v[12:15]
	v_mfma_f32_16x16x32_bf16 v[12:15], v[132:135], v[204:207], v[12:15]
	v_mfma_f32_16x16x32_bf16 v[44:47], v[128:131], v[242:245], v[44:47]
	v_mfma_f32_16x16x32_bf16 v[44:47], v[132:135], v[246:249], v[44:47]
	v_mfma_f32_16x16x32_bf16 v[108:111], v[120:123], v[242:245], v[108:111]
	v_mfma_f32_16x16x32_bf16 v[108:111], v[124:127], v[246:249], v[108:111]
	s_setprio 0
	s_setprio 1
	v_mfma_f32_16x16x32_bf16 v[88:91], v[136:139], v[170:173], v[88:91]
	v_mfma_f32_16x16x32_bf16 v[88:91], v[140:143], v[188:191], v[88:91]
	v_mfma_f32_16x16x32_bf16 v[24:27], v[162:165], v[170:173], v[24:27]
	v_mfma_f32_16x16x32_bf16 v[24:27], v[166:169], v[188:191], v[24:27]
	v_mfma_f32_16x16x32_bf16 v[16:19], v[162:165], v[192:195], v[16:19]
	v_mfma_f32_16x16x32_bf16 v[16:19], v[166:169], v[196:199], v[16:19]
	v_mfma_f32_16x16x32_bf16 v[80:83], v[136:139], v[192:195], v[80:83]
	v_mfma_f32_16x16x32_bf16 v[80:83], v[140:143], v[196:199], v[80:83]
	v_mfma_f32_16x16x32_bf16 v[72:75], v[136:139], v[200:203], v[72:75]
	v_mfma_f32_16x16x32_bf16 v[72:75], v[140:143], v[204:207], v[72:75]
	v_mfma_f32_16x16x32_bf16 v[8:11], v[162:165], v[200:203], v[8:11]
	v_mfma_f32_16x16x32_bf16 v[8:11], v[166:169], v[204:207], v[8:11]
	v_mfma_f32_16x16x32_bf16 v[40:43], v[162:165], v[242:245], v[40:43]
	v_mfma_f32_16x16x32_bf16 v[40:43], v[166:169], v[246:249], v[40:43]
	v_mfma_f32_16x16x32_bf16 v[104:107], v[136:139], v[242:245], v[104:107]
	v_mfma_f32_16x16x32_bf16 v[104:107], v[140:143], v[246:249], v[104:107]
	s_setprio 0
	s_barrier
	s_add_u32 s0, s0, 0x100
	s_addc_u32 s1, s1, 0
	s_add_u32 s72, s72, 0x100
	s_addc_u32 s73, s73, 0
	s_cmp_ge_u32 s88, s9
	s_mov_b32 s86, s88
	s_cbranch_scc0 .LBB0_365

; #define PG8_STAGE(bufoff, gbase, voff) do { _Pragma("unroll") for (int _i = 0; _i < 2; ++_i) \
;         __builtin_amdgcn_global_load_lds((const unsigned*)((const char*)(gbase) + (voff)[_i]), (PG8_LAS unsigned*)(lds + (bufoff) + ldsw + _i * 8192), 16, 0, 0); } while (0)
; #define PG8_LDA(dst, b, h) do { _Pragma("unroll") for (int m = 0; m < 4; ++m) _Pragma("unroll") for (int k = 0; k < 2; ++k) dst[m][k] = *(const PG8_LAS bf16x8*)(lds + PG8_SA(b, h) + aoff + m * 2048 + k * 1024); } while (0)
; #define PG8_WAIT_V(n) asm volatile("s_waitcnt vmcnt(" #n ")" ::: "memory")
; #define PG8_BAR __builtin_amdgcn_s_barrier()
; template <class Epi, class Sched, bool ALIGN_EPI = false, bool SP2 = false>
; __device__ __forceinline__ void gemm_phase(PG8_LAS unsigned char* lds, const Gemm g, const Sched& S, const Epi& E) {
;     ...
;         for (int t = 0; t < nt; t += 2) {
;             if constexpr (Epi::KHOOK) { if ((t & 7) == 0 && t != 0) E.khook(acc, t >> 3, wr, fr, lds); }
;             const bool last = (t == nt - 2);
;             const char* a1 = cA + (size_t)(t + 1) * kstep;
;             const char* a2 = last ? nA : cA + (size_t)(t + 2) * kstep; const char* b2 = last ? nB : cB + (size_t)(t + 2) * kstep;
;             const char* a3 = a2 + kstep; const char* b3 = b2 + kstep;
;             if (last && has_next) S.a_ready(nxt);
;             if constexpr (SP2) {
;             PG8_LDB(B0, 0, 0); PG8_LDB(B1, 0, 1); PG8_SCHED; PG8_LDA(At, 0, 0); PG8_STAGE(PG8_SA(1, 1), a1 + hstep, voffA);
;             PG8_WAIT_V(8); PG8_WAIT_L(0); PG8_BAR; PG8_MMA(0, 0, At, B0); PG8_MMA(0, 1, At, B1); PG8_BAR; PG8_SCHED;
;             PG8_LDA(At, 0, 1); PG8_STAGE(PG8_SB(0, 0), b2, voffB); PG8_STAGE(PG8_SB(0, 1), b2 + hstep, voffB); PG8_STAGE(PG8_SA(0, 0), a2, voffA);
;             PG8_WAIT_V(8); PG8_WAIT_L(0); PG8_BAR; PG8_MMA(1, 0, At, B0); PG8_MMA(1, 1, At, B1); PG8_BAR; PG8_SCHED;
;             PG8_LDB(B0, 1, 0); PG8_LDB(B1, 1, 1); PG8_SCHED; PG8_LDA(At, 1, 0); PG8_STAGE(PG8_SA(0, 1), a2 + hstep, voffA);
;             PG8_WAIT_V(8); PG8_WAIT_L(0); PG8_BAR; PG8_MMA(0, 0, At, B0); PG8_MMA(0, 1, At, B1); PG8_BAR; PG8_SCHED;
;             PG8_LDA(At, 1, 1); PG8_STAGE(PG8_SB(1, 0), b3, voffB); PG8_STAGE(PG8_SB(1, 1), b3 + hstep, voffB); PG8_STAGE(PG8_SA(1, 0), a3, voffA);
;             PG8_WAIT_V(8); PG8_WAIT_L(0); PG8_BAR; PG8_MMA(1, 0, At, B0); PG8_MMA(1, 1, At, B1); PG8_BAR; PG8_SCHED;
.LBB0_468:
	s_add_i32 s78, s38, 2
	s_add_u32 s79, s0, 0x80
	s_addc_u32 s39, s1, 0
	s_cmp_eq_u32 s33, s38
	s_cselect_b32 s39, s7, s39
	s_cselect_b32 s38, s6, s79
	s_cselect_b32 s81, s23, s41
	s_cselect_b32 s80, s22, s40
	s_add_i32 s79, 0, 0x14000
	v_add_u32_e32 v148, s19, v162
	v_add_u32_e32 v171, s79, v162
	ds_read_b128 v[136:139], v148
	ds_read_b128 v[140:143], v148 offset:1024
	ds_read_b128 v[144:147], v148 offset:2048
	ds_read_b128 v[148:151], v148 offset:3072
	ds_read_b128 v[172:175], v171
	ds_read_b128 v[176:179], v171 offset:1024
	ds_read_b128 v[184:187], v171 offset:2048
	ds_read_b128 v[188:191], v171 offset:3072
	v_lshl_add_u64 v[180:181], s[0:1], 0, v[158:159]
	s_add_i32 m0, s46, 0xc000
	ds_read_b128 v[192:195], v167
	ds_read_b128 v[196:199], v167 offset:1024
	ds_read_b128 v[200:203], v167 offset:2048
	ds_read_b128 v[204:207], v167 offset:3072
	ds_read_b128 v[230:233], v167 offset:4096
	ds_read_b128 v[234:237], v167 offset:5120
	ds_read_b128 v[238:241], v167 offset:6144
	ds_read_b128 v[242:245], v167 offset:7168
	global_load_lds_dwordx4 v[180:181], off
	v_lshl_add_u64 v[180:181], s[0:1], 0, v[160:161]
	s_add_i32 m0, s46, 0xe000
	s_nop 0
	global_load_lds_dwordx4 v[180:181], off
	s_waitcnt vmcnt(8)
	s_waitcnt lgkmcnt(0)
	s_barrier
	s_setprio 1
	s_waitcnt lgkmcnt(0)
	v_mfma_f32_16x16x32_bf16 v[132:135], v[136:139], v[192:195], v[132:135]
	v_mfma_f32_16x16x32_bf16 v[132:135], v[140:143], v[196:199], v[132:135]
	v_mfma_f32_16x16x32_bf16 v[128:131], v[144:147], v[192:195], v[128:131]
	v_mfma_f32_16x16x32_bf16 v[128:131], v[148:151], v[196:199], v[128:131]
	v_mfma_f32_16x16x32_bf16 v[112:115], v[144:147], v[200:203], v[112:115]
	v_mfma_f32_16x16x32_bf16 v[112:115], v[148:151], v[204:207], v[112:115]
	v_mfma_f32_16x16x32_bf16 v[116:119], v[136:139], v[200:203], v[116:119]
	v_mfma_f32_16x16x32_bf16 v[116:119], v[140:143], v[204:207], v[116:119]
	v_mfma_f32_16x16x32_bf16 v[100:103], v[136:139], v[230:233], v[100:103]
	v_mfma_f32_16x16x32_bf16 v[100:103], v[140:143], v[234:237], v[100:103]
	v_mfma_f32_16x16x32_bf16 v[96:99], v[144:147], v[230:233], v[96:99]
	v_mfma_f32_16x16x32_bf16 v[96:99], v[148:151], v[234:237], v[96:99]
	v_mfma_f32_16x16x32_bf16 v[80:83], v[144:147], v[238:241], v[80:83]
	v_mfma_f32_16x16x32_bf16 v[80:83], v[148:151], v[242:245], v[80:83]
	v_mfma_f32_16x16x32_bf16 v[84:87], v[136:139], v[238:241], v[84:87]
	v_mfma_f32_16x16x32_bf16 v[84:87], v[140:143], v[242:245], v[84:87]
	s_setprio 0
	s_setprio 1
	v_mfma_f32_16x16x32_bf16 v[124:127], v[172:175], v[192:195], v[124:127]
	v_mfma_f32_16x16x32_bf16 v[124:127], v[176:179], v[196:199], v[124:127]
	v_mfma_f32_16x16x32_bf16 v[120:123], v[184:187], v[192:195], v[120:123]
	v_mfma_f32_16x16x32_bf16 v[120:123], v[188:191], v[196:199], v[120:123]
	v_mfma_f32_16x16x32_bf16 v[104:107], v[184:187], v[200:203], v[104:107]
	v_mfma_f32_16x16x32_bf16 v[104:107], v[188:191], v[204:207], v[104:107]
	v_mfma_f32_16x16x32_bf16 v[108:111], v[172:175], v[200:203], v[108:111]
	v_mfma_f32_16x16x32_bf16 v[108:111], v[176:179], v[204:207], v[108:111]
	v_mfma_f32_16x16x32_bf16 v[92:95], v[172:175], v[230:233], v[92:95]
	v_mfma_f32_16x16x32_bf16 v[92:95], v[176:179], v[234:237], v[92:95]
	v_mfma_f32_16x16x32_bf16 v[88:91], v[184:187], v[230:233], v[88:91]
	v_mfma_f32_16x16x32_bf16 v[88:91], v[188:191], v[234:237], v[88:91]
	v_mfma_f32_16x16x32_bf16 v[72:75], v[184:187], v[238:241], v[72:75]
	v_mfma_f32_16x16x32_bf16 v[72:75], v[188:191], v[242:245], v[72:75]
	v_mfma_f32_16x16x32_bf16 v[76:79], v[172:175], v[238:241], v[76:79]
	v_mfma_f32_16x16x32_bf16 v[76:79], v[176:179], v[242:245], v[76:79]
	s_setprio 0
	s_barrier
	s_add_i32 s82, s19, s42
	v_lshl_add_u64 v[180:181], s[80:81], 0, v[154:155]
	s_mov_b32 m0, s82
	ds_read_b128 v[192:195], v167 offset:16384
	ds_read_b128 v[196:199], v167 offset:17408
	ds_read_b128 v[200:203], v167 offset:18432
	ds_read_b128 v[204:207], v167 offset:19456
	ds_read_b128 v[230:233], v167 offset:20480
	ds_read_b128 v[234:237], v167 offset:21504
	ds_read_b128 v[238:241], v167 offset:22528
	ds_read_b128 v[242:245], v167 offset:23552
	global_load_lds_dwordx4 v[180:181], off
	s_add_i32 m0, s82, 0x2000
	v_lshl_add_u64 v[208:209], s[80:81], 0, v[2:3]
	s_add_u32 s80, s80, s48
	s_addc_u32 s81, s81, s49
	s_add_i32 s79, s79, s42
	global_load_lds_dwordx4 v[208:209], off
	v_lshl_add_u64 v[216:217], s[80:81], 0, v[154:155]
	s_mov_b32 m0, s79
	v_lshl_add_u64 v[224:225], s[80:81], 0, v[2:3]
	global_load_lds_dwordx4 v[216:217], off
	s_add_i32 m0, s79, 0x2000
	v_lshl_add_u64 v[226:227], s[38:39], 0, v[156:157]
	global_load_lds_dwordx4 v[224:225], off
	s_mov_b32 m0, s46
	v_lshl_add_u64 v[246:247], s[38:39], 0, v[152:153]
	global_load_lds_dwordx4 v[226:227], off
	s_mov_b32 m0, s47
	s_nop 0
	global_load_lds_dwordx4 v[246:247], off
	s_waitcnt vmcnt(8)
	s_waitcnt lgkmcnt(0)
	s_barrier
; #define PG8_STAGE(bufoff, gbase, voff) do { _Pragma("unroll") for (int _i = 0; _i < 2; ++_i) \
;         __builtin_amdgcn_global_load_lds((const unsigned*)((const char*)(gbase) + (voff)[_i]), (PG8_LAS unsigned*)(lds + (bufoff) + ldsw + _i * 8192), 16, 0, 0); } while (0)
; #define PG8_LDA(dst, b, h) do { _Pragma("unroll") for (int m = 0; m < 4; ++m) _Pragma("unroll") for (int k = 0; k < 2; ++k) dst[m][k] = *(const PG8_LAS bf16x8*)(lds + PG8_SA(b, h) + aoff + m * 2048 + k * 1024); } while (0)
; #define PG8_LDB(dst, b, h) do { _Pragma("unroll") for (int n = 0; n < 2; ++n) _Pragma("unroll") for (int k = 0; k < 2; ++k) dst[n][k] = *(const PG8_LAS bf16x8*)(lds + PG8_SB(b, h) + boff + n * 2048 + k * 1024); } while (0)
; #define PG8_MMA(ai, bj, At, Bt) do { __builtin_amdgcn_s_setprio(1); _Pragma("unroll") for (int m = 0; m < 4; ++m) _Pragma("unroll") for (int n = 0; n < 2; ++n) _Pragma("unroll") for (int k = 0; k < 2; ++k) \
;         acc[ai][bj][m][n] = __builtin_amdgcn_mfma_f32_16x16x32_bf16(Bt[n][k], At[m][k], acc[ai][bj][m][n], 0, 0, 0); __builtin_amdgcn_s_setprio(0); } while (0)
; #define PG8_BAR __builtin_amdgcn_s_barrier()
; template <class Epi, class Sched, bool ALIGN_EPI = false, bool SP2 = false>
; __device__ __forceinline__ void gemm_phase(PG8_LAS unsigned char* lds, const Gemm g, const Sched& S, const Epi& E) {
;     ...
;             if constexpr (SP2) {
;             PG8_LDB(B0, 0, 0); PG8_LDB(B1, 0, 1); PG8_SCHED; PG8_LDA(At, 0, 0); PG8_STAGE(PG8_SA(1, 1), a1 + hstep, voffA);
;             PG8_WAIT_V(8); PG8_WAIT_L(0); PG8_BAR; PG8_MMA(0, 0, At, B0); PG8_MMA(0, 1, At, B1); PG8_BAR; PG8_SCHED;
;             PG8_LDA(At, 0, 1); PG8_STAGE(PG8_SB(0, 0), b2, voffB); PG8_STAGE(PG8_SB(0, 1), b2 + hstep, voffB); PG8_STAGE(PG8_SA(0, 0), a2, voffA);
;             PG8_WAIT_V(8); PG8_WAIT_L(0); PG8_BAR; PG8_MMA(1, 0, At, B0); PG8_MMA(1, 1, At, B1); PG8_BAR; PG8_SCHED;
;             PG8_LDB(B0, 1, 0); PG8_LDB(B1, 1, 1); PG8_SCHED; PG8_LDA(At, 1, 0); PG8_STAGE(PG8_SA(0, 1), a2 + hstep, voffA);
;             PG8_WAIT_V(8); PG8_WAIT_L(0); PG8_BAR; PG8_MMA(0, 0, At, B0); PG8_MMA(0, 1, At, B1); PG8_BAR; PG8_SCHED;
;             PG8_LDA(At, 1, 1); PG8_STAGE(PG8_SB(1, 0), b3, voffB); PG8_STAGE(PG8_SB(1, 1), b3 + hstep, voffB); PG8_STAGE(PG8_SA(1, 0), a3, voffA);
;             PG8_WAIT_V(8); PG8_WAIT_L(0); PG8_BAR; PG8_MMA(1, 0, At, B0); PG8_MMA(1, 1, At, B1); PG8_BAR; PG8_SCHED;
	s_setprio 1
	s_waitcnt lgkmcnt(0)
	v_mfma_f32_16x16x32_bf16 v[68:71], v[136:139], v[192:195], v[68:71]
	v_mfma_f32_16x16x32_bf16 v[68:71], v[140:143], v[196:199], v[68:71]
	v_mfma_f32_16x16x32_bf16 v[64:67], v[144:147], v[192:195], v[64:67]
	v_mfma_f32_16x16x32_bf16 v[64:67], v[148:151], v[196:199], v[64:67]
	v_mfma_f32_16x16x32_bf16 v[48:51], v[144:147], v[200:203], v[48:51]
	v_mfma_f32_16x16x32_bf16 v[48:51], v[148:151], v[204:207], v[48:51]
	v_mfma_f32_16x16x32_bf16 v[52:55], v[136:139], v[200:203], v[52:55]
	v_mfma_f32_16x16x32_bf16 v[52:55], v[140:143], v[204:207], v[52:55]
	v_mfma_f32_16x16x32_bf16 v[36:39], v[136:139], v[230:233], v[36:39]
	v_mfma_f32_16x16x32_bf16 v[36:39], v[140:143], v[234:237], v[36:39]
	v_mfma_f32_16x16x32_bf16 v[32:35], v[144:147], v[230:233], v[32:35]
	v_mfma_f32_16x16x32_bf16 v[32:35], v[148:151], v[234:237], v[32:35]
	v_mfma_f32_16x16x32_bf16 v[16:19], v[144:147], v[238:241], v[16:19]
	v_mfma_f32_16x16x32_bf16 v[16:19], v[148:151], v[242:245], v[16:19]
	v_mfma_f32_16x16x32_bf16 v[20:23], v[136:139], v[238:241], v[20:23]
	v_mfma_f32_16x16x32_bf16 v[20:23], v[140:143], v[242:245], v[20:23]
	s_setprio 0
	s_setprio 1
	v_mfma_f32_16x16x32_bf16 v[60:63], v[172:175], v[192:195], v[60:63]
	v_mfma_f32_16x16x32_bf16 v[60:63], v[176:179], v[196:199], v[60:63]
	v_mfma_f32_16x16x32_bf16 v[56:59], v[184:187], v[192:195], v[56:59]
	v_mfma_f32_16x16x32_bf16 v[56:59], v[188:191], v[196:199], v[56:59]
	v_mfma_f32_16x16x32_bf16 v[40:43], v[184:187], v[200:203], v[40:43]
	v_mfma_f32_16x16x32_bf16 v[40:43], v[188:191], v[204:207], v[40:43]
	v_mfma_f32_16x16x32_bf16 v[44:47], v[172:175], v[200:203], v[44:47]
	v_mfma_f32_16x16x32_bf16 v[44:47], v[176:179], v[204:207], v[44:47]
	v_mfma_f32_16x16x32_bf16 v[28:31], v[172:175], v[230:233], v[28:31]
	v_mfma_f32_16x16x32_bf16 v[28:31], v[176:179], v[234:237], v[28:31]
	v_mfma_f32_16x16x32_bf16 v[24:27], v[184:187], v[230:233], v[24:27]
	v_mfma_f32_16x16x32_bf16 v[24:27], v[188:191], v[234:237], v[24:27]
	v_mfma_f32_16x16x32_bf16 v[8:11], v[184:187], v[238:241], v[8:11]
	v_mfma_f32_16x16x32_bf16 v[8:11], v[188:191], v[242:245], v[8:11]
	v_mfma_f32_16x16x32_bf16 v[12:15], v[172:175], v[238:241], v[12:15]
	v_mfma_f32_16x16x32_bf16 v[12:15], v[176:179], v[242:245], v[12:15]
	s_setprio 0
	s_barrier
	s_add_i32 s79, 0, 0x1c000
	v_add_u32_e32 v148, s91, v162
	v_add_u32_e32 v171, s79, v162
	ds_read_b128 v[136:139], v148
	ds_read_b128 v[140:143], v148 offset:1024
	ds_read_b128 v[144:147], v148 offset:2048
	ds_read_b128 v[148:151], v148 offset:3072
	ds_read_b128 v[172:175], v171
	ds_read_b128 v[176:179], v171 offset:1024
	ds_read_b128 v[184:187], v171 offset:2048
	ds_read_b128 v[188:191], v171 offset:3072
	s_add_u32 s38, s38, s48
	s_addc_u32 s39, s39, s49
	s_mov_b32 m0, s52
	v_lshl_add_u64 v[248:249], s[38:39], 0, v[156:157]
	ds_read_b128 v[192:195], v167 offset:32768
	ds_read_b128 v[196:199], v167 offset:33792
	ds_read_b128 v[200:203], v167 offset:34816
	ds_read_b128 v[204:207], v167 offset:35840
	ds_read_b128 v[230:233], v167 offset:36864
	ds_read_b128 v[234:237], v167 offset:37888
	ds_read_b128 v[238:241], v167 offset:38912
	ds_read_b128 v[242:245], v167 offset:39936
	global_load_lds_dwordx4 v[248:249], off
	v_lshl_add_u64 v[248:249], s[38:39], 0, v[152:153]
	s_mov_b32 m0, s53
	s_nop 0
	global_load_lds_dwordx4 v[248:249], off
	s_waitcnt vmcnt(8)
	s_waitcnt lgkmcnt(0)
	s_barrier
	s_setprio 1
	s_waitcnt lgkmcnt(0)
	v_mfma_f32_16x16x32_bf16 v[132:135], v[136:139], v[192:195], v[132:135]
	v_mfma_f32_16x16x32_bf16 v[132:135], v[140:143], v[196:199], v[132:135]
	v_mfma_f32_16x16x32_bf16 v[128:131], v[144:147], v[192:195], v[128:131]
	v_mfma_f32_16x16x32_bf16 v[128:131], v[148:151], v[196:199], v[128:131]
	v_mfma_f32_16x16x32_bf16 v[112:115], v[144:147], v[200:203], v[112:115]
	v_mfma_f32_16x16x32_bf16 v[112:115], v[148:151], v[204:207], v[112:115]
	v_mfma_f32_16x16x32_bf16 v[116:119], v[136:139], v[200:203], v[116:119]
	v_mfma_f32_16x16x32_bf16 v[116:119], v[140:143], v[204:207], v[116:119]
	v_mfma_f32_16x16x32_bf16 v[100:103], v[136:139], v[230:233], v[100:103]
	v_mfma_f32_16x16x32_bf16 v[100:103], v[140:143], v[234:237], v[100:103]
	v_mfma_f32_16x16x32_bf16 v[96:99], v[144:147], v[230:233], v[96:99]
	v_mfma_f32_16x16x32_bf16 v[96:99], v[148:151], v[234:237], v[96:99]
	v_mfma_f32_16x16x32_bf16 v[80:83], v[144:147], v[238:241], v[80:83]
	v_mfma_f32_16x16x32_bf16 v[80:83], v[148:151], v[242:245], v[80:83]
	v_mfma_f32_16x16x32_bf16 v[84:87], v[136:139], v[238:241], v[84:87]
	v_mfma_f32_16x16x32_bf16 v[84:87], v[140:143], v[242:245], v[84:87]
	s_setprio 0
	s_setprio 1
	v_mfma_f32_16x16x32_bf16 v[124:127], v[172:175], v[192:195], v[124:127]
	v_mfma_f32_16x16x32_bf16 v[124:127], v[176:179], v[196:199], v[124:127]
	v_mfma_f32_16x16x32_bf16 v[120:123], v[184:187], v[192:195], v[120:123]
	v_mfma_f32_16x16x32_bf16 v[120:123], v[188:191], v[196:199], v[120:123]
	v_mfma_f32_16x16x32_bf16 v[104:107], v[184:187], v[200:203], v[104:107]
	v_mfma_f32_16x16x32_bf16 v[104:107], v[188:191], v[204:207], v[104:107]
	v_mfma_f32_16x16x32_bf16 v[108:111], v[172:175], v[200:203], v[108:111]
	v_mfma_f32_16x16x32_bf16 v[108:111], v[176:179], v[204:207], v[108:111]
	v_mfma_f32_16x16x32_bf16 v[92:95], v[172:175], v[230:233], v[92:95]
	v_mfma_f32_16x16x32_bf16 v[92:95], v[176:179], v[234:237], v[92:95]
	v_mfma_f32_16x16x32_bf16 v[88:91], v[184:187], v[230:233], v[88:91]
	v_mfma_f32_16x16x32_bf16 v[88:91], v[188:191], v[234:237], v[88:91]
	v_mfma_f32_16x16x32_bf16 v[72:75], v[184:187], v[238:241], v[72:75]
	v_mfma_f32_16x16x32_bf16 v[72:75], v[188:191], v[242:245], v[72:75]
	v_mfma_f32_16x16x32_bf16 v[76:79], v[172:175], v[238:241], v[76:79]
	v_mfma_f32_16x16x32_bf16 v[76:79], v[176:179], v[242:245], v[76:79]
	s_setprio 0
	s_barrier
; #define PG8_STAGE(bufoff, gbase, voff) do { _Pragma("unroll") for (int _i = 0; _i < 2; ++_i) \
;         __builtin_amdgcn_global_load_lds((const unsigned*)((const char*)(gbase) + (voff)[_i]), (PG8_LAS unsigned*)(lds + (bufoff) + ldsw + _i * 8192), 16, 0, 0); } while (0)
; #define PG8_LDA(dst, b, h) do { _Pragma("unroll") for (int m = 0; m < 4; ++m) _Pragma("unroll") for (int k = 0; k < 2; ++k) dst[m][k] = *(const PG8_LAS bf16x8*)(lds + PG8_SA(b, h) + aoff + m * 2048 + k * 1024); } while (0)
; #define PG8_WAIT_V(n) asm volatile("s_waitcnt vmcnt(" #n ")" ::: "memory")
; #define PG8_BAR __builtin_amdgcn_s_barrier()
; template <class Epi, class Sched, bool ALIGN_EPI = false, bool SP2 = false>
; __device__ __forceinline__ void gemm_phase(PG8_LAS unsigned char* lds, const Gemm g, const Sched& S, const Epi& E) {
;     ...
;         for (int t = 0; t < nt; t += 2) {
;             if constexpr (Epi::KHOOK) { if ((t & 7) == 0 && t != 0) E.khook(acc, t >> 3, wr, fr, lds); }
;             const bool last = (t == nt - 2);
;             const char* a1 = cA + (size_t)(t + 1) * kstep;
;             const char* a2 = last ? nA : cA + (size_t)(t + 2) * kstep; const char* b2 = last ? nB : cB + (size_t)(t + 2) * kstep;
;             const char* a3 = a2 + kstep; const char* b3 = b2 + kstep;
;             if (last && has_next) S.a_ready(nxt);
;             if constexpr (SP2) {
;             PG8_LDB(B0, 0, 0); PG8_LDB(B1, 0, 1); PG8_SCHED; PG8_LDA(At, 0, 0); PG8_STAGE(PG8_SA(1, 1), a1 + hstep, voffA);
;             PG8_WAIT_V(8); PG8_WAIT_L(0); PG8_BAR; PG8_MMA(0, 0, At, B0); PG8_MMA(0, 1, At, B1); PG8_BAR; PG8_SCHED;
;             PG8_LDA(At, 0, 1); PG8_STAGE(PG8_SB(0, 0), b2, voffB); PG8_STAGE(PG8_SB(0, 1), b2 + hstep, voffB); PG8_STAGE(PG8_SA(0, 0), a2, voffA);
;             PG8_WAIT_V(8); PG8_WAIT_L(0); PG8_BAR; PG8_MMA(1, 0, At, B0); PG8_MMA(1, 1, At, B1); PG8_BAR; PG8_SCHED;
;             PG8_LDB(B0, 1, 0); PG8_LDB(B1, 1, 1); PG8_SCHED; PG8_LDA(At, 1, 0); PG8_STAGE(PG8_SA(0, 1), a2 + hstep, voffA);
;             PG8_WAIT_V(8); PG8_WAIT_L(0); PG8_BAR; PG8_MMA(0, 0, At, B0); PG8_MMA(0, 1, At, B1); PG8_BAR; PG8_SCHED;
;             PG8_LDA(At, 1, 1); PG8_STAGE(PG8_SB(1, 0), b3, voffB); PG8_STAGE(PG8_SB(1, 1), b3 + hstep, voffB); PG8_STAGE(PG8_SA(1, 0), a3, voffA);
;             PG8_WAIT_V(8); PG8_WAIT_L(0); PG8_BAR; PG8_MMA(1, 0, At, B0); PG8_MMA(1, 1, At, B1); PG8_BAR; PG8_SCHED;
	s_add_i32 s38, s91, s42
	v_lshl_add_u64 v[180:181], v[180:181], 0, s[24:25]
	s_mov_b32 m0, s38
	ds_read_b128 v[192:195], v167 offset:49152
	ds_read_b128 v[196:199], v167 offset:50176
	ds_read_b128 v[200:203], v167 offset:51200
	ds_read_b128 v[204:207], v167 offset:52224
	ds_read_b128 v[230:233], v167 offset:53248
	ds_read_b128 v[234:237], v167 offset:54272
	ds_read_b128 v[238:241], v167 offset:55296
	ds_read_b128 v[242:245], v167 offset:56320
	global_load_lds_dwordx4 v[180:181], off
	v_lshl_add_u64 v[180:181], v[208:209], 0, s[24:25]
	s_add_i32 m0, s38, 0x2000
	s_add_i32 s38, s79, s42
	global_load_lds_dwordx4 v[180:181], off
	v_lshl_add_u64 v[180:181], v[216:217], 0, s[24:25]
	s_mov_b32 m0, s38
	s_nop 0
	global_load_lds_dwordx4 v[180:181], off
	v_lshl_add_u64 v[180:181], v[224:225], 0, s[24:25]
	s_add_i32 m0, s38, 0x2000
	s_nop 0
	global_load_lds_dwordx4 v[180:181], off
	v_lshl_add_u64 v[180:181], v[226:227], 0, s[24:25]
	s_mov_b32 m0, s72
	s_nop 0
	global_load_lds_dwordx4 v[180:181], off
	v_lshl_add_u64 v[180:181], v[246:247], 0, s[24:25]
	s_mov_b32 m0, s73
	s_nop 0
	global_load_lds_dwordx4 v[180:181], off
	s_waitcnt vmcnt(8)
	s_waitcnt lgkmcnt(0)
	s_barrier
	s_setprio 1
	s_waitcnt lgkmcnt(0)
	v_mfma_f32_16x16x32_bf16 v[68:71], v[136:139], v[192:195], v[68:71]
	v_mfma_f32_16x16x32_bf16 v[68:71], v[140:143], v[196:199], v[68:71]
	v_mfma_f32_16x16x32_bf16 v[64:67], v[144:147], v[192:195], v[64:67]
	v_mfma_f32_16x16x32_bf16 v[64:67], v[148:151], v[196:199], v[64:67]
	v_mfma_f32_16x16x32_bf16 v[48:51], v[144:147], v[200:203], v[48:51]
	v_mfma_f32_16x16x32_bf16 v[48:51], v[148:151], v[204:207], v[48:51]
	v_mfma_f32_16x16x32_bf16 v[52:55], v[136:139], v[200:203], v[52:55]
	v_mfma_f32_16x16x32_bf16 v[52:55], v[140:143], v[204:207], v[52:55]
	v_mfma_f32_16x16x32_bf16 v[36:39], v[136:139], v[230:233], v[36:39]
	v_mfma_f32_16x16x32_bf16 v[36:39], v[140:143], v[234:237], v[36:39]
	v_mfma_f32_16x16x32_bf16 v[32:35], v[144:147], v[230:233], v[32:35]
	v_mfma_f32_16x16x32_bf16 v[32:35], v[148:151], v[234:237], v[32:35]
	v_mfma_f32_16x16x32_bf16 v[16:19], v[144:147], v[238:241], v[16:19]
	v_mfma_f32_16x16x32_bf16 v[16:19], v[148:151], v[242:245], v[16:19]
	v_mfma_f32_16x16x32_bf16 v[20:23], v[136:139], v[238:241], v[20:23]
	v_mfma_f32_16x16x32_bf16 v[20:23], v[140:143], v[242:245], v[20:23]
	s_setprio 0
	s_setprio 1
	v_mfma_f32_16x16x32_bf16 v[60:63], v[172:175], v[192:195], v[60:63]
	v_mfma_f32_16x16x32_bf16 v[60:63], v[176:179], v[196:199], v[60:63]
	v_mfma_f32_16x16x32_bf16 v[56:59], v[184:187], v[192:195], v[56:59]
	v_mfma_f32_16x16x32_bf16 v[56:59], v[188:191], v[196:199], v[56:59]
	v_mfma_f32_16x16x32_bf16 v[40:43], v[184:187], v[200:203], v[40:43]
	v_mfma_f32_16x16x32_bf16 v[40:43], v[188:191], v[204:207], v[40:43]
	v_mfma_f32_16x16x32_bf16 v[44:47], v[172:175], v[200:203], v[44:47]
	v_mfma_f32_16x16x32_bf16 v[44:47], v[176:179], v[204:207], v[44:47]
	v_mfma_f32_16x16x32_bf16 v[28:31], v[172:175], v[230:233], v[28:31]
	v_mfma_f32_16x16x32_bf16 v[28:31], v[176:179], v[234:237], v[28:31]
	v_mfma_f32_16x16x32_bf16 v[24:27], v[184:187], v[230:233], v[24:27]
	v_mfma_f32_16x16x32_bf16 v[24:27], v[188:191], v[234:237], v[24:27]
	v_mfma_f32_16x16x32_bf16 v[8:11], v[184:187], v[238:241], v[8:11]
	v_mfma_f32_16x16x32_bf16 v[8:11], v[188:191], v[242:245], v[8:11]
	v_mfma_f32_16x16x32_bf16 v[12:15], v[172:175], v[238:241], v[12:15]
	v_mfma_f32_16x16x32_bf16 v[12:15], v[176:179], v[242:245], v[12:15]
	s_setprio 0
	s_barrier
	s_add_u32 s0, s0, 0x100
	s_addc_u32 s1, s1, 0
	s_add_u32 s40, s40, 0x100
	s_addc_u32 s41, s41, 0
	s_cmp_ge_u32 s78, s9
	s_mov_b32 s38, s78
	s_cbranch_scc0 .LBB0_468

; #define PG8_STAGE(bufoff, gbase, voff) do { _Pragma("unroll") for (int _i = 0; _i < 2; ++_i) \
;         __builtin_amdgcn_global_load_lds((const unsigned*)((const char*)(gbase) + (voff)[_i]), (PG8_LAS unsigned*)(lds + (bufoff) + ldsw + _i * 8192), 16, 0, 0); } while (0)
; #define PG8_LDA(dst, b, h) do { _Pragma("unroll") for (int m = 0; m < 4; ++m) _Pragma("unroll") for (int k = 0; k < 2; ++k) dst[m][k] = *(const PG8_LAS bf16x8*)(lds + PG8_SA(b, h) + aoff + m * 2048 + k * 1024); } while (0)
; #define PG8_WAIT_V(n) asm volatile("s_waitcnt vmcnt(" #n ")" ::: "memory")
; #define PG8_BAR __builtin_amdgcn_s_barrier()
; template <class Epi, class Sched, bool ALIGN_EPI = false, bool SP2 = false>
; __device__ __forceinline__ void gemm_phase(PG8_LAS unsigned char* lds, const Gemm g, const Sched& S, const Epi& E) {
;     ...
;         for (int t = 0; t < nt; t += 2) {
;             if constexpr (Epi::KHOOK) { if ((t & 7) == 0 && t != 0) E.khook(acc, t >> 3, wr, fr, lds); }
;             const bool last = (t == nt - 2);
;             const char* a1 = cA + (size_t)(t + 1) * kstep;
;             const char* a2 = last ? nA : cA + (size_t)(t + 2) * kstep; const char* b2 = last ? nB : cB + (size_t)(t + 2) * kstep;
;             const char* a3 = a2 + kstep; const char* b3 = b2 + kstep;
;             if (last && has_next) S.a_ready(nxt);
;             if constexpr (SP2) {
;             PG8_LDB(B0, 0, 0); PG8_LDB(B1, 0, 1); PG8_SCHED; PG8_LDA(At, 0, 0); PG8_STAGE(PG8_SA(1, 1), a1 + hstep, voffA);
;             PG8_WAIT_V(8); PG8_WAIT_L(0); PG8_BAR; PG8_MMA(0, 0, At, B0); PG8_MMA(0, 1, At, B1); PG8_BAR; PG8_SCHED;
;             PG8_LDA(At, 0, 1); PG8_STAGE(PG8_SB(0, 0), b2, voffB); PG8_STAGE(PG8_SB(0, 1), b2 + hstep, voffB); PG8_STAGE(PG8_SA(0, 0), a2, voffA);
;             PG8_WAIT_V(8); PG8_WAIT_L(0); PG8_BAR; PG8_MMA(1, 0, At, B0); PG8_MMA(1, 1, At, B1); PG8_BAR; PG8_SCHED;
;             PG8_LDB(B0, 1, 0); PG8_LDB(B1, 1, 1); PG8_SCHED; PG8_LDA(At, 1, 0); PG8_STAGE(PG8_SA(0, 1), a2 + hstep, voffA);
;             PG8_WAIT_V(8); PG8_WAIT_L(0); PG8_BAR; PG8_MMA(0, 0, At, B0); PG8_MMA(0, 1, At, B1); PG8_BAR; PG8_SCHED;
;             PG8_LDA(At, 1, 1); PG8_STAGE(PG8_SB(1, 0), b3, voffB); PG8_STAGE(PG8_SB(1, 1), b3 + hstep, voffB); PG8_STAGE(PG8_SA(1, 0), a3, voffA);
;             PG8_WAIT_V(8); PG8_WAIT_L(0); PG8_BAR; PG8_MMA(1, 0, At, B0); PG8_MMA(1, 1, At, B1); PG8_BAR; PG8_SCHED;
.LBB0_501:
	s_add_i32 s80, s4, 2
	s_add_u32 s81, s0, 0x80
	s_addc_u32 s5, s1, 0
	s_cmp_eq_u32 s33, s4
	s_cselect_b32 s5, s23, s5
	s_cselect_b32 s4, s22, s81
	s_cselect_b32 s83, s41, s43
	s_cselect_b32 s82, s40, s42
	s_add_i32 s81, 0, 0x14000
	v_add_u32_e32 v148, s19, v164
	v_add_u32_e32 v162, s81, v164
	ds_read_b128 v[136:139], v148
	ds_read_b128 v[140:143], v148 offset:1024
	ds_read_b128 v[144:147], v148 offset:2048
	ds_read_b128 v[148:151], v148 offset:3072
	ds_read_b128 v[174:177], v162
	ds_read_b128 v[178:181], v162 offset:1024
	ds_read_b128 v[184:187], v162 offset:2048
	ds_read_b128 v[188:191], v162 offset:3072
	v_lshl_add_u64 v[162:163], s[0:1], 0, v[158:159]
	s_add_i32 m0, s45, 0xc000
	ds_read_b128 v[192:195], v170
	ds_read_b128 v[196:199], v170 offset:1024
	ds_read_b128 v[200:203], v170 offset:2048
	ds_read_b128 v[204:207], v170 offset:3072
	ds_read_b128 v[230:233], v170 offset:4096
	ds_read_b128 v[234:237], v170 offset:5120
	ds_read_b128 v[238:241], v170 offset:6144
	ds_read_b128 v[242:245], v170 offset:7168
	global_load_lds_dwordx4 v[162:163], off
	v_lshl_add_u64 v[162:163], s[0:1], 0, v[160:161]
	s_add_i32 m0, s45, 0xe000
	s_nop 0
	global_load_lds_dwordx4 v[162:163], off
	s_waitcnt vmcnt(8)
	s_waitcnt lgkmcnt(0)
	s_barrier
	s_setprio 1
	s_waitcnt lgkmcnt(0)
	v_mfma_f32_16x16x32_bf16 v[132:135], v[136:139], v[192:195], v[132:135]
	v_mfma_f32_16x16x32_bf16 v[132:135], v[140:143], v[196:199], v[132:135]
	v_mfma_f32_16x16x32_bf16 v[128:131], v[144:147], v[192:195], v[128:131]
	v_mfma_f32_16x16x32_bf16 v[128:131], v[148:151], v[196:199], v[128:131]
	v_mfma_f32_16x16x32_bf16 v[112:115], v[144:147], v[200:203], v[112:115]
	v_mfma_f32_16x16x32_bf16 v[112:115], v[148:151], v[204:207], v[112:115]
	v_mfma_f32_16x16x32_bf16 v[116:119], v[136:139], v[200:203], v[116:119]
	v_mfma_f32_16x16x32_bf16 v[116:119], v[140:143], v[204:207], v[116:119]
	v_mfma_f32_16x16x32_bf16 v[100:103], v[136:139], v[230:233], v[100:103]
	v_mfma_f32_16x16x32_bf16 v[100:103], v[140:143], v[234:237], v[100:103]
	v_mfma_f32_16x16x32_bf16 v[96:99], v[144:147], v[230:233], v[96:99]
	v_mfma_f32_16x16x32_bf16 v[96:99], v[148:151], v[234:237], v[96:99]
	v_mfma_f32_16x16x32_bf16 v[80:83], v[144:147], v[238:241], v[80:83]
	v_mfma_f32_16x16x32_bf16 v[80:83], v[148:151], v[242:245], v[80:83]
	v_mfma_f32_16x16x32_bf16 v[84:87], v[136:139], v[238:241], v[84:87]
	v_mfma_f32_16x16x32_bf16 v[84:87], v[140:143], v[242:245], v[84:87]
	s_setprio 0
	s_setprio 1
	v_mfma_f32_16x16x32_bf16 v[124:127], v[174:177], v[192:195], v[124:127]
	v_mfma_f32_16x16x32_bf16 v[124:127], v[178:181], v[196:199], v[124:127]
	v_mfma_f32_16x16x32_bf16 v[120:123], v[184:187], v[192:195], v[120:123]
	v_mfma_f32_16x16x32_bf16 v[120:123], v[188:191], v[196:199], v[120:123]
	v_mfma_f32_16x16x32_bf16 v[104:107], v[184:187], v[200:203], v[104:107]
	v_mfma_f32_16x16x32_bf16 v[104:107], v[188:191], v[204:207], v[104:107]
	v_mfma_f32_16x16x32_bf16 v[108:111], v[174:177], v[200:203], v[108:111]
	v_mfma_f32_16x16x32_bf16 v[108:111], v[178:181], v[204:207], v[108:111]
	v_mfma_f32_16x16x32_bf16 v[92:95], v[174:177], v[230:233], v[92:95]
	v_mfma_f32_16x16x32_bf16 v[92:95], v[178:181], v[234:237], v[92:95]
	v_mfma_f32_16x16x32_bf16 v[88:91], v[184:187], v[230:233], v[88:91]
	v_mfma_f32_16x16x32_bf16 v[88:91], v[188:191], v[234:237], v[88:91]
	v_mfma_f32_16x16x32_bf16 v[72:75], v[184:187], v[238:241], v[72:75]
	v_mfma_f32_16x16x32_bf16 v[72:75], v[188:191], v[242:245], v[72:75]
	v_mfma_f32_16x16x32_bf16 v[76:79], v[174:177], v[238:241], v[76:79]
	v_mfma_f32_16x16x32_bf16 v[76:79], v[178:181], v[242:245], v[76:79]
	s_setprio 0
	s_barrier
	s_add_i32 s84, s19, s44
	v_lshl_add_u64 v[162:163], s[82:83], 0, v[152:153]
	s_mov_b32 m0, s84
	ds_read_b128 v[192:195], v170 offset:16384
	ds_read_b128 v[196:199], v170 offset:17408
	ds_read_b128 v[200:203], v170 offset:18432
	ds_read_b128 v[204:207], v170 offset:19456
	ds_read_b128 v[230:233], v170 offset:20480
	ds_read_b128 v[234:237], v170 offset:21504
	ds_read_b128 v[238:241], v170 offset:22528
	ds_read_b128 v[242:245], v170 offset:23552
	global_load_lds_dwordx4 v[162:163], off
	s_add_i32 m0, s84, 0x2000
	v_lshl_add_u64 v[208:209], s[82:83], 0, v[156:157]
	s_add_u32 s82, s82, s48
	s_addc_u32 s83, s83, s49
	s_add_i32 s81, s81, s44
	global_load_lds_dwordx4 v[208:209], off
	v_lshl_add_u64 v[246:247], s[82:83], 0, v[152:153]
	s_mov_b32 m0, s81
	v_lshl_add_u64 v[248:249], s[82:83], 0, v[156:157]
	global_load_lds_dwordx4 v[246:247], off
	s_add_i32 m0, s81, 0x2000
	v_lshl_add_u64 v[216:217], s[4:5], 0, v[2:3]
	global_load_lds_dwordx4 v[248:249], off
	s_mov_b32 m0, s45
	v_lshl_add_u64 v[224:225], s[4:5], 0, v[154:155]
	global_load_lds_dwordx4 v[216:217], off
	s_mov_b32 m0, s46
	s_nop 0
	global_load_lds_dwordx4 v[224:225], off
	s_waitcnt vmcnt(8)
	s_waitcnt lgkmcnt(0)
	s_barrier
; #define PG8_STAGE(bufoff, gbase, voff) do { _Pragma("unroll") for (int _i = 0; _i < 2; ++_i) \
;         __builtin_amdgcn_global_load_lds((const unsigned*)((const char*)(gbase) + (voff)[_i]), (PG8_LAS unsigned*)(lds + (bufoff) + ldsw + _i * 8192), 16, 0, 0); } while (0)
; #define PG8_LDA(dst, b, h) do { _Pragma("unroll") for (int m = 0; m < 4; ++m) _Pragma("unroll") for (int k = 0; k < 2; ++k) dst[m][k] = *(const PG8_LAS bf16x8*)(lds + PG8_SA(b, h) + aoff + m * 2048 + k * 1024); } while (0)
; #define PG8_LDB(dst, b, h) do { _Pragma("unroll") for (int n = 0; n < 2; ++n) _Pragma("unroll") for (int k = 0; k < 2; ++k) dst[n][k] = *(const PG8_LAS bf16x8*)(lds + PG8_SB(b, h) + boff + n * 2048 + k * 1024); } while (0)
; #define PG8_MMA(ai, bj, At, Bt) do { __builtin_amdgcn_s_setprio(1); _Pragma("unroll") for (int m = 0; m < 4; ++m) _Pragma("unroll") for (int n = 0; n < 2; ++n) _Pragma("unroll") for (int k = 0; k < 2; ++k) \
;         acc[ai][bj][m][n] = __builtin_amdgcn_mfma_f32_16x16x32_bf16(Bt[n][k], At[m][k], acc[ai][bj][m][n], 0, 0, 0); __builtin_amdgcn_s_setprio(0); } while (0)
; #define PG8_BAR __builtin_amdgcn_s_barrier()
; template <class Epi, class Sched, bool ALIGN_EPI = false, bool SP2 = false>
; __device__ __forceinline__ void gemm_phase(PG8_LAS unsigned char* lds, const Gemm g, const Sched& S, const Epi& E) {
;     ...
;             if constexpr (SP2) {
;             PG8_LDB(B0, 0, 0); PG8_LDB(B1, 0, 1); PG8_SCHED; PG8_LDA(At, 0, 0); PG8_STAGE(PG8_SA(1, 1), a1 + hstep, voffA);
;             PG8_WAIT_V(8); PG8_WAIT_L(0); PG8_BAR; PG8_MMA(0, 0, At, B0); PG8_MMA(0, 1, At, B1); PG8_BAR; PG8_SCHED;
;             PG8_LDA(At, 0, 1); PG8_STAGE(PG8_SB(0, 0), b2, voffB); PG8_STAGE(PG8_SB(0, 1), b2 + hstep, voffB); PG8_STAGE(PG8_SA(0, 0), a2, voffA);
;             PG8_WAIT_V(8); PG8_WAIT_L(0); PG8_BAR; PG8_MMA(1, 0, At, B0); PG8_MMA(1, 1, At, B1); PG8_BAR; PG8_SCHED;
;             PG8_LDB(B0, 1, 0); PG8_LDB(B1, 1, 1); PG8_SCHED; PG8_LDA(At, 1, 0); PG8_STAGE(PG8_SA(0, 1), a2 + hstep, voffA);
;             PG8_WAIT_V(8); PG8_WAIT_L(0); PG8_BAR; PG8_MMA(0, 0, At, B0); PG8_MMA(0, 1, At, B1); PG8_BAR; PG8_SCHED;
;             PG8_LDA(At, 1, 1); PG8_STAGE(PG8_SB(1, 0), b3, voffB); PG8_STAGE(PG8_SB(1, 1), b3 + hstep, voffB); PG8_STAGE(PG8_SA(1, 0), a3, voffA);
;             PG8_WAIT_V(8); PG8_WAIT_L(0); PG8_BAR; PG8_MMA(1, 0, At, B0); PG8_MMA(1, 1, At, B1); PG8_BAR; PG8_SCHED;
	s_setprio 1
	s_waitcnt lgkmcnt(0)
	v_mfma_f32_16x16x32_bf16 v[68:71], v[136:139], v[192:195], v[68:71]
	v_mfma_f32_16x16x32_bf16 v[68:71], v[140:143], v[196:199], v[68:71]
	v_mfma_f32_16x16x32_bf16 v[64:67], v[144:147], v[192:195], v[64:67]
	v_mfma_f32_16x16x32_bf16 v[64:67], v[148:151], v[196:199], v[64:67]
	v_mfma_f32_16x16x32_bf16 v[48:51], v[144:147], v[200:203], v[48:51]
	v_mfma_f32_16x16x32_bf16 v[48:51], v[148:151], v[204:207], v[48:51]
	v_mfma_f32_16x16x32_bf16 v[52:55], v[136:139], v[200:203], v[52:55]
	v_mfma_f32_16x16x32_bf16 v[52:55], v[140:143], v[204:207], v[52:55]
	v_mfma_f32_16x16x32_bf16 v[36:39], v[136:139], v[230:233], v[36:39]
	v_mfma_f32_16x16x32_bf16 v[36:39], v[140:143], v[234:237], v[36:39]
	v_mfma_f32_16x16x32_bf16 v[32:35], v[144:147], v[230:233], v[32:35]
	v_mfma_f32_16x16x32_bf16 v[32:35], v[148:151], v[234:237], v[32:35]
	v_mfma_f32_16x16x32_bf16 v[16:19], v[144:147], v[238:241], v[16:19]
	v_mfma_f32_16x16x32_bf16 v[16:19], v[148:151], v[242:245], v[16:19]
	v_mfma_f32_16x16x32_bf16 v[20:23], v[136:139], v[238:241], v[20:23]
	v_mfma_f32_16x16x32_bf16 v[20:23], v[140:143], v[242:245], v[20:23]
	s_setprio 0
	s_setprio 1
	v_mfma_f32_16x16x32_bf16 v[60:63], v[174:177], v[192:195], v[60:63]
	v_mfma_f32_16x16x32_bf16 v[60:63], v[178:181], v[196:199], v[60:63]
	v_mfma_f32_16x16x32_bf16 v[56:59], v[184:187], v[192:195], v[56:59]
	v_mfma_f32_16x16x32_bf16 v[56:59], v[188:191], v[196:199], v[56:59]
	v_mfma_f32_16x16x32_bf16 v[40:43], v[184:187], v[200:203], v[40:43]
	v_mfma_f32_16x16x32_bf16 v[40:43], v[188:191], v[204:207], v[40:43]
	v_mfma_f32_16x16x32_bf16 v[44:47], v[174:177], v[200:203], v[44:47]
	v_mfma_f32_16x16x32_bf16 v[44:47], v[178:181], v[204:207], v[44:47]
	v_mfma_f32_16x16x32_bf16 v[28:31], v[174:177], v[230:233], v[28:31]
	v_mfma_f32_16x16x32_bf16 v[28:31], v[178:181], v[234:237], v[28:31]
	v_mfma_f32_16x16x32_bf16 v[24:27], v[184:187], v[230:233], v[24:27]
	v_mfma_f32_16x16x32_bf16 v[24:27], v[188:191], v[234:237], v[24:27]
	v_mfma_f32_16x16x32_bf16 v[8:11], v[184:187], v[238:241], v[8:11]
	v_mfma_f32_16x16x32_bf16 v[8:11], v[188:191], v[242:245], v[8:11]
	v_mfma_f32_16x16x32_bf16 v[12:15], v[174:177], v[238:241], v[12:15]
	v_mfma_f32_16x16x32_bf16 v[12:15], v[178:181], v[242:245], v[12:15]
	s_setprio 0
	s_barrier
	s_add_i32 s81, 0, 0x1c000
	v_add_u32_e32 v148, s91, v164
	v_add_u32_e32 v173, s81, v164
	ds_read_b128 v[136:139], v148
	ds_read_b128 v[140:143], v148 offset:1024
	ds_read_b128 v[144:147], v148 offset:2048
	ds_read_b128 v[148:151], v148 offset:3072
	ds_read_b128 v[174:177], v173
	ds_read_b128 v[178:181], v173 offset:1024
	ds_read_b128 v[184:187], v173 offset:2048
	ds_read_b128 v[188:191], v173 offset:3072
	s_add_u32 s4, s4, s48
	s_addc_u32 s5, s5, s49
	s_mov_b32 m0, s47
	v_lshl_add_u64 v[226:227], s[4:5], 0, v[2:3]
	ds_read_b128 v[192:195], v170 offset:32768
	ds_read_b128 v[196:199], v170 offset:33792
	ds_read_b128 v[200:203], v170 offset:34816
	ds_read_b128 v[204:207], v170 offset:35840
	ds_read_b128 v[230:233], v170 offset:36864
	ds_read_b128 v[234:237], v170 offset:37888
	ds_read_b128 v[238:241], v170 offset:38912
	ds_read_b128 v[242:245], v170 offset:39936
	global_load_lds_dwordx4 v[226:227], off
	v_lshl_add_u64 v[226:227], s[4:5], 0, v[154:155]
	s_mov_b32 m0, s52
	s_nop 0
	global_load_lds_dwordx4 v[226:227], off
	s_waitcnt vmcnt(8)
	s_waitcnt lgkmcnt(0)
	s_barrier
	s_setprio 1
	s_waitcnt lgkmcnt(0)
	v_mfma_f32_16x16x32_bf16 v[132:135], v[136:139], v[192:195], v[132:135]
	v_mfma_f32_16x16x32_bf16 v[132:135], v[140:143], v[196:199], v[132:135]
	v_mfma_f32_16x16x32_bf16 v[128:131], v[144:147], v[192:195], v[128:131]
	v_mfma_f32_16x16x32_bf16 v[128:131], v[148:151], v[196:199], v[128:131]
	v_mfma_f32_16x16x32_bf16 v[112:115], v[144:147], v[200:203], v[112:115]
	v_mfma_f32_16x16x32_bf16 v[112:115], v[148:151], v[204:207], v[112:115]
	v_mfma_f32_16x16x32_bf16 v[116:119], v[136:139], v[200:203], v[116:119]
	v_mfma_f32_16x16x32_bf16 v[116:119], v[140:143], v[204:207], v[116:119]
	v_mfma_f32_16x16x32_bf16 v[100:103], v[136:139], v[230:233], v[100:103]
	v_mfma_f32_16x16x32_bf16 v[100:103], v[140:143], v[234:237], v[100:103]
	v_mfma_f32_16x16x32_bf16 v[96:99], v[144:147], v[230:233], v[96:99]
	v_mfma_f32_16x16x32_bf16 v[96:99], v[148:151], v[234:237], v[96:99]
	v_mfma_f32_16x16x32_bf16 v[80:83], v[144:147], v[238:241], v[80:83]
	v_mfma_f32_16x16x32_bf16 v[80:83], v[148:151], v[242:245], v[80:83]
	v_mfma_f32_16x16x32_bf16 v[84:87], v[136:139], v[238:241], v[84:87]
	v_mfma_f32_16x16x32_bf16 v[84:87], v[140:143], v[242:245], v[84:87]
	s_setprio 0
	s_setprio 1
	v_mfma_f32_16x16x32_bf16 v[124:127], v[174:177], v[192:195], v[124:127]
	v_mfma_f32_16x16x32_bf16 v[124:127], v[178:181], v[196:199], v[124:127]
	v_mfma_f32_16x16x32_bf16 v[120:123], v[184:187], v[192:195], v[120:123]
	v_mfma_f32_16x16x32_bf16 v[120:123], v[188:191], v[196:199], v[120:123]
	v_mfma_f32_16x16x32_bf16 v[104:107], v[184:187], v[200:203], v[104:107]
	v_mfma_f32_16x16x32_bf16 v[104:107], v[188:191], v[204:207], v[104:107]
	v_mfma_f32_16x16x32_bf16 v[108:111], v[174:177], v[200:203], v[108:111]
	v_mfma_f32_16x16x32_bf16 v[108:111], v[178:181], v[204:207], v[108:111]
	v_mfma_f32_16x16x32_bf16 v[92:95], v[174:177], v[230:233], v[92:95]
	v_mfma_f32_16x16x32_bf16 v[92:95], v[178:181], v[234:237], v[92:95]
	v_mfma_f32_16x16x32_bf16 v[88:91], v[184:187], v[230:233], v[88:91]
	v_mfma_f32_16x16x32_bf16 v[88:91], v[188:191], v[234:237], v[88:91]
	v_mfma_f32_16x16x32_bf16 v[72:75], v[184:187], v[238:241], v[72:75]
	v_mfma_f32_16x16x32_bf16 v[72:75], v[188:191], v[242:245], v[72:75]
	v_mfma_f32_16x16x32_bf16 v[76:79], v[174:177], v[238:241], v[76:79]
	v_mfma_f32_16x16x32_bf16 v[76:79], v[178:181], v[242:245], v[76:79]
	s_setprio 0
	s_barrier
; #define PG8_STAGE(bufoff, gbase, voff) do { _Pragma("unroll") for (int _i = 0; _i < 2; ++_i) \
;         __builtin_amdgcn_global_load_lds((const unsigned*)((const char*)(gbase) + (voff)[_i]), (PG8_LAS unsigned*)(lds + (bufoff) + ldsw + _i * 8192), 16, 0, 0); } while (0)
; #define PG8_LDA(dst, b, h) do { _Pragma("unroll") for (int m = 0; m < 4; ++m) _Pragma("unroll") for (int k = 0; k < 2; ++k) dst[m][k] = *(const PG8_LAS bf16x8*)(lds + PG8_SA(b, h) + aoff + m * 2048 + k * 1024); } while (0)
; #define PG8_WAIT_V(n) asm volatile("s_waitcnt vmcnt(" #n ")" ::: "memory")
; #define PG8_BAR __builtin_amdgcn_s_barrier()
; template <class Epi, class Sched, bool ALIGN_EPI = false, bool SP2 = false>
; __device__ __forceinline__ void gemm_phase(PG8_LAS unsigned char* lds, const Gemm g, const Sched& S, const Epi& E) {
;     ...
;         for (int t = 0; t < nt; t += 2) {
;             if constexpr (Epi::KHOOK) { if ((t & 7) == 0 && t != 0) E.khook(acc, t >> 3, wr, fr, lds); }
;             const bool last = (t == nt - 2);
;             const char* a1 = cA + (size_t)(t + 1) * kstep;
;             const char* a2 = last ? nA : cA + (size_t)(t + 2) * kstep; const char* b2 = last ? nB : cB + (size_t)(t + 2) * kstep;
;             const char* a3 = a2 + kstep; const char* b3 = b2 + kstep;
;             if (last && has_next) S.a_ready(nxt);
;             if constexpr (SP2) {
;             PG8_LDB(B0, 0, 0); PG8_LDB(B1, 0, 1); PG8_SCHED; PG8_LDA(At, 0, 0); PG8_STAGE(PG8_SA(1, 1), a1 + hstep, voffA);
;             PG8_WAIT_V(8); PG8_WAIT_L(0); PG8_BAR; PG8_MMA(0, 0, At, B0); PG8_MMA(0, 1, At, B1); PG8_BAR; PG8_SCHED;
;             PG8_LDA(At, 0, 1); PG8_STAGE(PG8_SB(0, 0), b2, voffB); PG8_STAGE(PG8_SB(0, 1), b2 + hstep, voffB); PG8_STAGE(PG8_SA(0, 0), a2, voffA);
;             PG8_WAIT_V(8); PG8_WAIT_L(0); PG8_BAR; PG8_MMA(1, 0, At, B0); PG8_MMA(1, 1, At, B1); PG8_BAR; PG8_SCHED;
;             PG8_LDB(B0, 1, 0); PG8_LDB(B1, 1, 1); PG8_SCHED; PG8_LDA(At, 1, 0); PG8_STAGE(PG8_SA(0, 1), a2 + hstep, voffA);
;             PG8_WAIT_V(8); PG8_WAIT_L(0); PG8_BAR; PG8_MMA(0, 0, At, B0); PG8_MMA(0, 1, At, B1); PG8_BAR; PG8_SCHED;
;             PG8_LDA(At, 1, 1); PG8_STAGE(PG8_SB(1, 0), b3, voffB); PG8_STAGE(PG8_SB(1, 1), b3 + hstep, voffB); PG8_STAGE(PG8_SA(1, 0), a3, voffA);
;             PG8_WAIT_V(8); PG8_WAIT_L(0); PG8_BAR; PG8_MMA(1, 0, At, B0); PG8_MMA(1, 1, At, B1); PG8_BAR; PG8_SCHED;
	s_add_i32 s4, s91, s44
	v_lshl_add_u64 v[162:163], v[162:163], 0, s[24:25]
	s_mov_b32 m0, s4
	ds_read_b128 v[192:195], v170 offset:49152
	ds_read_b128 v[196:199], v170 offset:50176
	ds_read_b128 v[200:203], v170 offset:51200
	ds_read_b128 v[204:207], v170 offset:52224
	ds_read_b128 v[230:233], v170 offset:53248
	ds_read_b128 v[234:237], v170 offset:54272
	ds_read_b128 v[238:241], v170 offset:55296
	ds_read_b128 v[242:245], v170 offset:56320
	global_load_lds_dwordx4 v[162:163], off
	v_lshl_add_u64 v[162:163], v[208:209], 0, s[24:25]
	s_add_i32 m0, s4, 0x2000
	s_add_i32 s4, s81, s44
	global_load_lds_dwordx4 v[162:163], off
	v_lshl_add_u64 v[162:163], v[246:247], 0, s[24:25]
	s_mov_b32 m0, s4
	s_nop 0
	global_load_lds_dwordx4 v[162:163], off
	v_lshl_add_u64 v[162:163], v[248:249], 0, s[24:25]
	s_add_i32 m0, s4, 0x2000
	s_nop 0
	global_load_lds_dwordx4 v[162:163], off
	v_lshl_add_u64 v[162:163], v[216:217], 0, s[24:25]
	s_mov_b32 m0, s53
	s_nop 0
	global_load_lds_dwordx4 v[162:163], off
	v_lshl_add_u64 v[162:163], v[224:225], 0, s[24:25]
	s_mov_b32 m0, s72
	s_nop 0
	global_load_lds_dwordx4 v[162:163], off
	s_waitcnt vmcnt(8)
	s_waitcnt lgkmcnt(0)
	s_barrier
	s_setprio 1
	s_waitcnt lgkmcnt(0)
	v_mfma_f32_16x16x32_bf16 v[68:71], v[136:139], v[192:195], v[68:71]
	v_mfma_f32_16x16x32_bf16 v[68:71], v[140:143], v[196:199], v[68:71]
	v_mfma_f32_16x16x32_bf16 v[64:67], v[144:147], v[192:195], v[64:67]
	v_mfma_f32_16x16x32_bf16 v[64:67], v[148:151], v[196:199], v[64:67]
	v_mfma_f32_16x16x32_bf16 v[48:51], v[144:147], v[200:203], v[48:51]
	v_mfma_f32_16x16x32_bf16 v[48:51], v[148:151], v[204:207], v[48:51]
	v_mfma_f32_16x16x32_bf16 v[52:55], v[136:139], v[200:203], v[52:55]
	v_mfma_f32_16x16x32_bf16 v[52:55], v[140:143], v[204:207], v[52:55]
	v_mfma_f32_16x16x32_bf16 v[36:39], v[136:139], v[230:233], v[36:39]
	v_mfma_f32_16x16x32_bf16 v[36:39], v[140:143], v[234:237], v[36:39]
	v_mfma_f32_16x16x32_bf16 v[32:35], v[144:147], v[230:233], v[32:35]
	v_mfma_f32_16x16x32_bf16 v[32:35], v[148:151], v[234:237], v[32:35]
	v_mfma_f32_16x16x32_bf16 v[16:19], v[144:147], v[238:241], v[16:19]
	v_mfma_f32_16x16x32_bf16 v[16:19], v[148:151], v[242:245], v[16:19]
	v_mfma_f32_16x16x32_bf16 v[20:23], v[136:139], v[238:241], v[20:23]
	v_mfma_f32_16x16x32_bf16 v[20:23], v[140:143], v[242:245], v[20:23]
	s_setprio 0
	s_setprio 1
	v_mfma_f32_16x16x32_bf16 v[60:63], v[174:177], v[192:195], v[60:63]
	v_mfma_f32_16x16x32_bf16 v[60:63], v[178:181], v[196:199], v[60:63]
	v_mfma_f32_16x16x32_bf16 v[56:59], v[184:187], v[192:195], v[56:59]
	v_mfma_f32_16x16x32_bf16 v[56:59], v[188:191], v[196:199], v[56:59]
	v_mfma_f32_16x16x32_bf16 v[40:43], v[184:187], v[200:203], v[40:43]
	v_mfma_f32_16x16x32_bf16 v[40:43], v[188:191], v[204:207], v[40:43]
	v_mfma_f32_16x16x32_bf16 v[44:47], v[174:177], v[200:203], v[44:47]
	v_mfma_f32_16x16x32_bf16 v[44:47], v[178:181], v[204:207], v[44:47]
	v_mfma_f32_16x16x32_bf16 v[28:31], v[174:177], v[230:233], v[28:31]
	v_mfma_f32_16x16x32_bf16 v[28:31], v[178:181], v[234:237], v[28:31]
	v_mfma_f32_16x16x32_bf16 v[24:27], v[184:187], v[230:233], v[24:27]
	v_mfma_f32_16x16x32_bf16 v[24:27], v[188:191], v[234:237], v[24:27]
	v_mfma_f32_16x16x32_bf16 v[8:11], v[184:187], v[238:241], v[8:11]
	v_mfma_f32_16x16x32_bf16 v[8:11], v[188:191], v[242:245], v[8:11]
	v_mfma_f32_16x16x32_bf16 v[12:15], v[174:177], v[238:241], v[12:15]
	v_mfma_f32_16x16x32_bf16 v[12:15], v[178:181], v[242:245], v[12:15]
	s_setprio 0
	s_barrier
	s_add_u32 s0, s0, 0x100
	s_addc_u32 s1, s1, 0
	s_add_u32 s42, s42, 0x100
	s_addc_u32 s43, s43, 0
	s_cmp_ge_u32 s80, s9
	s_mov_b32 s4, s80
	s_cbranch_scc0 .LBB0_501
